# P9/P10 epilogue loads hoisted; FoX ck-load wait deferred + accumulator copy skipped on hot path; P5-P6 grid barrier removed (same-WG dependency); P2 gate loop loads double-buffered
# speedup vs baseline: 1.0135x; 1.0114x over previous
; #define LAS __attribute__((address_space(3)))
; DI void p2_unit(int chunk, const Params& p, LAS unsigned char* lds) {
;     ...
;     { const int col = tid & 255, half = tid >> 8, t0 = 32 * half, t0u = __builtin_amdgcn_readfirstlane(t0);
;       LAS float* tots = (LAS float*)(lds + L2_DEC) + 256;
;       float w2c[16];
; #pragma unroll
;       for (int r = 0; r < 16; ++r) w2c[r] = p.gla_w2[r * 256 + col];
;       const float bgc = p.gla_bg[col];
;       bf16_t* pq = proj + (size_t)(tok0 + t0) * NPROJ + C_GQ + col; bf16_t* pk = proj + (size_t)(tok0 + t0) * NPROJ + C_GK + col;
;       bf16_t qv32[32], kv32[32];
; #pragma unroll
;       for (int j2 = 0; j2 < 32; ++j2) { qv32[j2] = pq[(size_t)j2 * NPROJ]; kv32[j2] = pk[(size_t)j2 * NPROJ]; }
.LBB0_354:
	v_and_b32_e32 v219, 0xff, v146
	v_lshlrev_b32_e32 v66, 2, v219
	v_lshl_add_u64 v[0:1], s[30:31], 0, v[66:67]
	v_add_co_u32_e32 v2, vcc, 0x1000, v0
	global_load_dword v19, v66, s[30:31]
	global_load_dword v21, v66, s[30:31] offset:1024
	global_load_dword v20, v66, s[30:31] offset:2048
	global_load_dword v18, v66, s[30:31] offset:3072
	v_addc_co_u32_e32 v3, vcc, 0, v1, vcc
	global_load_dword v23, v[2:3], off
	global_load_dword v25, v[2:3], off offset:1024
	global_load_dword v24, v[2:3], off offset:2048
	global_load_dword v22, v[2:3], off offset:3072
	v_add_co_u32_e32 v2, vcc, 0x2000, v0
	v_ashrrev_i32_e32 v69, 3, v146
	s_nop 0
	v_addc_co_u32_e32 v3, vcc, 0, v1, vcc
	v_add_co_u32_e32 v0, vcc, 0x3000, v0
	v_and_b32_e32 v204, 0xffffffe0, v69
	s_nop 0
	v_addc_co_u32_e32 v1, vcc, 0, v1, vcc
	global_load_dword v27, v[2:3], off
	global_load_dword v32, v[2:3], off offset:1024
	global_load_dword v28, v[2:3], off offset:2048
	global_load_dword v26, v[2:3], off offset:3072
	global_load_dword v30, v[0:1], off
	global_load_dword v33, v[0:1], off offset:1024
	global_load_dword v31, v[0:1], off offset:2048
	global_load_dword v29, v[0:1], off offset:3072
	v_add_u32_e32 v2, s52, v204
	v_mov_b64_e32 v[0:1], s[14:15]
	v_mad_i64_i32 v[0:1], s[0:1], v2, s53, v[0:1]
	v_lshlrev_b32_e32 v2, 1, v219
	v_mov_b32_e32 v3, v67
	v_lshl_add_u64 v[16:17], v[0:1], 0, v[2:3]
	s_movk_i32 s0, 0x2000
	v_readlane_b32 s36, v254, 0
	v_add_co_u32_e32 v0, vcc, s0, v16
	v_readlane_b32 s37, v254, 1
	s_nop 0
	v_addc_co_u32_e32 v1, vcc, 0, v17, vcc
	s_movk_i32 s0, 0x4000
	v_readlane_b32 s40, v254, 4
	v_readlane_b32 s41, v254, 5
	global_load_dword v34, v66, s[36:37]
	global_load_ushort v218, v[16:17], off offset:3072
	global_load_ushort v217, v[16:17], off offset:3584
	global_load_ushort v216, v[0:1], off offset:1536
	global_load_ushort v215, v[0:1], off offset:2048
	v_add_co_u32_e32 v0, vcc, s0, v16
	s_movk_i32 s0, 0x5000
	s_nop 0
	v_addc_co_u32_e32 v1, vcc, 0, v17, vcc
	global_load_ushort v214, v[0:1], off
	global_load_ushort v212, v[0:1], off offset:512
	v_add_co_u32_e32 v0, vcc, s0, v16
	s_movk_i32 s0, 0x7000
	s_nop 0
	v_addc_co_u32_e32 v1, vcc, 0, v17, vcc
	global_load_ushort v213, v[0:1], off offset:2560
	global_load_ushort v211, v[0:1], off offset:3072
	v_add_co_u32_e32 v0, vcc, s0, v16
	s_mov_b32 s0, 0x8000
	s_nop 0
	v_addc_co_u32_e32 v1, vcc, 0, v17, vcc
	global_load_ushort v210, v[0:1], off offset:1024
	global_load_ushort v209, v[0:1], off offset:1536
	v_add_co_u32_e32 v0, vcc, s0, v16
	s_mov_b32 s0, 0x9000
	s_nop 0
	v_addc_co_u32_e32 v1, vcc, 0, v17, vcc
	global_load_ushort v207, v[0:1], off offset:3584
	v_add_co_u32_e32 v0, vcc, s0, v16
	s_mov_b32 s0, 0xa000
	s_nop 0
	v_addc_co_u32_e32 v1, vcc, 0, v17, vcc
	global_load_ushort v205, v[0:1], off
	v_add_co_u32_e32 v0, vcc, s0, v16
	s_mov_b32 s0, 0xc000
	s_nop 0
	v_addc_co_u32_e32 v1, vcc, 0, v17, vcc
	global_load_ushort v203, v[0:1], off offset:2048
	global_load_ushort v201, v[0:1], off offset:2560
	v_add_co_u32_e32 v0, vcc, s0, v16
	s_mov_b32 s0, 0xd000
	s_nop 0
	v_addc_co_u32_e32 v1, vcc, 0, v17, vcc
	global_load_ushort v202, v[0:1], off offset:512
	global_load_ushort v200, v[0:1], off offset:1024
	v_add_co_u32_e32 v0, vcc, s0, v16
	s_mov_b32 s0, 0xf000
	s_nop 0
	v_addc_co_u32_e32 v1, vcc, 0, v17, vcc
	global_load_ushort v199, v[0:1], off offset:3072
	global_load_ushort v198, v[0:1], off offset:3584
	v_add_co_u32_e32 v0, vcc, s0, v16
	s_mov_b32 s0, 0x11000
	s_nop 0
	v_addc_co_u32_e32 v1, vcc, 0, v17, vcc
	global_load_ushort v197, v[0:1], off offset:1536
	global_load_ushort v196, v[0:1], off offset:2048
	v_add_co_u32_e32 v0, vcc, s0, v16
	s_mov_b32 s0, 0x12000
	s_nop 0
	v_addc_co_u32_e32 v1, vcc, 0, v17, vcc
	global_load_ushort v195, v[0:1], off
	global_load_ushort v193, v[0:1], off offset:512
	v_add_co_u32_e32 v0, vcc, s0, v16
	s_mov_b32 s0, 0x14000
	s_nop 0
	v_addc_co_u32_e32 v1, vcc, 0, v17, vcc
	global_load_ushort v194, v[0:1], off offset:2560
	global_load_ushort v192, v[0:1], off offset:3072
	v_add_co_u32_e32 v0, vcc, s0, v16
	s_mov_b32 s0, 0x15000
	s_nop 0
	v_addc_co_u32_e32 v1, vcc, 0, v17, vcc
	global_load_ushort v191, v[0:1], off offset:1024
	global_load_ushort v190, v[0:1], off offset:1536
	v_add_co_u32_e32 v0, vcc, s0, v16
	s_mov_b32 s0, 0x16000
	s_nop 0
	v_addc_co_u32_e32 v1, vcc, 0, v17, vcc
	global_load_ushort v189, v[0:1], off offset:3584
	v_add_co_u32_e32 v0, vcc, s0, v16
	s_mov_b32 s0, 0x17000
	s_nop 0
	v_addc_co_u32_e32 v1, vcc, 0, v17, vcc
	global_load_ushort v188, v[0:1], off
	v_add_co_u32_e32 v0, vcc, s0, v16
	s_mov_b32 s0, 0x19000
	s_nop 0
	v_addc_co_u32_e32 v1, vcc, 0, v17, vcc
	global_load_ushort v187, v[0:1], off offset:2048
	global_load_ushort v185, v[0:1], off offset:2560
	v_add_co_u32_e32 v0, vcc, s0, v16
	s_mov_b32 s0, 0x1a000
	s_nop 0
	v_addc_co_u32_e32 v1, vcc, 0, v17, vcc
	global_load_ushort v186, v[0:1], off offset:512
	global_load_ushort v184, v[0:1], off offset:1024
	v_add_co_u32_e32 v0, vcc, s0, v16
	s_mov_b32 s0, 0x1c000
	s_nop 0
	v_addc_co_u32_e32 v1, vcc, 0, v17, vcc
	global_load_ushort v183, v[0:1], off offset:3072
	global_load_ushort v182, v[0:1], off offset:3584
	v_add_co_u32_e32 v0, vcc, s0, v16
	s_mov_b32 s0, 0x1e000
	s_nop 0
	v_addc_co_u32_e32 v1, vcc, 0, v17, vcc
	global_load_ushort v181, v[0:1], off offset:1536
	global_load_ushort v180, v[0:1], off offset:2048
	v_add_co_u32_e32 v0, vcc, s0, v16
	s_mov_b32 s0, 0x1f000
	s_nop 0
	v_addc_co_u32_e32 v1, vcc, 0, v17, vcc
	global_load_ushort v179, v[0:1], off
	global_load_ushort v177, v[0:1], off offset:512
	v_add_co_u32_e32 v0, vcc, s0, v16
	s_mov_b32 s0, 0x21000
	s_nop 0
	v_addc_co_u32_e32 v1, vcc, 0, v17, vcc
; DI float logsig_fast(float z) { return fminf(z, 0.f) - __logf(1.0f + __expf(-fabsf(z))); }
; DI void p2_unit(int chunk, const Params& p, LAS unsigned char* lds) {
;     ...
;       for (int j2 = 0; j2 < 32; ++j2) { qv32[j2] = pq[(size_t)j2 * NPROJ]; kv32[j2] = pk[(size_t)j2 * NPROJ]; }
;       float lc[32]; float bc = 0.f;
; #pragma unroll
;       for (int j2 = 0; j2 < 32; ++j2) { const f32x4* ar = (const f32x4*)(aux + (size_t)(tok0 + t0u + j2) * 32 + 8);
;           float z = bgc;
; #pragma unroll
;           for (int r4 = 0; r4 < 4; ++r4) { const f32x4 a = ar[r4]; z += a.x * w2c[4 * r4] + a.y * w2c[4 * r4 + 1] + a.z * w2c[4 * r4 + 2] + a.w * w2c[4 * r4 + 3]; }
;           bc += logsig_fast(z) * (1.0f / 16.0f); lc[j2] = bc; }
	global_load_ushort v178, v[0:1], off offset:2560
	global_load_ushort v176, v[0:1], off offset:3072
	v_add_co_u32_e32 v0, vcc, s0, v16
	s_mov_b32 s0, 0x22000
	s_nop 0
	v_addc_co_u32_e32 v1, vcc, 0, v17, vcc
	global_load_ushort v175, v[0:1], off offset:1024
	global_load_ushort v174, v[0:1], off offset:1536
	v_add_co_u32_e32 v0, vcc, s0, v16
	s_mov_b32 s0, 0x23000
	s_nop 0
	v_addc_co_u32_e32 v1, vcc, 0, v17, vcc
	global_load_ushort v173, v[0:1], off offset:3584
	v_add_co_u32_e32 v0, vcc, s0, v16
	s_mov_b32 s0, 0x24000
	s_nop 0
	v_addc_co_u32_e32 v1, vcc, 0, v17, vcc
	global_load_ushort v172, v[0:1], off
	v_add_co_u32_e32 v0, vcc, s0, v16
	s_mov_b32 s0, 0x26000
	s_nop 0
	v_addc_co_u32_e32 v1, vcc, 0, v17, vcc
	global_load_ushort v171, v[0:1], off offset:2048
	global_load_ushort v170, v[0:1], off offset:2560
	v_add_co_u32_e32 v0, vcc, s0, v16
	s_mov_b32 s0, 0x27000
	s_nop 0
	v_addc_co_u32_e32 v1, vcc, 0, v17, vcc
	global_load_ushort v169, v[0:1], off offset:512
	global_load_ushort v168, v[0:1], off offset:1024
	v_add_co_u32_e32 v0, vcc, s0, v16
	s_mov_b32 s0, 0x29000
	s_nop 0
	v_addc_co_u32_e32 v1, vcc, 0, v17, vcc
	global_load_ushort v167, v[0:1], off offset:3072
	global_load_ushort v166, v[0:1], off offset:3584
	v_add_co_u32_e32 v0, vcc, s0, v16
	s_mov_b32 s0, 0x2b000
	s_nop 0
	v_addc_co_u32_e32 v1, vcc, 0, v17, vcc
	global_load_ushort v161, v[0:1], off offset:1536
	global_load_ushort v160, v[0:1], off offset:2048
	v_add_co_u32_e32 v0, vcc, s0, v16
	s_mov_b32 s0, 0x2c000
	s_nop 0
	v_addc_co_u32_e32 v1, vcc, 0, v17, vcc
	global_load_ushort v159, v[0:1], off
	global_load_ushort v158, v[0:1], off offset:512
	v_add_co_u32_e32 v0, vcc, s0, v16
	s_mov_b32 s0, 0x2e000
	s_nop 0
	v_addc_co_u32_e32 v1, vcc, 0, v17, vcc
	global_load_ushort v157, v[0:1], off offset:2560
	global_load_ushort v156, v[0:1], off offset:3072
	v_add_co_u32_e32 v0, vcc, s0, v16
	s_mov_b32 s0, 0x2f000
	s_nop 0
	v_addc_co_u32_e32 v1, vcc, 0, v17, vcc
	global_load_ushort v155, v[0:1], off offset:1024
	global_load_ushort v154, v[0:1], off offset:1536
	v_add_co_u32_e32 v0, vcc, s0, v16
	s_mov_b32 s0, 0x30000
	s_nop 0
	v_addc_co_u32_e32 v1, vcc, 0, v17, vcc
	global_load_ushort v153, v[0:1], off offset:3584
	v_add_co_u32_e32 v0, vcc, s0, v16
	s_mov_b32 s0, 0x31000
	s_nop 0
	v_addc_co_u32_e32 v1, vcc, 0, v17, vcc
	global_load_ushort v152, v[0:1], off
	v_add_co_u32_e32 v0, vcc, s0, v16
	s_mov_b32 s0, 0x33000
	s_nop 0
	v_addc_co_u32_e32 v1, vcc, 0, v17, vcc
	global_load_ushort v151, v[0:1], off offset:2048
	global_load_ushort v150, v[0:1], off offset:2560
	v_add_co_u32_e32 v0, vcc, s0, v16
	v_readfirstlane_b32 s0, v204
	s_add_i32 s40, s0, s52
	s_ashr_i32 s41, s40, 31
	s_lshl_b64 s[0:1], s[40:41], 7
	s_add_u32 s0, s60, s0
	v_addc_co_u32_e32 v1, vcc, 0, v17, vcc
	s_addc_u32 s1, s61, s1
	global_load_ushort v149, v[0:1], off offset:512
	global_load_ushort v148, v[0:1], off offset:1024
	s_nop 0
	s_mov_b64 s[98:99], s[0:1]
	global_load_dwordx4 v[70:73], v67, s[98:99] offset:80
	global_load_dwordx4 v[74:77], v67, s[98:99] offset:64
	global_load_dwordx4 v[78:81], v67, s[98:99] offset:48
	global_load_dwordx4 v[82:85], v67, s[98:99] offset:32
	global_load_dwordx4 v[0:3], v67, s[98:99] offset:208
	global_load_dwordx4 v[4:7], v67, s[98:99] offset:192
	global_load_dwordx4 v[8:11], v67, s[98:99] offset:176
	global_load_dwordx4 v[12:15], v67, s[98:99] offset:160
	v_readlane_b32 s38, v254, 2
	v_readlane_b32 s39, v254, 3
	s_mov_b32 s0, 0x3d800000
	v_readlane_b32 s42, v254, 6
	v_readlane_b32 s43, v254, 7
	v_readlane_b32 s44, v254, 8
	v_readlane_b32 s45, v254, 9
	v_readlane_b32 s46, v254, 10
	v_readlane_b32 s47, v254, 11
	v_readlane_b32 s48, v254, 12
	v_readlane_b32 s49, v254, 13
	v_readlane_b32 s50, v254, 14
	v_readlane_b32 s51, v254, 15
	s_waitcnt vmcnt(7)
	v_mul_f32_e32 v71, v33, v71
	s_waitcnt vmcnt(6)
	v_mul_f32_e32 v75, v32, v75
	s_waitcnt vmcnt(5)
	v_mul_f32_e32 v79, v25, v79
	s_waitcnt vmcnt(4)
	v_mul_f32_e32 v83, v21, v83
	v_fmac_f32_e32 v83, v19, v82
	v_fmac_f32_e32 v83, v20, v84
	v_fmac_f32_e32 v79, v23, v78
	v_fmac_f32_e32 v83, v18, v85
	v_fmac_f32_e32 v79, v24, v80
	v_fmac_f32_e32 v75, v27, v74
	v_add_f32_e32 v82, v34, v83
	v_fmac_f32_e32 v79, v22, v81
	v_fmac_f32_e32 v75, v28, v76
	v_fmac_f32_e32 v71, v30, v70
	v_add_f32_e32 v78, v82, v79
	v_fmac_f32_e32 v75, v26, v77
	v_fmac_f32_e32 v71, v31, v72
	v_add_f32_e32 v74, v78, v75
	v_fmac_f32_e32 v71, v29, v73
	v_add_f32_e32 v70, v74, v71
	v_min_f32_e32 v71, 0, v70
	v_mul_f32_e64 v70, |v70|, s59
	v_exp_f32_e32 v70, v70
	s_nop 0
	v_add_f32_e32 v70, 1.0, v70
	v_cmp_gt_f32_e32 vcc, s83, v70
	s_nop 1
	v_cndmask_b32_e64 v72, 0, 32, vcc
	v_ldexp_f32 v70, v70, v72
	v_log_f32_e32 v70, v70
	s_nop 0
	v_mul_f32_e32 v72, 0x3f317217, v70
	v_fma_f32 v72, v70, s87, -v72
	v_fmac_f32_e32 v72, 0x3377d1cf, v70
	v_fmac_f32_e32 v72, 0x3f317217, v70
	v_cmp_lt_f32_e64 s[38:39], |v70|, s73
	s_nop 1
	v_cndmask_b32_e64 v70, v70, v72, s[38:39]
	v_cndmask_b32_e32 v72, 0, v145, vcc
	v_sub_f32_e32 v70, v70, v72
	v_sub_f32_e32 v70, v71, v70
	v_fma_f32 v220, v70, s0, 0
	global_load_dwordx4 v[70:73], v67, s[98:99] offset:336
	global_load_dwordx4 v[74:77], v67, s[98:99] offset:320
	global_load_dwordx4 v[78:81], v67, s[98:99] offset:304
	global_load_dwordx4 v[82:85], v67, s[98:99] offset:288
	s_waitcnt vmcnt(7)
	v_mul_f32_e32 v1, v33, v1
	s_waitcnt vmcnt(6)
	v_mul_f32_e32 v5, v32, v5
	s_waitcnt vmcnt(5)
	v_mul_f32_e32 v9, v25, v9
	s_waitcnt vmcnt(4)
; DI float logsig_fast(float z) { return fminf(z, 0.f) - __logf(1.0f + __expf(-fabsf(z))); }
; DI void p2_unit(int chunk, const Params& p, LAS unsigned char* lds) {
;     ...
;       for (int j2 = 0; j2 < 32; ++j2) { const f32x4* ar = (const f32x4*)(aux + (size_t)(tok0 + t0u + j2) * 32 + 8);
;           float z = bgc;
; #pragma unroll
;           for (int r4 = 0; r4 < 4; ++r4) { const f32x4 a = ar[r4]; z += a.x * w2c[4 * r4] + a.y * w2c[4 * r4 + 1] + a.z * w2c[4 * r4 + 2] + a.w * w2c[4 * r4 + 3]; }
;           bc += logsig_fast(z) * (1.0f / 16.0f); lc[j2] = bc; }
	v_mul_f32_e32 v13, v21, v13
	v_fmac_f32_e32 v13, v19, v12
	v_fmac_f32_e32 v13, v20, v14
	v_fmac_f32_e32 v9, v23, v8
	v_fmac_f32_e32 v13, v18, v15
	v_fmac_f32_e32 v9, v24, v10
	v_fmac_f32_e32 v5, v27, v4
	v_add_f32_e32 v12, v34, v13
	v_fmac_f32_e32 v9, v22, v11
	v_fmac_f32_e32 v5, v28, v6
	v_fmac_f32_e32 v1, v30, v0
	v_add_f32_e32 v8, v12, v9
	v_fmac_f32_e32 v5, v26, v7
	v_fmac_f32_e32 v1, v31, v2
	v_add_f32_e32 v4, v8, v5
	v_fmac_f32_e32 v1, v29, v3
	v_add_f32_e32 v0, v4, v1
	v_min_f32_e32 v1, 0, v0
	v_mul_f32_e64 v0, |v0|, s59
	v_exp_f32_e32 v0, v0
	s_nop 0
	v_add_f32_e32 v0, 1.0, v0
	v_cmp_gt_f32_e32 vcc, s83, v0
	s_nop 1
	v_cndmask_b32_e64 v2, 0, 32, vcc
	v_ldexp_f32 v0, v0, v2
	v_log_f32_e32 v0, v0
	s_nop 0
	v_mul_f32_e32 v2, 0x3f317217, v0
	v_fma_f32 v2, v0, s87, -v2
	v_fmac_f32_e32 v2, 0x3377d1cf, v0
	v_fmac_f32_e32 v2, 0x3f317217, v0
	v_cmp_lt_f32_e64 s[38:39], |v0|, s73
	s_nop 1
	v_cndmask_b32_e64 v0, v0, v2, s[38:39]
	v_cndmask_b32_e32 v2, 0, v145, vcc
	v_sub_f32_e32 v0, v0, v2
	v_sub_f32_e32 v0, v1, v0
	v_fmamk_f32 v221, v0, 0x3d800000, v220
	global_load_dwordx4 v[0:3], v67, s[98:99] offset:464
	global_load_dwordx4 v[4:7], v67, s[98:99] offset:448
	global_load_dwordx4 v[8:11], v67, s[98:99] offset:432
	global_load_dwordx4 v[12:15], v67, s[98:99] offset:416
	s_waitcnt vmcnt(7)
	v_mul_f32_e32 v71, v33, v71
	s_waitcnt vmcnt(6)
	v_mul_f32_e32 v75, v32, v75
	s_waitcnt vmcnt(5)
	v_mul_f32_e32 v79, v25, v79
	s_waitcnt vmcnt(4)
	v_mul_f32_e32 v83, v21, v83
	v_fmac_f32_e32 v83, v19, v82
	v_fmac_f32_e32 v83, v20, v84
	v_fmac_f32_e32 v79, v23, v78
	v_fmac_f32_e32 v83, v18, v85
	v_fmac_f32_e32 v79, v24, v80
	v_fmac_f32_e32 v75, v27, v74
	v_add_f32_e32 v82, v34, v83
	v_fmac_f32_e32 v79, v22, v81
	v_fmac_f32_e32 v75, v28, v76
	v_fmac_f32_e32 v71, v30, v70
	v_add_f32_e32 v78, v82, v79
	v_fmac_f32_e32 v75, v26, v77
	v_fmac_f32_e32 v71, v31, v72
	v_add_f32_e32 v74, v78, v75
	v_fmac_f32_e32 v71, v29, v73
	v_add_f32_e32 v70, v74, v71
	v_min_f32_e32 v71, 0, v70
	v_mul_f32_e64 v70, |v70|, s59
	v_exp_f32_e32 v70, v70
	s_nop 0
	v_add_f32_e32 v70, 1.0, v70
	v_cmp_gt_f32_e32 vcc, s83, v70
	s_nop 1
	v_cndmask_b32_e64 v72, 0, 32, vcc
	v_ldexp_f32 v70, v70, v72
	v_log_f32_e32 v70, v70
	s_nop 0
	v_mul_f32_e32 v72, 0x3f317217, v70
	v_fma_f32 v72, v70, s87, -v72
	v_fmac_f32_e32 v72, 0x3377d1cf, v70
	v_fmac_f32_e32 v72, 0x3f317217, v70
	v_cmp_lt_f32_e64 s[38:39], |v70|, s73
	s_nop 1
	v_cndmask_b32_e64 v70, v70, v72, s[38:39]
	v_cndmask_b32_e32 v72, 0, v145, vcc
	v_sub_f32_e32 v70, v70, v72
	v_sub_f32_e32 v70, v71, v70
	v_fmamk_f32 v222, v70, 0x3d800000, v221
	global_load_dwordx4 v[70:73], v67, s[98:99] offset:592
	global_load_dwordx4 v[74:77], v67, s[98:99] offset:576
	global_load_dwordx4 v[78:81], v67, s[98:99] offset:560
	global_load_dwordx4 v[82:85], v67, s[98:99] offset:544
	s_waitcnt vmcnt(7)
	v_mul_f32_e32 v1, v33, v1
	s_waitcnt vmcnt(6)
	v_mul_f32_e32 v5, v32, v5
	s_waitcnt vmcnt(5)
	v_mul_f32_e32 v9, v25, v9
	s_waitcnt vmcnt(4)
	v_mul_f32_e32 v13, v21, v13
	v_fmac_f32_e32 v13, v19, v12
	v_fmac_f32_e32 v13, v20, v14
	v_fmac_f32_e32 v9, v23, v8
	v_fmac_f32_e32 v13, v18, v15
	v_fmac_f32_e32 v9, v24, v10
	v_fmac_f32_e32 v5, v27, v4
	v_add_f32_e32 v12, v34, v13
	v_fmac_f32_e32 v9, v22, v11
	v_fmac_f32_e32 v5, v28, v6
	v_fmac_f32_e32 v1, v30, v0
	v_add_f32_e32 v8, v12, v9
	v_fmac_f32_e32 v5, v26, v7
	v_fmac_f32_e32 v1, v31, v2
	v_add_f32_e32 v4, v8, v5
	v_fmac_f32_e32 v1, v29, v3
	v_add_f32_e32 v0, v4, v1
	v_min_f32_e32 v1, 0, v0
	v_mul_f32_e64 v0, |v0|, s59
	v_exp_f32_e32 v0, v0
	s_nop 0
	v_add_f32_e32 v0, 1.0, v0
	v_cmp_gt_f32_e32 vcc, s83, v0
	s_nop 1
	v_cndmask_b32_e64 v2, 0, 32, vcc
	v_ldexp_f32 v0, v0, v2
	v_log_f32_e32 v0, v0
	s_nop 0
	v_mul_f32_e32 v2, 0x3f317217, v0
	v_fma_f32 v2, v0, s87, -v2
	v_fmac_f32_e32 v2, 0x3377d1cf, v0
	v_fmac_f32_e32 v2, 0x3f317217, v0
	v_cmp_lt_f32_e64 s[38:39], |v0|, s73
	s_nop 1
	v_cndmask_b32_e64 v0, v0, v2, s[38:39]
	v_cndmask_b32_e32 v2, 0, v145, vcc
	v_sub_f32_e32 v0, v0, v2
	v_sub_f32_e32 v0, v1, v0
	v_fmamk_f32 v223, v0, 0x3d800000, v222
	global_load_dwordx4 v[0:3], v67, s[98:99] offset:720
	global_load_dwordx4 v[4:7], v67, s[98:99] offset:704
	global_load_dwordx4 v[8:11], v67, s[98:99] offset:688
	global_load_dwordx4 v[12:15], v67, s[98:99] offset:672
	s_waitcnt vmcnt(7)
	v_mul_f32_e32 v71, v33, v71
	s_waitcnt vmcnt(6)
	v_mul_f32_e32 v75, v32, v75
	s_waitcnt vmcnt(5)
	v_mul_f32_e32 v79, v25, v79
	s_waitcnt vmcnt(4)
	v_mul_f32_e32 v83, v21, v83
	v_fmac_f32_e32 v83, v19, v82
	v_fmac_f32_e32 v83, v20, v84
	v_fmac_f32_e32 v79, v23, v78
	v_fmac_f32_e32 v83, v18, v85
	v_fmac_f32_e32 v79, v24, v80
	v_fmac_f32_e32 v75, v27, v74
	v_add_f32_e32 v82, v34, v83
	v_fmac_f32_e32 v79, v22, v81
	v_fmac_f32_e32 v75, v28, v76
	v_fmac_f32_e32 v71, v30, v70
	v_add_f32_e32 v78, v82, v79
	v_fmac_f32_e32 v75, v26, v77
	v_fmac_f32_e32 v71, v31, v72
	v_add_f32_e32 v74, v78, v75
	v_fmac_f32_e32 v71, v29, v73
	v_add_f32_e32 v70, v74, v71
	v_min_f32_e32 v71, 0, v70
	v_mul_f32_e64 v70, |v70|, s59
	v_exp_f32_e32 v70, v70
	s_nop 0
	v_add_f32_e32 v70, 1.0, v70
	v_cmp_gt_f32_e32 vcc, s83, v70
	s_nop 1
	v_cndmask_b32_e64 v72, 0, 32, vcc
	v_ldexp_f32 v70, v70, v72
	v_log_f32_e32 v70, v70
	s_nop 0
	v_mul_f32_e32 v72, 0x3f317217, v70
	v_fma_f32 v72, v70, s87, -v72
	v_fmac_f32_e32 v72, 0x3377d1cf, v70
	v_fmac_f32_e32 v72, 0x3f317217, v70
	v_cmp_lt_f32_e64 s[38:39], |v70|, s73
	s_nop 1
	v_cndmask_b32_e64 v70, v70, v72, s[38:39]
	v_cndmask_b32_e32 v72, 0, v145, vcc
	v_sub_f32_e32 v70, v70, v72
	v_sub_f32_e32 v70, v71, v70
	v_fmamk_f32 v224, v70, 0x3d800000, v223
	global_load_dwordx4 v[70:73], v67, s[98:99] offset:848
	global_load_dwordx4 v[74:77], v67, s[98:99] offset:832
	global_load_dwordx4 v[78:81], v67, s[98:99] offset:816
	global_load_dwordx4 v[82:85], v67, s[98:99] offset:800
	s_waitcnt vmcnt(7)
; DI float logsig_fast(float z) { return fminf(z, 0.f) - __logf(1.0f + __expf(-fabsf(z))); }
; DI void p2_unit(int chunk, const Params& p, LAS unsigned char* lds) {
;     ...
;       for (int j2 = 0; j2 < 32; ++j2) { const f32x4* ar = (const f32x4*)(aux + (size_t)(tok0 + t0u + j2) * 32 + 8);
;           float z = bgc;
; #pragma unroll
;           for (int r4 = 0; r4 < 4; ++r4) { const f32x4 a = ar[r4]; z += a.x * w2c[4 * r4] + a.y * w2c[4 * r4 + 1] + a.z * w2c[4 * r4 + 2] + a.w * w2c[4 * r4 + 3]; }
;           bc += logsig_fast(z) * (1.0f / 16.0f); lc[j2] = bc; }
	v_mul_f32_e32 v1, v33, v1
	s_waitcnt vmcnt(6)
	v_mul_f32_e32 v5, v32, v5
	s_waitcnt vmcnt(5)
	v_mul_f32_e32 v9, v25, v9
	s_waitcnt vmcnt(4)
	v_mul_f32_e32 v13, v21, v13
	v_fmac_f32_e32 v13, v19, v12
	v_fmac_f32_e32 v13, v20, v14
	v_fmac_f32_e32 v9, v23, v8
	v_fmac_f32_e32 v13, v18, v15
	v_fmac_f32_e32 v9, v24, v10
	v_fmac_f32_e32 v5, v27, v4
	v_add_f32_e32 v12, v34, v13
	v_fmac_f32_e32 v9, v22, v11
	v_fmac_f32_e32 v5, v28, v6
	v_fmac_f32_e32 v1, v30, v0
	v_add_f32_e32 v8, v12, v9
	v_fmac_f32_e32 v5, v26, v7
	v_fmac_f32_e32 v1, v31, v2
	v_add_f32_e32 v4, v8, v5
	v_fmac_f32_e32 v1, v29, v3
	v_add_f32_e32 v0, v4, v1
	v_min_f32_e32 v1, 0, v0
	v_mul_f32_e64 v0, |v0|, s59
	v_exp_f32_e32 v0, v0
	s_nop 0
	v_add_f32_e32 v0, 1.0, v0
	v_cmp_gt_f32_e32 vcc, s83, v0
	s_nop 1
	v_cndmask_b32_e64 v2, 0, 32, vcc
	v_ldexp_f32 v0, v0, v2
	v_log_f32_e32 v0, v0
	s_nop 0
	v_mul_f32_e32 v2, 0x3f317217, v0
	v_fma_f32 v2, v0, s87, -v2
	v_fmac_f32_e32 v2, 0x3377d1cf, v0
	v_fmac_f32_e32 v2, 0x3f317217, v0
	v_cmp_lt_f32_e64 s[38:39], |v0|, s73
	s_nop 1
	v_cndmask_b32_e64 v0, v0, v2, s[38:39]
	v_cndmask_b32_e32 v2, 0, v145, vcc
	v_sub_f32_e32 v0, v0, v2
	v_sub_f32_e32 v0, v1, v0
	v_fmamk_f32 v225, v0, 0x3d800000, v224
	global_load_dwordx4 v[0:3], v67, s[98:99] offset:976
	global_load_dwordx4 v[4:7], v67, s[98:99] offset:960
	global_load_dwordx4 v[8:11], v67, s[98:99] offset:944
	global_load_dwordx4 v[12:15], v67, s[98:99] offset:928
	s_waitcnt vmcnt(7)
	v_mul_f32_e32 v71, v33, v71
	s_waitcnt vmcnt(6)
	v_mul_f32_e32 v75, v32, v75
	s_waitcnt vmcnt(5)
	v_mul_f32_e32 v79, v25, v79
	s_waitcnt vmcnt(4)
	v_mul_f32_e32 v83, v21, v83
	v_fmac_f32_e32 v83, v19, v82
	v_fmac_f32_e32 v83, v20, v84
	v_fmac_f32_e32 v79, v23, v78
	v_fmac_f32_e32 v83, v18, v85
	v_fmac_f32_e32 v79, v24, v80
	v_fmac_f32_e32 v75, v27, v74
	v_add_f32_e32 v82, v34, v83
	v_fmac_f32_e32 v79, v22, v81
	v_fmac_f32_e32 v75, v28, v76
	v_fmac_f32_e32 v71, v30, v70
	v_add_f32_e32 v78, v82, v79
	v_fmac_f32_e32 v75, v26, v77
	v_fmac_f32_e32 v71, v31, v72
	v_add_f32_e32 v74, v78, v75
	v_fmac_f32_e32 v71, v29, v73
	v_add_f32_e32 v70, v74, v71
	v_min_f32_e32 v71, 0, v70
	v_mul_f32_e64 v70, |v70|, s59
	v_exp_f32_e32 v70, v70
	s_nop 0
	v_add_f32_e32 v70, 1.0, v70
	v_cmp_gt_f32_e32 vcc, s83, v70
	s_nop 1
	v_cndmask_b32_e64 v72, 0, 32, vcc
	v_ldexp_f32 v70, v70, v72
	v_log_f32_e32 v70, v70
	s_nop 0
	v_mul_f32_e32 v72, 0x3f317217, v70
	v_fma_f32 v72, v70, s87, -v72
	v_fmac_f32_e32 v72, 0x3377d1cf, v70
	v_fmac_f32_e32 v72, 0x3f317217, v70
	v_cmp_lt_f32_e64 s[38:39], |v70|, s73
	s_nop 1
	v_cndmask_b32_e64 v70, v70, v72, s[38:39]
	v_cndmask_b32_e32 v72, 0, v145, vcc
	v_sub_f32_e32 v70, v70, v72
	v_sub_f32_e32 v70, v71, v70
	v_fmamk_f32 v226, v70, 0x3d800000, v225
	global_load_dwordx4 v[70:73], v67, s[98:99] offset:1104
	global_load_dwordx4 v[74:77], v67, s[98:99] offset:1088
	global_load_dwordx4 v[78:81], v67, s[98:99] offset:1072
	global_load_dwordx4 v[82:85], v67, s[98:99] offset:1056
	s_waitcnt vmcnt(7)
	v_mul_f32_e32 v1, v33, v1
	s_waitcnt vmcnt(6)
	v_mul_f32_e32 v5, v32, v5
	s_waitcnt vmcnt(5)
	v_mul_f32_e32 v9, v25, v9
	s_waitcnt vmcnt(4)
	v_mul_f32_e32 v13, v21, v13
	v_fmac_f32_e32 v13, v19, v12
	v_fmac_f32_e32 v13, v20, v14
	v_fmac_f32_e32 v9, v23, v8
	v_fmac_f32_e32 v13, v18, v15
	v_fmac_f32_e32 v9, v24, v10
	v_fmac_f32_e32 v5, v27, v4
	v_add_f32_e32 v12, v34, v13
	v_fmac_f32_e32 v9, v22, v11
	v_fmac_f32_e32 v5, v28, v6
	v_fmac_f32_e32 v1, v30, v0
	v_add_f32_e32 v8, v12, v9
	v_fmac_f32_e32 v5, v26, v7
	v_fmac_f32_e32 v1, v31, v2
	v_add_f32_e32 v4, v8, v5
	v_fmac_f32_e32 v1, v29, v3
	v_add_f32_e32 v0, v4, v1
	v_min_f32_e32 v1, 0, v0
	v_mul_f32_e64 v0, |v0|, s59
	v_exp_f32_e32 v0, v0
	s_nop 0
	v_add_f32_e32 v0, 1.0, v0
	v_cmp_gt_f32_e32 vcc, s83, v0
	s_nop 1
	v_cndmask_b32_e64 v2, 0, 32, vcc
	v_ldexp_f32 v0, v0, v2
	v_log_f32_e32 v0, v0
	s_nop 0
	v_mul_f32_e32 v2, 0x3f317217, v0
	v_fma_f32 v2, v0, s87, -v2
	v_fmac_f32_e32 v2, 0x3377d1cf, v0
	v_fmac_f32_e32 v2, 0x3f317217, v0
	v_cmp_lt_f32_e64 s[38:39], |v0|, s73
	s_nop 1
	v_cndmask_b32_e64 v0, v0, v2, s[38:39]
	v_cndmask_b32_e32 v2, 0, v145, vcc
	v_sub_f32_e32 v0, v0, v2
	v_sub_f32_e32 v0, v1, v0
	v_fmamk_f32 v227, v0, 0x3d800000, v226
	global_load_dwordx4 v[0:3], v67, s[98:99] offset:1232
	global_load_dwordx4 v[4:7], v67, s[98:99] offset:1216
	global_load_dwordx4 v[8:11], v67, s[98:99] offset:1200
	global_load_dwordx4 v[12:15], v67, s[98:99] offset:1184
	s_waitcnt vmcnt(7)
	v_mul_f32_e32 v71, v33, v71
	s_waitcnt vmcnt(6)
	v_mul_f32_e32 v75, v32, v75
	s_waitcnt vmcnt(5)
	v_mul_f32_e32 v79, v25, v79
	s_waitcnt vmcnt(4)
	v_mul_f32_e32 v83, v21, v83
	v_fmac_f32_e32 v83, v19, v82
	v_fmac_f32_e32 v83, v20, v84
	v_fmac_f32_e32 v79, v23, v78
	v_fmac_f32_e32 v83, v18, v85
	v_fmac_f32_e32 v79, v24, v80
	v_fmac_f32_e32 v75, v27, v74
	v_add_f32_e32 v82, v34, v83
	v_fmac_f32_e32 v79, v22, v81
	v_fmac_f32_e32 v75, v28, v76
	v_fmac_f32_e32 v71, v30, v70
	v_add_f32_e32 v78, v82, v79
	v_fmac_f32_e32 v75, v26, v77
	v_fmac_f32_e32 v71, v31, v72
	v_add_f32_e32 v74, v78, v75
	v_fmac_f32_e32 v71, v29, v73
	v_add_f32_e32 v70, v74, v71
	v_min_f32_e32 v71, 0, v70
	v_mul_f32_e64 v70, |v70|, s59
	v_exp_f32_e32 v70, v70
	s_nop 0
	v_add_f32_e32 v70, 1.0, v70
	v_cmp_gt_f32_e32 vcc, s83, v70
	s_nop 1
	v_cndmask_b32_e64 v72, 0, 32, vcc
	v_ldexp_f32 v70, v70, v72
	v_log_f32_e32 v70, v70
	s_nop 0
	v_mul_f32_e32 v72, 0x3f317217, v70
	v_fma_f32 v72, v70, s87, -v72
	v_fmac_f32_e32 v72, 0x3377d1cf, v70
	v_fmac_f32_e32 v72, 0x3f317217, v70
	v_cmp_lt_f32_e64 s[38:39], |v70|, s73
	s_nop 1
	v_cndmask_b32_e64 v70, v70, v72, s[38:39]
	v_cndmask_b32_e32 v72, 0, v145, vcc
	v_sub_f32_e32 v70, v70, v72
	v_sub_f32_e32 v70, v71, v70
	v_fmamk_f32 v228, v70, 0x3d800000, v227
	global_load_dwordx4 v[70:73], v67, s[98:99] offset:1360
	global_load_dwordx4 v[74:77], v67, s[98:99] offset:1344
	global_load_dwordx4 v[78:81], v67, s[98:99] offset:1328
	global_load_dwordx4 v[82:85], v67, s[98:99] offset:1312
	s_waitcnt vmcnt(7)
; DI float logsig_fast(float z) { return fminf(z, 0.f) - __logf(1.0f + __expf(-fabsf(z))); }
; DI void p2_unit(int chunk, const Params& p, LAS unsigned char* lds) {
;     ...
;       for (int j2 = 0; j2 < 32; ++j2) { const f32x4* ar = (const f32x4*)(aux + (size_t)(tok0 + t0u + j2) * 32 + 8);
;           float z = bgc;
; #pragma unroll
;           for (int r4 = 0; r4 < 4; ++r4) { const f32x4 a = ar[r4]; z += a.x * w2c[4 * r4] + a.y * w2c[4 * r4 + 1] + a.z * w2c[4 * r4 + 2] + a.w * w2c[4 * r4 + 3]; }
;           bc += logsig_fast(z) * (1.0f / 16.0f); lc[j2] = bc; }
	v_mul_f32_e32 v1, v33, v1
	s_waitcnt vmcnt(6)
	v_mul_f32_e32 v5, v32, v5
	s_waitcnt vmcnt(5)
	v_mul_f32_e32 v9, v25, v9
	s_waitcnt vmcnt(4)
	v_mul_f32_e32 v13, v21, v13
	v_fmac_f32_e32 v13, v19, v12
	v_fmac_f32_e32 v13, v20, v14
	v_fmac_f32_e32 v9, v23, v8
	v_fmac_f32_e32 v13, v18, v15
	v_fmac_f32_e32 v9, v24, v10
	v_fmac_f32_e32 v5, v27, v4
	v_add_f32_e32 v12, v34, v13
	v_fmac_f32_e32 v9, v22, v11
	v_fmac_f32_e32 v5, v28, v6
	v_fmac_f32_e32 v1, v30, v0
	v_add_f32_e32 v8, v12, v9
	v_fmac_f32_e32 v5, v26, v7
	v_fmac_f32_e32 v1, v31, v2
	v_add_f32_e32 v4, v8, v5
	v_fmac_f32_e32 v1, v29, v3
	v_add_f32_e32 v0, v4, v1
	v_min_f32_e32 v1, 0, v0
	v_mul_f32_e64 v0, |v0|, s59
	v_exp_f32_e32 v0, v0
	s_nop 0
	v_add_f32_e32 v0, 1.0, v0
	v_cmp_gt_f32_e32 vcc, s83, v0
	s_nop 1
	v_cndmask_b32_e64 v2, 0, 32, vcc
	v_ldexp_f32 v0, v0, v2
	v_log_f32_e32 v0, v0
	s_nop 0
	v_mul_f32_e32 v2, 0x3f317217, v0
	v_fma_f32 v2, v0, s87, -v2
	v_fmac_f32_e32 v2, 0x3377d1cf, v0
	v_fmac_f32_e32 v2, 0x3f317217, v0
	v_cmp_lt_f32_e64 s[38:39], |v0|, s73
	s_nop 1
	v_cndmask_b32_e64 v0, v0, v2, s[38:39]
	v_cndmask_b32_e32 v2, 0, v145, vcc
	v_sub_f32_e32 v0, v0, v2
	v_sub_f32_e32 v0, v1, v0
	v_fmamk_f32 v229, v0, 0x3d800000, v228
	global_load_dwordx4 v[0:3], v67, s[98:99] offset:1488
	global_load_dwordx4 v[4:7], v67, s[98:99] offset:1472
	global_load_dwordx4 v[8:11], v67, s[98:99] offset:1456
	global_load_dwordx4 v[12:15], v67, s[98:99] offset:1440
	s_waitcnt vmcnt(7)
	v_mul_f32_e32 v71, v33, v71
	s_waitcnt vmcnt(6)
	v_mul_f32_e32 v75, v32, v75
	s_waitcnt vmcnt(5)
	v_mul_f32_e32 v79, v25, v79
	s_waitcnt vmcnt(4)
	v_mul_f32_e32 v83, v21, v83
	v_fmac_f32_e32 v83, v19, v82
	v_fmac_f32_e32 v83, v20, v84
	v_fmac_f32_e32 v79, v23, v78
	v_fmac_f32_e32 v83, v18, v85
	v_fmac_f32_e32 v79, v24, v80
	v_fmac_f32_e32 v75, v27, v74
	v_add_f32_e32 v82, v34, v83
	v_fmac_f32_e32 v79, v22, v81
	v_fmac_f32_e32 v75, v28, v76
	v_fmac_f32_e32 v71, v30, v70
	v_add_f32_e32 v78, v82, v79
	v_fmac_f32_e32 v75, v26, v77
	v_fmac_f32_e32 v71, v31, v72
	v_add_f32_e32 v74, v78, v75
	v_fmac_f32_e32 v71, v29, v73
	v_add_f32_e32 v70, v74, v71
	v_min_f32_e32 v71, 0, v70
	v_mul_f32_e64 v70, |v70|, s59
	v_exp_f32_e32 v70, v70
	s_nop 0
	v_add_f32_e32 v70, 1.0, v70
	v_cmp_gt_f32_e32 vcc, s83, v70
	s_nop 1
	v_cndmask_b32_e64 v72, 0, 32, vcc
	v_ldexp_f32 v70, v70, v72
	v_log_f32_e32 v70, v70
	s_nop 0
	v_mul_f32_e32 v72, 0x3f317217, v70
	v_fma_f32 v72, v70, s87, -v72
	v_fmac_f32_e32 v72, 0x3377d1cf, v70
	v_fmac_f32_e32 v72, 0x3f317217, v70
	v_cmp_lt_f32_e64 s[38:39], |v70|, s73
	s_nop 1
	v_cndmask_b32_e64 v70, v70, v72, s[38:39]
	v_cndmask_b32_e32 v72, 0, v145, vcc
	v_sub_f32_e32 v70, v70, v72
	v_sub_f32_e32 v70, v71, v70
	v_fmamk_f32 v230, v70, 0x3d800000, v229
	global_load_dwordx4 v[70:73], v67, s[98:99] offset:1616
	global_load_dwordx4 v[74:77], v67, s[98:99] offset:1600
	global_load_dwordx4 v[78:81], v67, s[98:99] offset:1584
	global_load_dwordx4 v[82:85], v67, s[98:99] offset:1568
	s_waitcnt vmcnt(7)
	v_mul_f32_e32 v1, v33, v1
	s_waitcnt vmcnt(6)
	v_mul_f32_e32 v5, v32, v5
	s_waitcnt vmcnt(5)
	v_mul_f32_e32 v9, v25, v9
	s_waitcnt vmcnt(4)
	v_mul_f32_e32 v13, v21, v13
	v_fmac_f32_e32 v13, v19, v12
	v_fmac_f32_e32 v13, v20, v14
	v_fmac_f32_e32 v9, v23, v8
	v_fmac_f32_e32 v13, v18, v15
	v_fmac_f32_e32 v9, v24, v10
	v_fmac_f32_e32 v5, v27, v4
	v_add_f32_e32 v12, v34, v13
	v_fmac_f32_e32 v9, v22, v11
	v_fmac_f32_e32 v5, v28, v6
	v_fmac_f32_e32 v1, v30, v0
	v_add_f32_e32 v8, v12, v9
	v_fmac_f32_e32 v5, v26, v7
	v_fmac_f32_e32 v1, v31, v2
	v_add_f32_e32 v4, v8, v5
	v_fmac_f32_e32 v1, v29, v3
	v_add_f32_e32 v0, v4, v1
	v_min_f32_e32 v1, 0, v0
	v_mul_f32_e64 v0, |v0|, s59
	v_exp_f32_e32 v0, v0
	s_nop 0
	v_add_f32_e32 v0, 1.0, v0
	v_cmp_gt_f32_e32 vcc, s83, v0
	s_nop 1
	v_cndmask_b32_e64 v2, 0, 32, vcc
	v_ldexp_f32 v0, v0, v2
	v_log_f32_e32 v0, v0
	s_nop 0
	v_mul_f32_e32 v2, 0x3f317217, v0
	v_fma_f32 v2, v0, s87, -v2
	v_fmac_f32_e32 v2, 0x3377d1cf, v0
	v_fmac_f32_e32 v2, 0x3f317217, v0
	v_cmp_lt_f32_e64 s[38:39], |v0|, s73
	s_nop 1
	v_cndmask_b32_e64 v0, v0, v2, s[38:39]
	v_cndmask_b32_e32 v2, 0, v145, vcc
	v_sub_f32_e32 v0, v0, v2
	v_sub_f32_e32 v0, v1, v0
	v_fmamk_f32 v231, v0, 0x3d800000, v230
	global_load_dwordx4 v[0:3], v67, s[98:99] offset:1744
	global_load_dwordx4 v[4:7], v67, s[98:99] offset:1728
	global_load_dwordx4 v[8:11], v67, s[98:99] offset:1712
	global_load_dwordx4 v[12:15], v67, s[98:99] offset:1696
	s_waitcnt vmcnt(7)
	v_mul_f32_e32 v71, v33, v71
	s_waitcnt vmcnt(6)
	v_mul_f32_e32 v75, v32, v75
	s_waitcnt vmcnt(5)
	v_mul_f32_e32 v79, v25, v79
	s_waitcnt vmcnt(4)
	v_mul_f32_e32 v83, v21, v83
	v_fmac_f32_e32 v83, v19, v82
	v_fmac_f32_e32 v83, v20, v84
	v_fmac_f32_e32 v79, v23, v78
	v_fmac_f32_e32 v83, v18, v85
	v_fmac_f32_e32 v79, v24, v80
	v_fmac_f32_e32 v75, v27, v74
	v_add_f32_e32 v82, v34, v83
	v_fmac_f32_e32 v79, v22, v81
	v_fmac_f32_e32 v75, v28, v76
	v_fmac_f32_e32 v71, v30, v70
	v_add_f32_e32 v78, v82, v79
	v_fmac_f32_e32 v75, v26, v77
	v_fmac_f32_e32 v71, v31, v72
	v_add_f32_e32 v74, v78, v75
	v_fmac_f32_e32 v71, v29, v73
	v_add_f32_e32 v70, v74, v71
	v_min_f32_e32 v71, 0, v70
	v_mul_f32_e64 v70, |v70|, s59
	v_exp_f32_e32 v70, v70
	s_nop 0
	v_add_f32_e32 v70, 1.0, v70
	v_cmp_gt_f32_e32 vcc, s83, v70
	s_nop 1
	v_cndmask_b32_e64 v72, 0, 32, vcc
	v_ldexp_f32 v70, v70, v72
	v_log_f32_e32 v70, v70
	s_nop 0
	v_mul_f32_e32 v72, 0x3f317217, v70
	v_fma_f32 v72, v70, s87, -v72
	v_fmac_f32_e32 v72, 0x3377d1cf, v70
	v_fmac_f32_e32 v72, 0x3f317217, v70
	v_cmp_lt_f32_e64 s[38:39], |v70|, s73
	s_nop 1
	v_cndmask_b32_e64 v70, v70, v72, s[38:39]
	v_cndmask_b32_e32 v72, 0, v145, vcc
	v_sub_f32_e32 v70, v70, v72
	v_sub_f32_e32 v70, v71, v70
	v_fmamk_f32 v232, v70, 0x3d800000, v231
	global_load_dwordx4 v[70:73], v67, s[98:99] offset:1872
	global_load_dwordx4 v[74:77], v67, s[98:99] offset:1856
	global_load_dwordx4 v[78:81], v67, s[98:99] offset:1840
	global_load_dwordx4 v[82:85], v67, s[98:99] offset:1824
	s_waitcnt vmcnt(7)
; DI float logsig_fast(float z) { return fminf(z, 0.f) - __logf(1.0f + __expf(-fabsf(z))); }
; DI void p2_unit(int chunk, const Params& p, LAS unsigned char* lds) {
;     ...
;       for (int j2 = 0; j2 < 32; ++j2) { const f32x4* ar = (const f32x4*)(aux + (size_t)(tok0 + t0u + j2) * 32 + 8);
;           float z = bgc;
; #pragma unroll
;           for (int r4 = 0; r4 < 4; ++r4) { const f32x4 a = ar[r4]; z += a.x * w2c[4 * r4] + a.y * w2c[4 * r4 + 1] + a.z * w2c[4 * r4 + 2] + a.w * w2c[4 * r4 + 3]; }
;           bc += logsig_fast(z) * (1.0f / 16.0f); lc[j2] = bc; }
	v_mul_f32_e32 v1, v33, v1
	s_waitcnt vmcnt(6)
	v_mul_f32_e32 v5, v32, v5
	s_waitcnt vmcnt(5)
	v_mul_f32_e32 v9, v25, v9
	s_waitcnt vmcnt(4)
	v_mul_f32_e32 v13, v21, v13
	v_fmac_f32_e32 v13, v19, v12
	v_fmac_f32_e32 v13, v20, v14
	v_fmac_f32_e32 v9, v23, v8
	v_fmac_f32_e32 v13, v18, v15
	v_fmac_f32_e32 v9, v24, v10
	v_fmac_f32_e32 v5, v27, v4
	v_add_f32_e32 v12, v34, v13
	v_fmac_f32_e32 v9, v22, v11
	v_fmac_f32_e32 v5, v28, v6
	v_fmac_f32_e32 v1, v30, v0
	v_add_f32_e32 v8, v12, v9
	v_fmac_f32_e32 v5, v26, v7
	v_fmac_f32_e32 v1, v31, v2
	v_add_f32_e32 v4, v8, v5
	v_fmac_f32_e32 v1, v29, v3
	v_add_f32_e32 v0, v4, v1
	v_min_f32_e32 v1, 0, v0
	v_mul_f32_e64 v0, |v0|, s59
	v_exp_f32_e32 v0, v0
	s_nop 0
	v_add_f32_e32 v0, 1.0, v0
	v_cmp_gt_f32_e32 vcc, s83, v0
	s_nop 1
	v_cndmask_b32_e64 v2, 0, 32, vcc
	v_ldexp_f32 v0, v0, v2
	v_log_f32_e32 v0, v0
	s_nop 0
	v_mul_f32_e32 v2, 0x3f317217, v0
	v_fma_f32 v2, v0, s87, -v2
	v_fmac_f32_e32 v2, 0x3377d1cf, v0
	v_fmac_f32_e32 v2, 0x3f317217, v0
	v_cmp_lt_f32_e64 s[38:39], |v0|, s73
	s_nop 1
	v_cndmask_b32_e64 v0, v0, v2, s[38:39]
	v_cndmask_b32_e32 v2, 0, v145, vcc
	v_sub_f32_e32 v0, v0, v2
	v_sub_f32_e32 v0, v1, v0
	v_fmamk_f32 v233, v0, 0x3d800000, v232
	global_load_dwordx4 v[0:3], v67, s[98:99] offset:2000
	global_load_dwordx4 v[4:7], v67, s[98:99] offset:1984
	global_load_dwordx4 v[8:11], v67, s[98:99] offset:1968
	global_load_dwordx4 v[12:15], v67, s[98:99] offset:1952
	s_waitcnt vmcnt(7)
	v_mul_f32_e32 v71, v33, v71
	s_waitcnt vmcnt(6)
	v_mul_f32_e32 v75, v32, v75
	s_waitcnt vmcnt(5)
	v_mul_f32_e32 v79, v25, v79
	s_waitcnt vmcnt(4)
	v_mul_f32_e32 v83, v21, v83
	v_fmac_f32_e32 v83, v19, v82
	v_fmac_f32_e32 v83, v20, v84
	v_fmac_f32_e32 v79, v23, v78
	v_fmac_f32_e32 v83, v18, v85
	v_fmac_f32_e32 v79, v24, v80
	v_fmac_f32_e32 v75, v27, v74
	v_add_f32_e32 v82, v34, v83
	v_fmac_f32_e32 v79, v22, v81
	v_fmac_f32_e32 v75, v28, v76
	v_fmac_f32_e32 v71, v30, v70
	v_add_f32_e32 v78, v82, v79
	v_fmac_f32_e32 v75, v26, v77
	v_fmac_f32_e32 v71, v31, v72
	v_add_f32_e32 v74, v78, v75
	v_fmac_f32_e32 v71, v29, v73
	v_add_f32_e32 v70, v74, v71
	v_min_f32_e32 v71, 0, v70
	v_mul_f32_e64 v70, |v70|, s59
	v_exp_f32_e32 v70, v70
	s_nop 0
	v_add_f32_e32 v70, 1.0, v70
	v_cmp_gt_f32_e32 vcc, s83, v70
	s_nop 1
	v_cndmask_b32_e64 v72, 0, 32, vcc
	v_ldexp_f32 v70, v70, v72
	v_log_f32_e32 v70, v70
	s_nop 0
	v_mul_f32_e32 v72, 0x3f317217, v70
	v_fma_f32 v72, v70, s87, -v72
	v_fmac_f32_e32 v72, 0x3377d1cf, v70
	v_fmac_f32_e32 v72, 0x3f317217, v70
	v_cmp_lt_f32_e64 s[38:39], |v70|, s73
	s_nop 1
	v_cndmask_b32_e64 v70, v70, v72, s[38:39]
	v_cndmask_b32_e32 v72, 0, v145, vcc
	v_sub_f32_e32 v70, v70, v72
	v_sub_f32_e32 v70, v71, v70
	v_fmamk_f32 v234, v70, 0x3d800000, v233
	global_load_dwordx4 v[70:73], v67, s[98:99] offset:2128
	global_load_dwordx4 v[74:77], v67, s[98:99] offset:2112
	global_load_dwordx4 v[78:81], v67, s[98:99] offset:2096
	global_load_dwordx4 v[82:85], v67, s[98:99] offset:2080
	s_waitcnt vmcnt(7)
	v_mul_f32_e32 v1, v33, v1
	s_waitcnt vmcnt(6)
	v_mul_f32_e32 v5, v32, v5
	s_waitcnt vmcnt(5)
	v_mul_f32_e32 v9, v25, v9
	s_waitcnt vmcnt(4)
	v_mul_f32_e32 v13, v21, v13
	v_fmac_f32_e32 v13, v19, v12
	v_fmac_f32_e32 v13, v20, v14
	v_fmac_f32_e32 v9, v23, v8
	v_fmac_f32_e32 v13, v18, v15
	v_fmac_f32_e32 v9, v24, v10
	v_fmac_f32_e32 v5, v27, v4
	v_add_f32_e32 v12, v34, v13
	v_fmac_f32_e32 v9, v22, v11
	v_fmac_f32_e32 v5, v28, v6
	v_fmac_f32_e32 v1, v30, v0
	v_add_f32_e32 v8, v12, v9
	v_fmac_f32_e32 v5, v26, v7
	v_fmac_f32_e32 v1, v31, v2
	v_add_f32_e32 v4, v8, v5
	v_fmac_f32_e32 v1, v29, v3
	v_add_f32_e32 v0, v4, v1
	v_min_f32_e32 v1, 0, v0
	v_mul_f32_e64 v0, |v0|, s59
	v_exp_f32_e32 v0, v0
	s_nop 0
	v_add_f32_e32 v0, 1.0, v0
	v_cmp_gt_f32_e32 vcc, s83, v0
	s_nop 1
	v_cndmask_b32_e64 v2, 0, 32, vcc
	v_ldexp_f32 v0, v0, v2
	v_log_f32_e32 v0, v0
	s_nop 0
	v_mul_f32_e32 v2, 0x3f317217, v0
	v_fma_f32 v2, v0, s87, -v2
	v_fmac_f32_e32 v2, 0x3377d1cf, v0
	v_fmac_f32_e32 v2, 0x3f317217, v0
	v_cmp_lt_f32_e64 s[38:39], |v0|, s73
	s_nop 1
	v_cndmask_b32_e64 v0, v0, v2, s[38:39]
	v_cndmask_b32_e32 v2, 0, v145, vcc
	v_sub_f32_e32 v0, v0, v2
	v_sub_f32_e32 v0, v1, v0
	v_fmamk_f32 v235, v0, 0x3d800000, v234
	global_load_dwordx4 v[0:3], v67, s[98:99] offset:2256
	global_load_dwordx4 v[4:7], v67, s[98:99] offset:2240
	global_load_dwordx4 v[8:11], v67, s[98:99] offset:2224
	global_load_dwordx4 v[12:15], v67, s[98:99] offset:2208
	s_waitcnt vmcnt(7)
	v_mul_f32_e32 v71, v33, v71
	s_waitcnt vmcnt(6)
	v_mul_f32_e32 v75, v32, v75
	s_waitcnt vmcnt(5)
	v_mul_f32_e32 v79, v25, v79
	s_waitcnt vmcnt(4)
	v_mul_f32_e32 v83, v21, v83
	v_fmac_f32_e32 v83, v19, v82
	v_fmac_f32_e32 v83, v20, v84
	v_fmac_f32_e32 v79, v23, v78
	v_fmac_f32_e32 v83, v18, v85
	v_fmac_f32_e32 v79, v24, v80
	v_fmac_f32_e32 v75, v27, v74
	v_add_f32_e32 v82, v34, v83
	v_fmac_f32_e32 v79, v22, v81
	v_fmac_f32_e32 v75, v28, v76
	v_fmac_f32_e32 v71, v30, v70
	v_add_f32_e32 v78, v82, v79
	v_fmac_f32_e32 v75, v26, v77
	v_fmac_f32_e32 v71, v31, v72
	v_add_f32_e32 v74, v78, v75
	v_fmac_f32_e32 v71, v29, v73
	v_add_f32_e32 v70, v74, v71
	v_min_f32_e32 v71, 0, v70
	v_mul_f32_e64 v70, |v70|, s59
	v_exp_f32_e32 v70, v70
	s_nop 0
	v_add_f32_e32 v70, 1.0, v70
	v_cmp_gt_f32_e32 vcc, s83, v70
	s_nop 1
	v_cndmask_b32_e64 v72, 0, 32, vcc
	v_ldexp_f32 v70, v70, v72
	v_log_f32_e32 v70, v70
	s_nop 0
	v_mul_f32_e32 v72, 0x3f317217, v70
	v_fma_f32 v72, v70, s87, -v72
	v_fmac_f32_e32 v72, 0x3377d1cf, v70
	v_fmac_f32_e32 v72, 0x3f317217, v70
	v_cmp_lt_f32_e64 s[38:39], |v70|, s73
	s_nop 1
	v_cndmask_b32_e64 v70, v70, v72, s[38:39]
	v_cndmask_b32_e32 v72, 0, v145, vcc
	v_sub_f32_e32 v70, v70, v72
	v_sub_f32_e32 v70, v71, v70
	v_fmamk_f32 v236, v70, 0x3d800000, v235
	global_load_dwordx4 v[70:73], v67, s[98:99] offset:2384
	global_load_dwordx4 v[74:77], v67, s[98:99] offset:2368
	global_load_dwordx4 v[78:81], v67, s[98:99] offset:2352
	global_load_dwordx4 v[82:85], v67, s[98:99] offset:2336
	s_waitcnt vmcnt(7)
; DI float logsig_fast(float z) { return fminf(z, 0.f) - __logf(1.0f + __expf(-fabsf(z))); }
; DI void p2_unit(int chunk, const Params& p, LAS unsigned char* lds) {
;     ...
;       for (int j2 = 0; j2 < 32; ++j2) { const f32x4* ar = (const f32x4*)(aux + (size_t)(tok0 + t0u + j2) * 32 + 8);
;           float z = bgc;
; #pragma unroll
;           for (int r4 = 0; r4 < 4; ++r4) { const f32x4 a = ar[r4]; z += a.x * w2c[4 * r4] + a.y * w2c[4 * r4 + 1] + a.z * w2c[4 * r4 + 2] + a.w * w2c[4 * r4 + 3]; }
;           bc += logsig_fast(z) * (1.0f / 16.0f); lc[j2] = bc; }
	v_mul_f32_e32 v1, v33, v1
	s_waitcnt vmcnt(6)
	v_mul_f32_e32 v5, v32, v5
	s_waitcnt vmcnt(5)
	v_mul_f32_e32 v9, v25, v9
	s_waitcnt vmcnt(4)
	v_mul_f32_e32 v13, v21, v13
	v_fmac_f32_e32 v13, v19, v12
	v_fmac_f32_e32 v13, v20, v14
	v_fmac_f32_e32 v9, v23, v8
	v_fmac_f32_e32 v13, v18, v15
	v_fmac_f32_e32 v9, v24, v10
	v_fmac_f32_e32 v5, v27, v4
	v_add_f32_e32 v12, v34, v13
	v_fmac_f32_e32 v9, v22, v11
	v_fmac_f32_e32 v5, v28, v6
	v_fmac_f32_e32 v1, v30, v0
	v_add_f32_e32 v8, v12, v9
	v_fmac_f32_e32 v5, v26, v7
	v_fmac_f32_e32 v1, v31, v2
	v_add_f32_e32 v4, v8, v5
	v_fmac_f32_e32 v1, v29, v3
	v_add_f32_e32 v0, v4, v1
	v_min_f32_e32 v1, 0, v0
	v_mul_f32_e64 v0, |v0|, s59
	v_exp_f32_e32 v0, v0
	s_nop 0
	v_add_f32_e32 v0, 1.0, v0
	v_cmp_gt_f32_e32 vcc, s83, v0
	s_nop 1
	v_cndmask_b32_e64 v2, 0, 32, vcc
	v_ldexp_f32 v0, v0, v2
	v_log_f32_e32 v0, v0
	s_nop 0
	v_mul_f32_e32 v2, 0x3f317217, v0
	v_fma_f32 v2, v0, s87, -v2
	v_fmac_f32_e32 v2, 0x3377d1cf, v0
	v_fmac_f32_e32 v2, 0x3f317217, v0
	v_cmp_lt_f32_e64 s[38:39], |v0|, s73
	s_nop 1
	v_cndmask_b32_e64 v0, v0, v2, s[38:39]
	v_cndmask_b32_e32 v2, 0, v145, vcc
	v_sub_f32_e32 v0, v0, v2
	v_sub_f32_e32 v0, v1, v0
	v_fmamk_f32 v237, v0, 0x3d800000, v236
	global_load_dwordx4 v[0:3], v67, s[98:99] offset:2512
	global_load_dwordx4 v[4:7], v67, s[98:99] offset:2496
	global_load_dwordx4 v[8:11], v67, s[98:99] offset:2480
	global_load_dwordx4 v[12:15], v67, s[98:99] offset:2464
	s_waitcnt vmcnt(7)
	v_mul_f32_e32 v71, v33, v71
	s_waitcnt vmcnt(6)
	v_mul_f32_e32 v75, v32, v75
	s_waitcnt vmcnt(5)
	v_mul_f32_e32 v79, v25, v79
	s_waitcnt vmcnt(4)
	v_mul_f32_e32 v83, v21, v83
	v_fmac_f32_e32 v83, v19, v82
	v_fmac_f32_e32 v83, v20, v84
	v_fmac_f32_e32 v79, v23, v78
	v_fmac_f32_e32 v83, v18, v85
	v_fmac_f32_e32 v79, v24, v80
	v_fmac_f32_e32 v75, v27, v74
	v_add_f32_e32 v82, v34, v83
	v_fmac_f32_e32 v79, v22, v81
	v_fmac_f32_e32 v75, v28, v76
	v_fmac_f32_e32 v71, v30, v70
	v_add_f32_e32 v78, v82, v79
	v_fmac_f32_e32 v75, v26, v77
	v_fmac_f32_e32 v71, v31, v72
	v_add_f32_e32 v74, v78, v75
	v_fmac_f32_e32 v71, v29, v73
	v_add_f32_e32 v70, v74, v71
	v_min_f32_e32 v71, 0, v70
	v_mul_f32_e64 v70, |v70|, s59
	v_exp_f32_e32 v70, v70
	s_nop 0
	v_add_f32_e32 v70, 1.0, v70
	v_cmp_gt_f32_e32 vcc, s83, v70
	s_nop 1
	v_cndmask_b32_e64 v72, 0, 32, vcc
	v_ldexp_f32 v70, v70, v72
	v_log_f32_e32 v70, v70
	s_nop 0
	v_mul_f32_e32 v72, 0x3f317217, v70
	v_fma_f32 v72, v70, s87, -v72
	v_fmac_f32_e32 v72, 0x3377d1cf, v70
	v_fmac_f32_e32 v72, 0x3f317217, v70
	v_cmp_lt_f32_e64 s[38:39], |v70|, s73
	s_nop 1
	v_cndmask_b32_e64 v70, v70, v72, s[38:39]
	v_cndmask_b32_e32 v72, 0, v145, vcc
	v_sub_f32_e32 v70, v70, v72
	v_sub_f32_e32 v70, v71, v70
	v_fmamk_f32 v238, v70, 0x3d800000, v237
	global_load_dwordx4 v[70:73], v67, s[98:99] offset:2640
	global_load_dwordx4 v[74:77], v67, s[98:99] offset:2624
	global_load_dwordx4 v[78:81], v67, s[98:99] offset:2608
	global_load_dwordx4 v[82:85], v67, s[98:99] offset:2592
	s_waitcnt vmcnt(7)
	v_mul_f32_e32 v1, v33, v1
	s_waitcnt vmcnt(6)
	v_mul_f32_e32 v5, v32, v5
	s_waitcnt vmcnt(5)
	v_mul_f32_e32 v9, v25, v9
	s_waitcnt vmcnt(4)
	v_mul_f32_e32 v13, v21, v13
	v_fmac_f32_e32 v13, v19, v12
	v_fmac_f32_e32 v13, v20, v14
	v_fmac_f32_e32 v9, v23, v8
	v_fmac_f32_e32 v13, v18, v15
	v_fmac_f32_e32 v9, v24, v10
	v_fmac_f32_e32 v5, v27, v4
	v_add_f32_e32 v12, v34, v13
	v_fmac_f32_e32 v9, v22, v11
	v_fmac_f32_e32 v5, v28, v6
	v_fmac_f32_e32 v1, v30, v0
	v_add_f32_e32 v8, v12, v9
	v_fmac_f32_e32 v5, v26, v7
	v_fmac_f32_e32 v1, v31, v2
	v_add_f32_e32 v4, v8, v5
	v_fmac_f32_e32 v1, v29, v3
	v_add_f32_e32 v0, v4, v1
	v_min_f32_e32 v1, 0, v0
	v_mul_f32_e64 v0, |v0|, s59
	v_exp_f32_e32 v0, v0
	s_nop 0
	v_add_f32_e32 v0, 1.0, v0
	v_cmp_gt_f32_e32 vcc, s83, v0
	s_nop 1
	v_cndmask_b32_e64 v2, 0, 32, vcc
	v_ldexp_f32 v0, v0, v2
	v_log_f32_e32 v0, v0
	s_nop 0
	v_mul_f32_e32 v2, 0x3f317217, v0
	v_fma_f32 v2, v0, s87, -v2
	v_fmac_f32_e32 v2, 0x3377d1cf, v0
	v_fmac_f32_e32 v2, 0x3f317217, v0
	v_cmp_lt_f32_e64 s[38:39], |v0|, s73
	s_nop 1
	v_cndmask_b32_e64 v0, v0, v2, s[38:39]
	v_cndmask_b32_e32 v2, 0, v145, vcc
	v_sub_f32_e32 v0, v0, v2
	v_sub_f32_e32 v0, v1, v0
	v_fmamk_f32 v239, v0, 0x3d800000, v238
	global_load_dwordx4 v[0:3], v67, s[98:99] offset:2768
	global_load_dwordx4 v[4:7], v67, s[98:99] offset:2752
	global_load_dwordx4 v[8:11], v67, s[98:99] offset:2736
	global_load_dwordx4 v[12:15], v67, s[98:99] offset:2720
	s_waitcnt vmcnt(7)
	v_mul_f32_e32 v71, v33, v71
	s_waitcnt vmcnt(6)
	v_mul_f32_e32 v75, v32, v75
	s_waitcnt vmcnt(5)
	v_mul_f32_e32 v79, v25, v79
	s_waitcnt vmcnt(4)
	v_mul_f32_e32 v83, v21, v83
	v_fmac_f32_e32 v83, v19, v82
	v_fmac_f32_e32 v83, v20, v84
	v_fmac_f32_e32 v79, v23, v78
	v_fmac_f32_e32 v83, v18, v85
	v_fmac_f32_e32 v79, v24, v80
	v_fmac_f32_e32 v75, v27, v74
	v_add_f32_e32 v82, v34, v83
	v_fmac_f32_e32 v79, v22, v81
	v_fmac_f32_e32 v75, v28, v76
	v_fmac_f32_e32 v71, v30, v70
	v_add_f32_e32 v78, v82, v79
	v_fmac_f32_e32 v75, v26, v77
	v_fmac_f32_e32 v71, v31, v72
	v_add_f32_e32 v74, v78, v75
	v_fmac_f32_e32 v71, v29, v73
	v_add_f32_e32 v70, v74, v71
	v_min_f32_e32 v71, 0, v70
	v_mul_f32_e64 v70, |v70|, s59
	v_exp_f32_e32 v70, v70
	s_nop 0
	v_add_f32_e32 v70, 1.0, v70
	v_cmp_gt_f32_e32 vcc, s83, v70
	s_nop 1
	v_cndmask_b32_e64 v72, 0, 32, vcc
	v_ldexp_f32 v70, v70, v72
	v_log_f32_e32 v70, v70
	s_nop 0
	v_mul_f32_e32 v72, 0x3f317217, v70
	v_fma_f32 v72, v70, s87, -v72
	v_fmac_f32_e32 v72, 0x3377d1cf, v70
	v_fmac_f32_e32 v72, 0x3f317217, v70
	v_cmp_lt_f32_e64 s[38:39], |v70|, s73
	s_nop 1
	v_cndmask_b32_e64 v70, v70, v72, s[38:39]
	v_cndmask_b32_e32 v72, 0, v145, vcc
	v_sub_f32_e32 v70, v70, v72
	v_sub_f32_e32 v70, v71, v70
	v_fmamk_f32 v240, v70, 0x3d800000, v239
	global_load_dwordx4 v[70:73], v67, s[98:99] offset:2896
	global_load_dwordx4 v[74:77], v67, s[98:99] offset:2880
	global_load_dwordx4 v[78:81], v67, s[98:99] offset:2864
	global_load_dwordx4 v[82:85], v67, s[98:99] offset:2848
	s_waitcnt vmcnt(7)
; DI float logsig_fast(float z) { return fminf(z, 0.f) - __logf(1.0f + __expf(-fabsf(z))); }
; DI void p2_unit(int chunk, const Params& p, LAS unsigned char* lds) {
;     ...
;       for (int j2 = 0; j2 < 32; ++j2) { const f32x4* ar = (const f32x4*)(aux + (size_t)(tok0 + t0u + j2) * 32 + 8);
;           float z = bgc;
; #pragma unroll
;           for (int r4 = 0; r4 < 4; ++r4) { const f32x4 a = ar[r4]; z += a.x * w2c[4 * r4] + a.y * w2c[4 * r4 + 1] + a.z * w2c[4 * r4 + 2] + a.w * w2c[4 * r4 + 3]; }
;           bc += logsig_fast(z) * (1.0f / 16.0f); lc[j2] = bc; }
	v_mul_f32_e32 v1, v33, v1
	s_waitcnt vmcnt(6)
	v_mul_f32_e32 v5, v32, v5
	s_waitcnt vmcnt(5)
	v_mul_f32_e32 v9, v25, v9
	s_waitcnt vmcnt(4)
	v_mul_f32_e32 v13, v21, v13
	v_fmac_f32_e32 v13, v19, v12
	v_fmac_f32_e32 v13, v20, v14
	v_fmac_f32_e32 v9, v23, v8
	v_fmac_f32_e32 v13, v18, v15
	v_fmac_f32_e32 v9, v24, v10
	v_fmac_f32_e32 v5, v27, v4
	v_add_f32_e32 v12, v34, v13
	v_fmac_f32_e32 v9, v22, v11
	v_fmac_f32_e32 v5, v28, v6
	v_fmac_f32_e32 v1, v30, v0
	v_add_f32_e32 v8, v12, v9
	v_fmac_f32_e32 v5, v26, v7
	v_fmac_f32_e32 v1, v31, v2
	v_add_f32_e32 v4, v8, v5
	v_fmac_f32_e32 v1, v29, v3
	v_add_f32_e32 v0, v4, v1
	v_min_f32_e32 v1, 0, v0
	v_mul_f32_e64 v0, |v0|, s59
	v_exp_f32_e32 v0, v0
	s_nop 0
	v_add_f32_e32 v0, 1.0, v0
	v_cmp_gt_f32_e32 vcc, s83, v0
	s_nop 1
	v_cndmask_b32_e64 v2, 0, 32, vcc
	v_ldexp_f32 v0, v0, v2
	v_log_f32_e32 v0, v0
	s_nop 0
	v_mul_f32_e32 v2, 0x3f317217, v0
	v_fma_f32 v2, v0, s87, -v2
	v_fmac_f32_e32 v2, 0x3377d1cf, v0
	v_fmac_f32_e32 v2, 0x3f317217, v0
	v_cmp_lt_f32_e64 s[38:39], |v0|, s73
	s_nop 1
	v_cndmask_b32_e64 v0, v0, v2, s[38:39]
	v_cndmask_b32_e32 v2, 0, v145, vcc
	v_sub_f32_e32 v0, v0, v2
	v_sub_f32_e32 v0, v1, v0
	v_fmamk_f32 v241, v0, 0x3d800000, v240
	global_load_dwordx4 v[0:3], v67, s[98:99] offset:3024
	global_load_dwordx4 v[4:7], v67, s[98:99] offset:3008
	global_load_dwordx4 v[8:11], v67, s[98:99] offset:2992
	global_load_dwordx4 v[12:15], v67, s[98:99] offset:2976
	s_waitcnt vmcnt(7)
	v_mul_f32_e32 v71, v33, v71
	s_waitcnt vmcnt(6)
	v_mul_f32_e32 v75, v32, v75
	s_waitcnt vmcnt(5)
	v_mul_f32_e32 v79, v25, v79
	s_waitcnt vmcnt(4)
	v_mul_f32_e32 v83, v21, v83
	v_fmac_f32_e32 v83, v19, v82
	v_fmac_f32_e32 v83, v20, v84
	v_fmac_f32_e32 v79, v23, v78
	v_fmac_f32_e32 v83, v18, v85
	v_fmac_f32_e32 v79, v24, v80
	v_fmac_f32_e32 v75, v27, v74
	v_add_f32_e32 v82, v34, v83
	v_fmac_f32_e32 v79, v22, v81
	v_fmac_f32_e32 v75, v28, v76
	v_fmac_f32_e32 v71, v30, v70
	v_add_f32_e32 v78, v82, v79
	v_fmac_f32_e32 v75, v26, v77
	v_fmac_f32_e32 v71, v31, v72
	v_add_f32_e32 v74, v78, v75
	v_fmac_f32_e32 v71, v29, v73
	v_add_f32_e32 v70, v74, v71
	v_min_f32_e32 v71, 0, v70
	v_mul_f32_e64 v70, |v70|, s59
	v_exp_f32_e32 v70, v70
	s_nop 0
	v_add_f32_e32 v70, 1.0, v70
	v_cmp_gt_f32_e32 vcc, s83, v70
	s_nop 1
	v_cndmask_b32_e64 v72, 0, 32, vcc
	v_ldexp_f32 v70, v70, v72
	v_log_f32_e32 v70, v70
	s_nop 0
	v_mul_f32_e32 v72, 0x3f317217, v70
	v_fma_f32 v72, v70, s87, -v72
	v_fmac_f32_e32 v72, 0x3377d1cf, v70
	v_fmac_f32_e32 v72, 0x3f317217, v70
	v_cmp_lt_f32_e64 s[38:39], |v70|, s73
	s_nop 1
	v_cndmask_b32_e64 v70, v70, v72, s[38:39]
	v_cndmask_b32_e32 v72, 0, v145, vcc
	v_sub_f32_e32 v70, v70, v72
	v_sub_f32_e32 v70, v71, v70
	v_fmamk_f32 v242, v70, 0x3d800000, v241
	global_load_dwordx4 v[70:73], v67, s[98:99] offset:3152
	global_load_dwordx4 v[74:77], v67, s[98:99] offset:3136
	global_load_dwordx4 v[78:81], v67, s[98:99] offset:3120
	global_load_dwordx4 v[82:85], v67, s[98:99] offset:3104
	s_waitcnt vmcnt(7)
	v_mul_f32_e32 v1, v33, v1
	s_waitcnt vmcnt(6)
	v_mul_f32_e32 v5, v32, v5
	s_waitcnt vmcnt(5)
	v_mul_f32_e32 v9, v25, v9
	s_waitcnt vmcnt(4)
	v_mul_f32_e32 v13, v21, v13
	v_fmac_f32_e32 v13, v19, v12
	v_fmac_f32_e32 v13, v20, v14
	v_fmac_f32_e32 v9, v23, v8
	v_fmac_f32_e32 v13, v18, v15
	v_fmac_f32_e32 v9, v24, v10
	v_fmac_f32_e32 v5, v27, v4
	v_add_f32_e32 v12, v34, v13
	v_fmac_f32_e32 v9, v22, v11
	v_fmac_f32_e32 v5, v28, v6
	v_fmac_f32_e32 v1, v30, v0
	v_add_f32_e32 v8, v12, v9
	v_fmac_f32_e32 v5, v26, v7
	v_fmac_f32_e32 v1, v31, v2
	v_add_f32_e32 v4, v8, v5
	v_fmac_f32_e32 v1, v29, v3
	v_add_f32_e32 v0, v4, v1
	v_min_f32_e32 v1, 0, v0
	v_mul_f32_e64 v0, |v0|, s59
	v_exp_f32_e32 v0, v0
	s_nop 0
	v_add_f32_e32 v0, 1.0, v0
	v_cmp_gt_f32_e32 vcc, s83, v0
	s_nop 1
	v_cndmask_b32_e64 v2, 0, 32, vcc
	v_ldexp_f32 v0, v0, v2
	v_log_f32_e32 v0, v0
	s_nop 0
	v_mul_f32_e32 v2, 0x3f317217, v0
	v_fma_f32 v2, v0, s87, -v2
	v_fmac_f32_e32 v2, 0x3377d1cf, v0
	v_fmac_f32_e32 v2, 0x3f317217, v0
	v_cmp_lt_f32_e64 s[38:39], |v0|, s73
	s_nop 1
	v_cndmask_b32_e64 v0, v0, v2, s[38:39]
	v_cndmask_b32_e32 v2, 0, v145, vcc
	v_sub_f32_e32 v0, v0, v2
	v_sub_f32_e32 v0, v1, v0
	v_fmamk_f32 v243, v0, 0x3d800000, v242
	global_load_dwordx4 v[0:3], v67, s[98:99] offset:3280
	global_load_dwordx4 v[4:7], v67, s[98:99] offset:3264
	global_load_dwordx4 v[8:11], v67, s[98:99] offset:3248
	global_load_dwordx4 v[12:15], v67, s[98:99] offset:3232
	s_waitcnt vmcnt(7)
	v_mul_f32_e32 v71, v33, v71
	s_waitcnt vmcnt(6)
	v_mul_f32_e32 v75, v32, v75
	s_waitcnt vmcnt(5)
	v_mul_f32_e32 v79, v25, v79
	s_waitcnt vmcnt(4)
	v_mul_f32_e32 v83, v21, v83
	v_fmac_f32_e32 v83, v19, v82
	v_fmac_f32_e32 v83, v20, v84
	v_fmac_f32_e32 v79, v23, v78
	v_fmac_f32_e32 v83, v18, v85
	v_fmac_f32_e32 v79, v24, v80
	v_fmac_f32_e32 v75, v27, v74
	v_add_f32_e32 v82, v34, v83
	v_fmac_f32_e32 v79, v22, v81
	v_fmac_f32_e32 v75, v28, v76
	v_fmac_f32_e32 v71, v30, v70
	v_add_f32_e32 v78, v82, v79
	v_fmac_f32_e32 v75, v26, v77
	v_fmac_f32_e32 v71, v31, v72
	v_add_f32_e32 v74, v78, v75
	v_fmac_f32_e32 v71, v29, v73
	v_add_f32_e32 v70, v74, v71
	v_min_f32_e32 v71, 0, v70
	v_mul_f32_e64 v70, |v70|, s59
	v_exp_f32_e32 v70, v70
	s_nop 0
	v_add_f32_e32 v70, 1.0, v70
	v_cmp_gt_f32_e32 vcc, s83, v70
	s_nop 1
	v_cndmask_b32_e64 v72, 0, 32, vcc
	v_ldexp_f32 v70, v70, v72
	v_log_f32_e32 v70, v70
	s_nop 0
	v_mul_f32_e32 v72, 0x3f317217, v70
	v_fma_f32 v72, v70, s87, -v72
	v_fmac_f32_e32 v72, 0x3377d1cf, v70
	v_fmac_f32_e32 v72, 0x3f317217, v70
	v_cmp_lt_f32_e64 s[38:39], |v70|, s73
	s_nop 1
	v_cndmask_b32_e64 v70, v70, v72, s[38:39]
	v_cndmask_b32_e32 v72, 0, v145, vcc
	v_sub_f32_e32 v70, v70, v72
	v_sub_f32_e32 v70, v71, v70
	v_fmamk_f32 v244, v70, 0x3d800000, v243
	global_load_dwordx4 v[70:73], v67, s[98:99] offset:3408
	global_load_dwordx4 v[74:77], v67, s[98:99] offset:3392
	global_load_dwordx4 v[78:81], v67, s[98:99] offset:3376
	global_load_dwordx4 v[82:85], v67, s[98:99] offset:3360
	s_waitcnt vmcnt(7)
; DI float logsig_fast(float z) { return fminf(z, 0.f) - __logf(1.0f + __expf(-fabsf(z))); }
; DI void p2_unit(int chunk, const Params& p, LAS unsigned char* lds) {
;     ...
;       for (int j2 = 0; j2 < 32; ++j2) { const f32x4* ar = (const f32x4*)(aux + (size_t)(tok0 + t0u + j2) * 32 + 8);
;           float z = bgc;
; #pragma unroll
;           for (int r4 = 0; r4 < 4; ++r4) { const f32x4 a = ar[r4]; z += a.x * w2c[4 * r4] + a.y * w2c[4 * r4 + 1] + a.z * w2c[4 * r4 + 2] + a.w * w2c[4 * r4 + 3]; }
;           bc += logsig_fast(z) * (1.0f / 16.0f); lc[j2] = bc; }
	v_mul_f32_e32 v1, v33, v1
	s_waitcnt vmcnt(6)
	v_mul_f32_e32 v5, v32, v5
	s_waitcnt vmcnt(5)
	v_mul_f32_e32 v9, v25, v9
	s_waitcnt vmcnt(4)
	v_mul_f32_e32 v13, v21, v13
	v_fmac_f32_e32 v13, v19, v12
	v_fmac_f32_e32 v13, v20, v14
	v_fmac_f32_e32 v9, v23, v8
	v_fmac_f32_e32 v13, v18, v15
	v_fmac_f32_e32 v9, v24, v10
	v_fmac_f32_e32 v5, v27, v4
	v_add_f32_e32 v12, v34, v13
	v_fmac_f32_e32 v9, v22, v11
	v_fmac_f32_e32 v5, v28, v6
	v_fmac_f32_e32 v1, v30, v0
	v_add_f32_e32 v8, v12, v9
	v_fmac_f32_e32 v5, v26, v7
	v_fmac_f32_e32 v1, v31, v2
	v_add_f32_e32 v4, v8, v5
	v_fmac_f32_e32 v1, v29, v3
	v_add_f32_e32 v0, v4, v1
	v_min_f32_e32 v1, 0, v0
	v_mul_f32_e64 v0, |v0|, s59
	v_exp_f32_e32 v0, v0
	s_nop 0
	v_add_f32_e32 v0, 1.0, v0
	v_cmp_gt_f32_e32 vcc, s83, v0
	s_nop 1
	v_cndmask_b32_e64 v2, 0, 32, vcc
	v_ldexp_f32 v0, v0, v2
	v_log_f32_e32 v0, v0
	s_nop 0
	v_mul_f32_e32 v2, 0x3f317217, v0
	v_fma_f32 v2, v0, s87, -v2
	v_fmac_f32_e32 v2, 0x3377d1cf, v0
	v_fmac_f32_e32 v2, 0x3f317217, v0
	v_cmp_lt_f32_e64 s[38:39], |v0|, s73
	s_nop 1
	v_cndmask_b32_e64 v0, v0, v2, s[38:39]
	v_cndmask_b32_e32 v2, 0, v145, vcc
	v_sub_f32_e32 v0, v0, v2
	v_sub_f32_e32 v0, v1, v0
	v_fmamk_f32 v245, v0, 0x3d800000, v244
	global_load_dwordx4 v[0:3], v67, s[98:99] offset:3536
	global_load_dwordx4 v[4:7], v67, s[98:99] offset:3520
	global_load_dwordx4 v[8:11], v67, s[98:99] offset:3504
	global_load_dwordx4 v[12:15], v67, s[98:99] offset:3488
	s_waitcnt vmcnt(7)
	v_mul_f32_e32 v71, v33, v71
	s_waitcnt vmcnt(6)
	v_mul_f32_e32 v75, v32, v75
	s_waitcnt vmcnt(5)
	v_mul_f32_e32 v79, v25, v79
	s_waitcnt vmcnt(4)
	v_mul_f32_e32 v83, v21, v83
	v_fmac_f32_e32 v83, v19, v82
	v_fmac_f32_e32 v83, v20, v84
	v_fmac_f32_e32 v79, v23, v78
	v_fmac_f32_e32 v83, v18, v85
	v_fmac_f32_e32 v79, v24, v80
	v_fmac_f32_e32 v75, v27, v74
	v_add_f32_e32 v82, v34, v83
	v_fmac_f32_e32 v79, v22, v81
	v_fmac_f32_e32 v75, v28, v76
	v_fmac_f32_e32 v71, v30, v70
	v_add_f32_e32 v78, v82, v79
	v_fmac_f32_e32 v75, v26, v77
	v_fmac_f32_e32 v71, v31, v72
	v_add_f32_e32 v74, v78, v75
	v_fmac_f32_e32 v71, v29, v73
	v_add_f32_e32 v70, v74, v71
	v_min_f32_e32 v71, 0, v70
	v_mul_f32_e64 v70, |v70|, s59
	v_exp_f32_e32 v70, v70
	s_nop 0
	v_add_f32_e32 v70, 1.0, v70
	v_cmp_gt_f32_e32 vcc, s83, v70
	s_nop 1
	v_cndmask_b32_e64 v72, 0, 32, vcc
	v_ldexp_f32 v70, v70, v72
	v_log_f32_e32 v70, v70
	s_nop 0
	v_mul_f32_e32 v72, 0x3f317217, v70
	v_fma_f32 v72, v70, s87, -v72
	v_fmac_f32_e32 v72, 0x3377d1cf, v70
	v_fmac_f32_e32 v72, 0x3f317217, v70
	v_cmp_lt_f32_e64 s[38:39], |v70|, s73
	s_nop 1
	v_cndmask_b32_e64 v70, v70, v72, s[38:39]
	v_cndmask_b32_e32 v72, 0, v145, vcc
	v_sub_f32_e32 v70, v70, v72
	v_sub_f32_e32 v70, v71, v70
	v_fmamk_f32 v246, v70, 0x3d800000, v245
	global_load_dwordx4 v[70:73], v67, s[98:99] offset:3664
	global_load_dwordx4 v[74:77], v67, s[98:99] offset:3648
	global_load_dwordx4 v[78:81], v67, s[98:99] offset:3632
	global_load_dwordx4 v[82:85], v67, s[98:99] offset:3616
	s_waitcnt vmcnt(7)
	v_mul_f32_e32 v1, v33, v1
	s_waitcnt vmcnt(6)
	v_mul_f32_e32 v5, v32, v5
	s_waitcnt vmcnt(5)
	v_mul_f32_e32 v9, v25, v9
	s_waitcnt vmcnt(4)
	v_mul_f32_e32 v13, v21, v13
	v_fmac_f32_e32 v13, v19, v12
	v_fmac_f32_e32 v13, v20, v14
	v_fmac_f32_e32 v9, v23, v8
	v_fmac_f32_e32 v13, v18, v15
	v_fmac_f32_e32 v9, v24, v10
	v_fmac_f32_e32 v5, v27, v4
	v_add_f32_e32 v12, v34, v13
	v_fmac_f32_e32 v9, v22, v11
	v_fmac_f32_e32 v5, v28, v6
	v_fmac_f32_e32 v1, v30, v0
	v_add_f32_e32 v8, v12, v9
	v_fmac_f32_e32 v5, v26, v7
	v_fmac_f32_e32 v1, v31, v2
	v_add_f32_e32 v4, v8, v5
	v_fmac_f32_e32 v1, v29, v3
	v_add_f32_e32 v0, v4, v1
	v_min_f32_e32 v1, 0, v0
	v_mul_f32_e64 v0, |v0|, s59
	v_exp_f32_e32 v0, v0
	s_nop 0
	v_add_f32_e32 v0, 1.0, v0
	v_cmp_gt_f32_e32 vcc, s83, v0
	s_nop 1
	v_cndmask_b32_e64 v2, 0, 32, vcc
	v_ldexp_f32 v0, v0, v2
	v_log_f32_e32 v0, v0
	s_nop 0
	v_mul_f32_e32 v2, 0x3f317217, v0
	v_fma_f32 v2, v0, s87, -v2
	v_fmac_f32_e32 v2, 0x3377d1cf, v0
	v_fmac_f32_e32 v2, 0x3f317217, v0
	v_cmp_lt_f32_e64 s[38:39], |v0|, s73
	s_nop 1
	v_cndmask_b32_e64 v0, v0, v2, s[38:39]
	v_cndmask_b32_e32 v2, 0, v145, vcc
	v_sub_f32_e32 v0, v0, v2
	v_sub_f32_e32 v0, v1, v0
	v_fmamk_f32 v247, v0, 0x3d800000, v246
	global_load_dwordx4 v[0:3], v67, s[98:99] offset:3792
	global_load_dwordx4 v[4:7], v67, s[98:99] offset:3776
	global_load_dwordx4 v[8:11], v67, s[98:99] offset:3760
	global_load_dwordx4 v[12:15], v67, s[98:99] offset:3744
	s_waitcnt vmcnt(7)
	v_mul_f32_e32 v71, v33, v71
	s_waitcnt vmcnt(6)
	v_mul_f32_e32 v75, v32, v75
	s_waitcnt vmcnt(5)
	v_mul_f32_e32 v79, v25, v79
	s_waitcnt vmcnt(4)
	v_mul_f32_e32 v83, v21, v83
	v_fmac_f32_e32 v83, v19, v82
	v_fmac_f32_e32 v83, v20, v84
	v_fmac_f32_e32 v79, v23, v78
	v_fmac_f32_e32 v83, v18, v85
	v_fmac_f32_e32 v79, v24, v80
	v_fmac_f32_e32 v75, v27, v74
	v_add_f32_e32 v82, v34, v83
	v_fmac_f32_e32 v79, v22, v81
	v_fmac_f32_e32 v75, v28, v76
	v_fmac_f32_e32 v71, v30, v70
	v_add_f32_e32 v78, v82, v79
	v_fmac_f32_e32 v75, v26, v77
	v_fmac_f32_e32 v71, v31, v72
	v_add_f32_e32 v74, v78, v75
	v_fmac_f32_e32 v71, v29, v73
	v_add_f32_e32 v70, v74, v71
	v_min_f32_e32 v71, 0, v70
	v_mul_f32_e64 v70, |v70|, s59
	v_exp_f32_e32 v70, v70
	s_nop 0
	v_add_f32_e32 v70, 1.0, v70
	v_cmp_gt_f32_e32 vcc, s83, v70
	s_nop 1
	v_cndmask_b32_e64 v72, 0, 32, vcc
	v_ldexp_f32 v70, v70, v72
	v_log_f32_e32 v70, v70
	s_nop 0
	v_mul_f32_e32 v72, 0x3f317217, v70
	v_fma_f32 v72, v70, s87, -v72
	v_fmac_f32_e32 v72, 0x3377d1cf, v70
	v_fmac_f32_e32 v72, 0x3f317217, v70
	v_cmp_lt_f32_e64 s[38:39], |v70|, s73
	s_nop 1
	v_cndmask_b32_e64 v70, v70, v72, s[38:39]
	v_cndmask_b32_e32 v72, 0, v145, vcc
	v_sub_f32_e32 v70, v70, v72
	v_sub_f32_e32 v70, v71, v70
	v_fmamk_f32 v248, v70, 0x3d800000, v247
	global_load_dwordx4 v[70:73], v67, s[98:99] offset:3920
	global_load_dwordx4 v[74:77], v67, s[98:99] offset:3904
	global_load_dwordx4 v[78:81], v67, s[98:99] offset:3888
	global_load_dwordx4 v[82:85], v67, s[98:99] offset:3872
	s_waitcnt vmcnt(7)
; DI float logsig_fast(float z) { return fminf(z, 0.f) - __logf(1.0f + __expf(-fabsf(z))); }
; DI void p2_unit(int chunk, const Params& p, LAS unsigned char* lds) {
;     ...
;       for (int j2 = 0; j2 < 32; ++j2) { const f32x4* ar = (const f32x4*)(aux + (size_t)(tok0 + t0u + j2) * 32 + 8);
;           float z = bgc;
; #pragma unroll
;           for (int r4 = 0; r4 < 4; ++r4) { const f32x4 a = ar[r4]; z += a.x * w2c[4 * r4] + a.y * w2c[4 * r4 + 1] + a.z * w2c[4 * r4 + 2] + a.w * w2c[4 * r4 + 3]; }
;           bc += logsig_fast(z) * (1.0f / 16.0f); lc[j2] = bc; }
;       if (half == 0) tots[col] = bc;
;       __syncthreads();
	v_mul_f32_e32 v1, v33, v1
	s_waitcnt vmcnt(6)
	v_mul_f32_e32 v5, v32, v5
	s_waitcnt vmcnt(5)
	v_mul_f32_e32 v9, v25, v9
	s_waitcnt vmcnt(4)
	v_mul_f32_e32 v13, v21, v13
	v_fmac_f32_e32 v13, v19, v12
	v_fmac_f32_e32 v13, v20, v14
	v_fmac_f32_e32 v9, v23, v8
	v_fmac_f32_e32 v13, v18, v15
	v_fmac_f32_e32 v9, v24, v10
	v_fmac_f32_e32 v5, v27, v4
	v_add_f32_e32 v12, v34, v13
	v_fmac_f32_e32 v9, v22, v11
	v_fmac_f32_e32 v5, v28, v6
	v_fmac_f32_e32 v1, v30, v0
	v_add_f32_e32 v8, v12, v9
	v_fmac_f32_e32 v5, v26, v7
	v_fmac_f32_e32 v1, v31, v2
	v_add_f32_e32 v4, v8, v5
	v_fmac_f32_e32 v1, v29, v3
	v_add_f32_e32 v0, v4, v1
	v_min_f32_e32 v1, 0, v0
	v_mul_f32_e64 v0, |v0|, s59
	v_exp_f32_e32 v0, v0
	s_nop 0
	v_add_f32_e32 v0, 1.0, v0
	v_cmp_gt_f32_e32 vcc, s83, v0
	s_nop 1
	v_cndmask_b32_e64 v2, 0, 32, vcc
	v_ldexp_f32 v0, v0, v2
	v_log_f32_e32 v0, v0
	s_nop 0
	v_mul_f32_e32 v2, 0x3f317217, v0
	v_fma_f32 v2, v0, s87, -v2
	v_fmac_f32_e32 v2, 0x3377d1cf, v0
	v_fmac_f32_e32 v2, 0x3f317217, v0
	v_cmp_lt_f32_e64 s[38:39], |v0|, s73
	s_nop 1
	v_cndmask_b32_e64 v0, v0, v2, s[38:39]
	v_cndmask_b32_e32 v2, 0, v145, vcc
	v_sub_f32_e32 v0, v0, v2
	v_sub_f32_e32 v0, v1, v0
	v_fmamk_f32 v249, v0, 0x3d800000, v248
	global_load_dwordx4 v[0:3], v67, s[98:99] offset:4048
	global_load_dwordx4 v[4:7], v67, s[98:99] offset:4032
	global_load_dwordx4 v[8:11], v67, s[98:99] offset:4016
	global_load_dwordx4 v[12:15], v67, s[98:99] offset:4000
	s_waitcnt vmcnt(7)
	v_mul_f32_e32 v71, v33, v71
	s_waitcnt vmcnt(6)
	v_mul_f32_e32 v75, v32, v75
	s_waitcnt vmcnt(5)
	v_mul_f32_e32 v79, v25, v79
	s_waitcnt vmcnt(4)
	v_mul_f32_e32 v83, v21, v83
	v_fmac_f32_e32 v83, v19, v82
	v_fmac_f32_e32 v83, v20, v84
	v_fmac_f32_e32 v79, v23, v78
	v_fmac_f32_e32 v83, v18, v85
	v_fmac_f32_e32 v79, v24, v80
	v_fmac_f32_e32 v75, v27, v74
	v_add_f32_e32 v82, v34, v83
	v_fmac_f32_e32 v79, v22, v81
	v_fmac_f32_e32 v75, v28, v76
	v_fmac_f32_e32 v71, v30, v70
	v_add_f32_e32 v78, v82, v79
	v_fmac_f32_e32 v75, v26, v77
	v_fmac_f32_e32 v71, v31, v72
	v_add_f32_e32 v74, v78, v75
	v_fmac_f32_e32 v71, v29, v73
	v_add_f32_e32 v70, v74, v71
	v_min_f32_e32 v71, 0, v70
	v_mul_f32_e64 v70, |v70|, s59
	v_exp_f32_e32 v70, v70
	s_nop 0
	v_add_f32_e32 v70, 1.0, v70
	v_cmp_gt_f32_e32 vcc, s83, v70
	s_nop 1
	v_cndmask_b32_e64 v72, 0, 32, vcc
	v_ldexp_f32 v70, v70, v72
	v_log_f32_e32 v70, v70
	s_nop 0
	v_mul_f32_e32 v72, 0x3f317217, v70
	v_fma_f32 v72, v70, s87, -v72
	v_fmac_f32_e32 v72, 0x3377d1cf, v70
	v_fmac_f32_e32 v72, 0x3f317217, v70
	v_cmp_lt_f32_e64 s[38:39], |v70|, s73
	s_nop 1
	v_cndmask_b32_e64 v70, v70, v72, s[38:39]
	v_cndmask_b32_e32 v72, 0, v145, vcc
	v_sub_f32_e32 v70, v70, v72
	v_sub_f32_e32 v70, v71, v70
	v_fmamk_f32 v250, v70, 0x3d800000, v249
	s_movk_i32 s0, 0xff
	s_waitcnt vmcnt(3)
	v_mul_f32_e32 v1, v33, v1
	s_waitcnt vmcnt(2)
	v_mul_f32_e32 v5, v32, v5
	s_waitcnt vmcnt(1)
	v_mul_f32_e32 v9, v25, v9
	s_waitcnt vmcnt(0)
	v_mul_f32_e32 v13, v21, v13
	v_fmac_f32_e32 v13, v19, v12
	v_fmac_f32_e32 v13, v20, v14
	v_fmac_f32_e32 v9, v23, v8
	v_fmac_f32_e32 v13, v18, v15
	v_fmac_f32_e32 v9, v24, v10
	v_fmac_f32_e32 v5, v27, v4
	v_add_f32_e32 v12, v34, v13
	v_fmac_f32_e32 v9, v22, v11
	v_fmac_f32_e32 v5, v28, v6
	v_fmac_f32_e32 v1, v30, v0
	v_add_f32_e32 v8, v12, v9
	v_fmac_f32_e32 v5, v26, v7
	v_fmac_f32_e32 v1, v31, v2
	v_add_f32_e32 v4, v8, v5
	v_fmac_f32_e32 v1, v29, v3
	v_add_f32_e32 v0, v4, v1
	v_min_f32_e32 v1, 0, v0
	v_mul_f32_e64 v0, |v0|, s59
	v_exp_f32_e32 v0, v0
	s_nop 0
	v_add_f32_e32 v0, 1.0, v0
	v_cmp_gt_f32_e32 vcc, s83, v0
	s_nop 1
	v_cndmask_b32_e64 v2, 0, 32, vcc
	v_ldexp_f32 v0, v0, v2
	v_log_f32_e32 v0, v0
	s_nop 0
	v_mul_f32_e32 v2, 0x3f317217, v0
	v_fma_f32 v2, v0, s87, -v2
	v_fmac_f32_e32 v2, 0x3377d1cf, v0
	v_fmac_f32_e32 v2, 0x3f317217, v0
	v_cmp_lt_f32_e64 s[38:39], |v0|, s73
	s_nop 1
	v_cndmask_b32_e64 v0, v0, v2, s[38:39]
	v_cndmask_b32_e32 v2, 0, v145, vcc
	v_sub_f32_e32 v0, v0, v2
	v_sub_f32_e32 v0, v1, v0
	v_cmp_lt_u32_e32 vcc, s0, v146
	s_movk_i32 s0, 0x100
	v_fmamk_f32 v251, v0, 0x3d800000, v250
	v_cmp_gt_u32_e64 s[38:39], s0, v146
	v_lshl_add_u32 v0, v219, 2, 0
	s_and_saveexec_b64 s[20:21], s[38:39]
	v_add_u32_e32 v1, 0x1d400, v0
	ds_write_b32 v1, v251
	s_or_b64 exec, exec, s[20:21]
	v_mov_b32_e32 v252, 0
	s_waitcnt lgkmcnt(0)
	s_barrier
; DI float bf2f(bf16_t u) { return __uint_as_float(((unsigned)u) << 16); }
; DI bf16_t f2bf(float f) { return (bf16_t)(pk2(f, 0.f) & 0xffffu); }
; DI void p2_unit(int chunk, const Params& p, LAS unsigned char* lds) {
;     ...
;       const float offs = half ? tots[col] : 0.f;
; #pragma unroll
;       for (int j2 = 0; j2 < 32; ++j2) { const float bcl = (offs + lc[j2]) * LOG2E;
;           const float qd = bf2f(qv32[j2]) * 0.125f * __builtin_amdgcn_exp2f(bcl), kd = bf2f(kv32[j2]) * __builtin_amdgcn_exp2f(-bcl);
;           const bf16_t kdb = f2bf(kd);
;           pq[(size_t)j2 * NPROJ] = f2bf(qd); pk[(size_t)j2 * NPROJ] = kdb; kdT[(t0 + j2) * KD_PITCH + col] = kdb; }
	s_and_saveexec_b64 s[20:21], vcc
	v_add_u32_e32 v0, 0x1d400, v0
	ds_read_b32 v252, v0
	s_or_b64 exec, exec, s[20:21]
	s_mov_b64 s[0:1], 0xc00
	v_lshl_add_u64 v[50:51], v[16:17], 0, s[0:1]
	s_mov_b64 s[0:1], 0xe00
	v_lshl_add_u64 v[134:135], v[16:17], 0, s[0:1]
	s_mov_b64 s[0:1], 0x2600
	v_lshl_add_u64 v[130:131], v[16:17], 0, s[0:1]
	s_mov_b64 s[0:1], 0x2800
	v_lshl_add_u64 v[132:133], v[16:17], 0, s[0:1]
	s_mov_b64 s[0:1], 0x4000
	v_lshl_add_u64 v[126:127], v[16:17], 0, s[0:1]
	s_mov_b64 s[0:1], 0x4200
	v_lshl_add_u64 v[128:129], v[16:17], 0, s[0:1]
	s_mov_b64 s[0:1], 0x5a00
	v_lshl_add_u64 v[122:123], v[16:17], 0, s[0:1]
	s_mov_b64 s[0:1], 0x5c00
	v_lshl_add_u64 v[124:125], v[16:17], 0, s[0:1]
	s_mov_b64 s[0:1], 0x7400
	v_lshl_add_u64 v[118:119], v[16:17], 0, s[0:1]
	s_mov_b64 s[0:1], 0x7600
	v_lshl_add_u64 v[120:121], v[16:17], 0, s[0:1]
	s_mov_b64 s[0:1], 0x8e00
	v_lshl_add_u64 v[114:115], v[16:17], 0, s[0:1]
	s_mov_b64 s[0:1], 0x9000
	v_lshl_add_u64 v[116:117], v[16:17], 0, s[0:1]
	s_mov_b64 s[0:1], 0xa800
	v_lshl_add_u64 v[110:111], v[16:17], 0, s[0:1]
	s_mov_b64 s[0:1], 0xaa00
	v_lshl_add_u64 v[112:113], v[16:17], 0, s[0:1]
	s_mov_b64 s[0:1], 0xc200
	v_lshl_add_u64 v[106:107], v[16:17], 0, s[0:1]
	s_mov_b64 s[0:1], 0xc400
	v_lshl_add_u64 v[108:109], v[16:17], 0, s[0:1]
	s_mov_b64 s[0:1], 0xdc00
	v_lshl_add_u64 v[102:103], v[16:17], 0, s[0:1]
	s_mov_b64 s[0:1], 0xde00
	v_lshl_add_u64 v[104:105], v[16:17], 0, s[0:1]
	s_mov_b64 s[0:1], 0xf600
	v_lshl_add_u64 v[98:99], v[16:17], 0, s[0:1]
	s_mov_b64 s[0:1], 0xf800
	v_lshl_add_u64 v[100:101], v[16:17], 0, s[0:1]
	s_mov_b64 s[0:1], 0x11000
	v_lshl_add_u64 v[94:95], v[16:17], 0, s[0:1]
	s_mov_b64 s[0:1], 0x11200
	v_lshl_add_u64 v[96:97], v[16:17], 0, s[0:1]
	s_mov_b64 s[0:1], 0x12a00
	v_lshl_add_u64 v[90:91], v[16:17], 0, s[0:1]
	s_mov_b64 s[0:1], 0x12c00
	v_lshl_add_u64 v[92:93], v[16:17], 0, s[0:1]
	s_mov_b64 s[0:1], 0x14400
	v_lshl_add_u64 v[86:87], v[16:17], 0, s[0:1]
	s_mov_b64 s[0:1], 0x14600
	v_lshl_add_u64 v[88:89], v[16:17], 0, s[0:1]
	s_mov_b64 s[0:1], 0x15e00
	v_lshl_add_u64 v[82:83], v[16:17], 0, s[0:1]
	s_mov_b64 s[0:1], 0x16000
	v_lshl_add_u64 v[84:85], v[16:17], 0, s[0:1]
	s_mov_b64 s[0:1], 0x17800
	v_lshl_add_u64 v[78:79], v[16:17], 0, s[0:1]
	s_mov_b64 s[0:1], 0x17a00
	v_lshl_add_u64 v[80:81], v[16:17], 0, s[0:1]
	s_mov_b64 s[0:1], 0x19200
	v_lshl_add_u64 v[74:75], v[16:17], 0, s[0:1]
	s_mov_b64 s[0:1], 0x19400
	v_lshl_add_u64 v[76:77], v[16:17], 0, s[0:1]
	s_mov_b64 s[0:1], 0x1ac00
	v_lshl_add_u64 v[70:71], v[16:17], 0, s[0:1]
	s_mov_b64 s[0:1], 0x1ae00
	v_lshl_add_u64 v[72:73], v[16:17], 0, s[0:1]
	s_mov_b64 s[0:1], 0x1c600
	v_lshl_add_u64 v[60:61], v[16:17], 0, s[0:1]
	s_mov_b64 s[0:1], 0x1c800
	v_lshl_add_u64 v[62:63], v[16:17], 0, s[0:1]
	s_mov_b64 s[0:1], 0x1e000
	v_lshl_add_u64 v[56:57], v[16:17], 0, s[0:1]
	s_mov_b64 s[0:1], 0x1e200
	v_lshl_add_u64 v[58:59], v[16:17], 0, s[0:1]
	s_mov_b64 s[0:1], 0x1fa00
	v_lshl_add_u64 v[52:53], v[16:17], 0, s[0:1]
	s_mov_b64 s[0:1], 0x1fc00
	v_lshl_add_u64 v[54:55], v[16:17], 0, s[0:1]
	s_mov_b64 s[0:1], 0x21400
	v_lshl_add_u64 v[46:47], v[16:17], 0, s[0:1]
	s_mov_b64 s[0:1], 0x21600
	v_lshl_add_u64 v[48:49], v[16:17], 0, s[0:1]
	s_mov_b64 s[0:1], 0x22e00
	v_lshl_add_u64 v[42:43], v[16:17], 0, s[0:1]
	s_mov_b64 s[0:1], 0x23000
	v_lshl_add_u64 v[44:45], v[16:17], 0, s[0:1]
	s_mov_b64 s[0:1], 0x24800
	v_lshl_add_u64 v[38:39], v[16:17], 0, s[0:1]
	s_mov_b64 s[0:1], 0x24a00
	v_lshl_add_u64 v[40:41], v[16:17], 0, s[0:1]
	s_mov_b64 s[0:1], 0x26200
	v_lshl_add_u64 v[34:35], v[16:17], 0, s[0:1]
	s_mov_b64 s[0:1], 0x26400
	v_lshl_add_u64 v[36:37], v[16:17], 0, s[0:1]
	s_mov_b64 s[0:1], 0x27c00
	v_lshl_add_u64 v[30:31], v[16:17], 0, s[0:1]
	s_mov_b64 s[0:1], 0x27e00
	v_lshl_add_u64 v[32:33], v[16:17], 0, s[0:1]
	s_mov_b64 s[0:1], 0x29600
	v_lshl_add_u64 v[26:27], v[16:17], 0, s[0:1]
	s_mov_b64 s[0:1], 0x29800
	v_lshl_add_u64 v[28:29], v[16:17], 0, s[0:1]
	s_mov_b64 s[0:1], 0x2b000
	v_lshl_add_u64 v[22:23], v[16:17], 0, s[0:1]
	s_mov_b64 s[0:1], 0x2b200
	v_lshl_add_u64 v[24:25], v[16:17], 0, s[0:1]
	s_mov_b64 s[0:1], 0x2ca00
	v_lshl_add_u64 v[18:19], v[16:17], 0, s[0:1]
	s_mov_b64 s[0:1], 0x2cc00
	v_lshl_add_u64 v[20:21], v[16:17], 0, s[0:1]
	s_mov_b64 s[0:1], 0x2e400
	v_lshl_add_u64 v[12:13], v[16:17], 0, s[0:1]
	s_mov_b64 s[0:1], 0x2e600
	v_lshl_add_u64 v[14:15], v[16:17], 0, s[0:1]
	s_mov_b64 s[0:1], 0x2fe00
	v_lshl_add_u64 v[8:9], v[16:17], 0, s[0:1]
	s_mov_b64 s[0:1], 0x30000
	v_lshl_add_u64 v[10:11], v[16:17], 0, s[0:1]
	s_mov_b64 s[0:1], 0x31800
	v_lshl_add_u64 v[4:5], v[16:17], 0, s[0:1]
	s_mov_b64 s[0:1], 0x31a00
	v_lshl_add_u64 v[6:7], v[16:17], 0, s[0:1]
	s_mov_b64 s[0:1], 0x33200
	v_lshl_add_u64 v[0:1], v[16:17], 0, s[0:1]
	s_mov_b64 s[0:1], 0x33400
	v_lshl_add_u64 v[2:3], v[16:17], 0, s[0:1]
	s_waitcnt lgkmcnt(0)
; DI float bf2f(bf16_t u) { return __uint_as_float(((unsigned)u) << 16); }
; DI bf16_t f2bf(float f) { return (bf16_t)(pk2(f, 0.f) & 0xffffu); }
; DI void p2_unit(int chunk, const Params& p, LAS unsigned char* lds) {
;     ...
; #pragma unroll
;       for (int j2 = 0; j2 < 32; ++j2) { const float bcl = (offs + lc[j2]) * LOG2E;
;           const float qd = bf2f(qv32[j2]) * 0.125f * __builtin_amdgcn_exp2f(bcl), kd = bf2f(kv32[j2]) * __builtin_amdgcn_exp2f(-bcl);
;           const bf16_t kdb = f2bf(kd);
;           pq[(size_t)j2 * NPROJ] = f2bf(qd); pk[(size_t)j2 * NPROJ] = kdb; kdT[(t0 + j2) * KD_PITCH + col] = kdb; }
	v_add_f32_e32 v17, v220, v252
	s_add_i32 s0, 0, 0x12000
	v_mul_f32_e32 v17, 0x3fb8aa3b, v17
	v_lshl_add_u32 v16, v219, 1, s0
	v_exp_f32_e32 v219, v17
	v_exp_f32_e64 v17, -v17
	v_lshlrev_b32_e32 v218, 16, v218
	v_mul_f32_e32 v218, 0x3e000000, v218
	v_lshlrev_b32_e32 v217, 16, v217
	v_mul_f32_e32 v218, v218, v219
	v_mul_f32_e32 v17, v17, v217
	v_cvt_pk_bf16_f32 v17, v17, s0
	v_cvt_pk_bf16_f32 v217, v218, s0
	global_store_short v[50:51], v217, off
	global_store_short v[134:135], v17, off
	v_mad_u64_u32 v[50:51], s[0:1], v204, s88, v[16:17]
	ds_write_b16 v50, v17
	v_add_f32_e32 v17, v221, v252
	v_mul_f32_e32 v17, 0x3fb8aa3b, v17
	v_exp_f32_e32 v134, v17
	v_exp_f32_e64 v17, -v17
	v_lshlrev_b32_e32 v51, 16, v216
	v_mul_f32_e32 v51, 0x3e000000, v51
	v_mul_f32_e32 v51, v51, v134
	v_lshlrev_b32_e32 v134, 16, v215
	v_mul_f32_e32 v17, v17, v134
	v_cvt_pk_bf16_f32 v17, v17, s0
	v_cvt_pk_bf16_f32 v51, v51, s0
	global_store_short v[130:131], v51, off
	global_store_short v[132:133], v17, off
	ds_write_b16 v50, v17 offset:576
	v_add_f32_e32 v17, v222, v252
	v_mul_f32_e32 v17, 0x3fb8aa3b, v17
	v_exp_f32_e32 v130, v17
	v_exp_f32_e64 v17, -v17
	v_lshlrev_b32_e32 v51, 16, v214
	v_mul_f32_e32 v51, 0x3e000000, v51
	v_mul_f32_e32 v51, v51, v130
	v_lshlrev_b32_e32 v130, 16, v212
	v_mul_f32_e32 v17, v17, v130
	v_cvt_pk_bf16_f32 v17, v17, s0
	v_cvt_pk_bf16_f32 v51, v51, s0
	global_store_short v[126:127], v51, off
	global_store_short v[128:129], v17, off
	ds_write_b16 v50, v17 offset:1152
	v_add_f32_e32 v17, v223, v252
	v_mul_f32_e32 v17, 0x3fb8aa3b, v17
	v_exp_f32_e32 v126, v17
	v_exp_f32_e64 v17, -v17
	v_lshlrev_b32_e32 v51, 16, v213
	v_mul_f32_e32 v51, 0x3e000000, v51
	v_mul_f32_e32 v51, v51, v126
	v_lshlrev_b32_e32 v126, 16, v211
	v_mul_f32_e32 v17, v17, v126
	v_cvt_pk_bf16_f32 v17, v17, s0
	v_cvt_pk_bf16_f32 v51, v51, s0
	global_store_short v[122:123], v51, off
	global_store_short v[124:125], v17, off
	ds_write_b16 v50, v17 offset:1728
	v_add_f32_e32 v17, v224, v252
	v_mul_f32_e32 v17, 0x3fb8aa3b, v17
	v_exp_f32_e32 v122, v17
	v_exp_f32_e64 v17, -v17
	v_lshlrev_b32_e32 v51, 16, v210
	v_mul_f32_e32 v51, 0x3e000000, v51
	v_mul_f32_e32 v51, v51, v122
	v_lshlrev_b32_e32 v122, 16, v209
	v_mul_f32_e32 v17, v17, v122
	v_cvt_pk_bf16_f32 v17, v17, s0
	v_cvt_pk_bf16_f32 v51, v51, s0
	global_store_short v[118:119], v51, off
	global_store_short v[120:121], v17, off
	ds_write_b16 v50, v17 offset:2304
	v_add_f32_e32 v17, v225, v252
	v_mul_f32_e32 v17, 0x3fb8aa3b, v17
	v_exp_f32_e32 v118, v17
	v_exp_f32_e64 v17, -v17
	v_lshlrev_b32_e32 v51, 16, v207
	v_mul_f32_e32 v51, 0x3e000000, v51
	v_mul_f32_e32 v51, v51, v118
	v_lshlrev_b32_e32 v118, 16, v205
	v_mul_f32_e32 v17, v17, v118
	v_cvt_pk_bf16_f32 v17, v17, s0
	v_cvt_pk_bf16_f32 v51, v51, s0
	global_store_short v[114:115], v51, off
	global_store_short v[116:117], v17, off
	ds_write_b16 v50, v17 offset:2880
	v_add_f32_e32 v17, v226, v252
	v_mul_f32_e32 v17, 0x3fb8aa3b, v17
	v_exp_f32_e32 v114, v17
	v_exp_f32_e64 v17, -v17
	v_lshlrev_b32_e32 v51, 16, v203
	v_mul_f32_e32 v51, 0x3e000000, v51
	v_mul_f32_e32 v51, v51, v114
	v_lshlrev_b32_e32 v114, 16, v201
	v_mul_f32_e32 v17, v17, v114
	v_cvt_pk_bf16_f32 v17, v17, s0
	v_cvt_pk_bf16_f32 v51, v51, s0
	global_store_short v[110:111], v51, off
	global_store_short v[112:113], v17, off
	ds_write_b16 v50, v17 offset:3456
	v_add_f32_e32 v17, v227, v252
	v_mul_f32_e32 v17, 0x3fb8aa3b, v17
	v_exp_f32_e32 v110, v17
	v_exp_f32_e64 v17, -v17
	v_lshlrev_b32_e32 v51, 16, v202
	v_mul_f32_e32 v51, 0x3e000000, v51
	v_mul_f32_e32 v51, v51, v110
	v_lshlrev_b32_e32 v110, 16, v200
	v_mul_f32_e32 v17, v17, v110
	v_cvt_pk_bf16_f32 v17, v17, s0
	v_cvt_pk_bf16_f32 v51, v51, s0
	global_store_short v[106:107], v51, off
	global_store_short v[108:109], v17, off
	ds_write_b16 v50, v17 offset:4032
	v_add_f32_e32 v17, v228, v252
	v_mul_f32_e32 v17, 0x3fb8aa3b, v17
	v_exp_f32_e32 v106, v17
	v_exp_f32_e64 v17, -v17
	v_lshlrev_b32_e32 v51, 16, v199
	v_mul_f32_e32 v51, 0x3e000000, v51
	v_mul_f32_e32 v51, v51, v106
	v_lshlrev_b32_e32 v106, 16, v198
	v_mul_f32_e32 v17, v17, v106
	v_cvt_pk_bf16_f32 v17, v17, s0
	v_cvt_pk_bf16_f32 v51, v51, s0
	global_store_short v[102:103], v51, off
	global_store_short v[104:105], v17, off
	ds_write_b16 v50, v17 offset:4608
	v_add_f32_e32 v17, v229, v252
	v_mul_f32_e32 v17, 0x3fb8aa3b, v17
	v_exp_f32_e32 v102, v17
	v_exp_f32_e64 v17, -v17
	v_lshlrev_b32_e32 v51, 16, v197
	v_mul_f32_e32 v51, 0x3e000000, v51
	v_mul_f32_e32 v51, v51, v102
	v_lshlrev_b32_e32 v102, 16, v196
	v_mul_f32_e32 v17, v17, v102
	v_cvt_pk_bf16_f32 v17, v17, s0
	v_cvt_pk_bf16_f32 v51, v51, s0
	global_store_short v[98:99], v51, off
	global_store_short v[100:101], v17, off
	ds_write_b16 v50, v17 offset:5184
	v_add_f32_e32 v17, v230, v252
	v_mul_f32_e32 v17, 0x3fb8aa3b, v17
	v_exp_f32_e32 v98, v17
	v_exp_f32_e64 v17, -v17
	v_lshlrev_b32_e32 v51, 16, v195
	v_mul_f32_e32 v51, 0x3e000000, v51
	v_mul_f32_e32 v51, v51, v98
	v_lshlrev_b32_e32 v98, 16, v193
	v_mul_f32_e32 v17, v17, v98
	v_cvt_pk_bf16_f32 v17, v17, s0
	v_cvt_pk_bf16_f32 v51, v51, s0
	global_store_short v[94:95], v51, off
	global_store_short v[96:97], v17, off
	ds_write_b16 v50, v17 offset:5760
	v_add_f32_e32 v17, v231, v252
	v_mul_f32_e32 v17, 0x3fb8aa3b, v17
	v_exp_f32_e32 v94, v17
	v_exp_f32_e64 v17, -v17
	v_lshlrev_b32_e32 v51, 16, v194
	v_mul_f32_e32 v51, 0x3e000000, v51
	v_mul_f32_e32 v51, v51, v94
	v_lshlrev_b32_e32 v94, 16, v192
	v_mul_f32_e32 v17, v17, v94
	v_cvt_pk_bf16_f32 v17, v17, s0
	v_cvt_pk_bf16_f32 v51, v51, s0
	global_store_short v[90:91], v51, off
	global_store_short v[92:93], v17, off
	ds_write_b16 v50, v17 offset:6336
	v_add_f32_e32 v17, v232, v252
; DI float bf2f(bf16_t u) { return __uint_as_float(((unsigned)u) << 16); }
; DI bf16_t f2bf(float f) { return (bf16_t)(pk2(f, 0.f) & 0xffffu); }
; DI void p2_unit(int chunk, const Params& p, LAS unsigned char* lds) {
;     ...
; #pragma unroll
;       for (int j2 = 0; j2 < 32; ++j2) { const float bcl = (offs + lc[j2]) * LOG2E;
;           const float qd = bf2f(qv32[j2]) * 0.125f * __builtin_amdgcn_exp2f(bcl), kd = bf2f(kv32[j2]) * __builtin_amdgcn_exp2f(-bcl);
;           const bf16_t kdb = f2bf(kd);
;           pq[(size_t)j2 * NPROJ] = f2bf(qd); pk[(size_t)j2 * NPROJ] = kdb; kdT[(t0 + j2) * KD_PITCH + col] = kdb; }
	v_mul_f32_e32 v17, 0x3fb8aa3b, v17
	v_exp_f32_e32 v90, v17
	v_exp_f32_e64 v17, -v17
	v_lshlrev_b32_e32 v51, 16, v191
	v_mul_f32_e32 v51, 0x3e000000, v51
	v_mul_f32_e32 v51, v51, v90
	v_lshlrev_b32_e32 v90, 16, v190
	v_mul_f32_e32 v17, v17, v90
	v_cvt_pk_bf16_f32 v17, v17, s0
	v_cvt_pk_bf16_f32 v51, v51, s0
	global_store_short v[86:87], v51, off
	global_store_short v[88:89], v17, off
	ds_write_b16 v50, v17 offset:6912
	v_add_f32_e32 v17, v233, v252
	v_mul_f32_e32 v17, 0x3fb8aa3b, v17
	v_exp_f32_e32 v86, v17
	v_exp_f32_e64 v17, -v17
	v_lshlrev_b32_e32 v51, 16, v189
	v_mul_f32_e32 v51, 0x3e000000, v51
	v_mul_f32_e32 v51, v51, v86
	v_lshlrev_b32_e32 v86, 16, v188
	v_mul_f32_e32 v17, v17, v86
	v_cvt_pk_bf16_f32 v17, v17, s0
	v_cvt_pk_bf16_f32 v51, v51, s0
	global_store_short v[82:83], v51, off
	global_store_short v[84:85], v17, off
	ds_write_b16 v50, v17 offset:7488
	v_add_f32_e32 v17, v234, v252
	v_mul_f32_e32 v17, 0x3fb8aa3b, v17
	v_exp_f32_e32 v82, v17
	v_exp_f32_e64 v17, -v17
	v_lshlrev_b32_e32 v51, 16, v187
	v_mul_f32_e32 v51, 0x3e000000, v51
	v_mul_f32_e32 v51, v51, v82
	v_lshlrev_b32_e32 v82, 16, v185
	v_mul_f32_e32 v17, v17, v82
	v_cvt_pk_bf16_f32 v17, v17, s0
	v_cvt_pk_bf16_f32 v51, v51, s0
	global_store_short v[78:79], v51, off
	global_store_short v[80:81], v17, off
	ds_write_b16 v50, v17 offset:8064
	v_add_f32_e32 v17, v235, v252
	v_mul_f32_e32 v17, 0x3fb8aa3b, v17
	v_exp_f32_e32 v78, v17
	v_exp_f32_e64 v17, -v17
	v_lshlrev_b32_e32 v51, 16, v186
	v_mul_f32_e32 v51, 0x3e000000, v51
	v_mul_f32_e32 v51, v51, v78
	v_lshlrev_b32_e32 v78, 16, v184
	v_mul_f32_e32 v17, v17, v78
	v_cvt_pk_bf16_f32 v17, v17, s0
	v_cvt_pk_bf16_f32 v51, v51, s0
	global_store_short v[74:75], v51, off
	global_store_short v[76:77], v17, off
	ds_write_b16 v50, v17 offset:8640
	v_add_f32_e32 v17, v236, v252
	v_mul_f32_e32 v17, 0x3fb8aa3b, v17
	v_exp_f32_e32 v74, v17
	v_exp_f32_e64 v17, -v17
	v_lshlrev_b32_e32 v51, 16, v183
	v_mul_f32_e32 v51, 0x3e000000, v51
	v_mul_f32_e32 v51, v51, v74
	v_lshlrev_b32_e32 v74, 16, v182
	v_mul_f32_e32 v17, v17, v74
	v_cvt_pk_bf16_f32 v17, v17, s0
	v_cvt_pk_bf16_f32 v51, v51, s0
	global_store_short v[70:71], v51, off
	global_store_short v[72:73], v17, off
	ds_write_b16 v50, v17 offset:9216
	v_add_f32_e32 v17, v237, v252
	v_mul_f32_e32 v17, 0x3fb8aa3b, v17
	v_exp_f32_e32 v70, v17
	v_exp_f32_e64 v17, -v17
	v_lshlrev_b32_e32 v51, 16, v181
	v_mul_f32_e32 v51, 0x3e000000, v51
	v_mul_f32_e32 v51, v51, v70
	v_lshlrev_b32_e32 v70, 16, v180
	v_mul_f32_e32 v17, v17, v70
	v_cvt_pk_bf16_f32 v17, v17, s0
	v_cvt_pk_bf16_f32 v51, v51, s0
	global_store_short v[60:61], v51, off
	global_store_short v[62:63], v17, off
	ds_write_b16 v50, v17 offset:9792
	v_add_f32_e32 v17, v238, v252
	v_mul_f32_e32 v17, 0x3fb8aa3b, v17
	v_exp_f32_e32 v60, v17
	v_exp_f32_e64 v17, -v17
	v_lshlrev_b32_e32 v51, 16, v179
	v_mul_f32_e32 v51, 0x3e000000, v51
	v_mul_f32_e32 v51, v51, v60
	v_lshlrev_b32_e32 v60, 16, v177
	v_mul_f32_e32 v17, v17, v60
	v_cvt_pk_bf16_f32 v17, v17, s0
	v_cvt_pk_bf16_f32 v51, v51, s0
	global_store_short v[56:57], v51, off
	global_store_short v[58:59], v17, off
	ds_write_b16 v50, v17 offset:10368
	v_add_f32_e32 v17, v239, v252
	v_mul_f32_e32 v17, 0x3fb8aa3b, v17
	v_exp_f32_e32 v56, v17
	v_exp_f32_e64 v17, -v17
	v_lshlrev_b32_e32 v51, 16, v178
	v_mul_f32_e32 v51, 0x3e000000, v51
	v_mul_f32_e32 v51, v51, v56
	v_lshlrev_b32_e32 v56, 16, v176
	v_mul_f32_e32 v17, v17, v56
	v_cvt_pk_bf16_f32 v17, v17, s0
	v_cvt_pk_bf16_f32 v51, v51, s0
	global_store_short v[52:53], v51, off
	global_store_short v[54:55], v17, off
	ds_write_b16 v50, v17 offset:10944
	v_add_f32_e32 v17, v240, v252
	v_mul_f32_e32 v17, 0x3fb8aa3b, v17
	v_exp_f32_e32 v52, v17
	v_exp_f32_e64 v17, -v17
	v_lshlrev_b32_e32 v51, 16, v175
	v_mul_f32_e32 v51, 0x3e000000, v51
	v_mul_f32_e32 v51, v51, v52
	v_lshlrev_b32_e32 v52, 16, v174
	v_mul_f32_e32 v17, v17, v52
	v_cvt_pk_bf16_f32 v17, v17, s0
	v_cvt_pk_bf16_f32 v51, v51, s0
	global_store_short v[46:47], v51, off
	global_store_short v[48:49], v17, off
	ds_write_b16 v50, v17 offset:11520
	v_add_f32_e32 v17, v241, v252
	v_mul_f32_e32 v17, 0x3fb8aa3b, v17
	v_exp_f32_e32 v47, v17
	v_exp_f32_e64 v17, -v17
	v_lshlrev_b32_e32 v46, 16, v173
	v_mul_f32_e32 v46, 0x3e000000, v46
	v_mul_f32_e32 v46, v46, v47
	v_lshlrev_b32_e32 v47, 16, v172
	v_mul_f32_e32 v17, v17, v47
	v_cvt_pk_bf16_f32 v17, v17, s0
	v_cvt_pk_bf16_f32 v46, v46, s0
	global_store_short v[42:43], v46, off
	global_store_short v[44:45], v17, off
	ds_write_b16 v50, v17 offset:12096
	v_add_f32_e32 v17, v242, v252
	v_mul_f32_e32 v17, 0x3fb8aa3b, v17
	v_exp_f32_e32 v43, v17
	v_exp_f32_e64 v17, -v17
; DI float bf2f(bf16_t u) { return __uint_as_float(((unsigned)u) << 16); }
; DI bf16_t f2bf(float f) { return (bf16_t)(pk2(f, 0.f) & 0xffffu); }
; DI void p2_unit(int chunk, const Params& p, LAS unsigned char* lds) {
;     ...
; #pragma unroll
;       for (int j2 = 0; j2 < 32; ++j2) { const float bcl = (offs + lc[j2]) * LOG2E;
;           const float qd = bf2f(qv32[j2]) * 0.125f * __builtin_amdgcn_exp2f(bcl), kd = bf2f(kv32[j2]) * __builtin_amdgcn_exp2f(-bcl);
;           const bf16_t kdb = f2bf(kd);
;           pq[(size_t)j2 * NPROJ] = f2bf(qd); pk[(size_t)j2 * NPROJ] = kdb; kdT[(t0 + j2) * KD_PITCH + col] = kdb; }
;       if (half) { const float dec = __builtin_amdgcn_exp2f((offs + bc) * LOG2E); decs[col] = dec; ((float*)(ws + WS_DECAY))[(size_t)(b * 128 + n) * 256 + col] = dec; }
	v_lshlrev_b32_e32 v42, 16, v171
	v_mul_f32_e32 v42, 0x3e000000, v42
	v_mul_f32_e32 v42, v42, v43
	v_lshlrev_b32_e32 v43, 16, v170
	v_mul_f32_e32 v17, v17, v43
	v_cvt_pk_bf16_f32 v17, v17, s0
	v_cvt_pk_bf16_f32 v42, v42, s0
	global_store_short v[38:39], v42, off
	global_store_short v[40:41], v17, off
	ds_write_b16 v50, v17 offset:12672
	v_add_f32_e32 v17, v243, v252
	v_mul_f32_e32 v17, 0x3fb8aa3b, v17
	v_exp_f32_e32 v39, v17
	v_exp_f32_e64 v17, -v17
	v_lshlrev_b32_e32 v38, 16, v169
	v_mul_f32_e32 v38, 0x3e000000, v38
	v_mul_f32_e32 v38, v38, v39
	v_lshlrev_b32_e32 v39, 16, v168
	v_mul_f32_e32 v17, v17, v39
	v_cvt_pk_bf16_f32 v17, v17, s0
	v_cvt_pk_bf16_f32 v38, v38, s0
	global_store_short v[34:35], v38, off
	global_store_short v[36:37], v17, off
	ds_write_b16 v50, v17 offset:13248
	v_add_f32_e32 v17, v244, v252
	v_mul_f32_e32 v17, 0x3fb8aa3b, v17
	v_exp_f32_e32 v35, v17
	v_exp_f32_e64 v17, -v17
	v_lshlrev_b32_e32 v34, 16, v167
	v_mul_f32_e32 v34, 0x3e000000, v34
	v_mul_f32_e32 v34, v34, v35
	v_lshlrev_b32_e32 v35, 16, v166
	v_mul_f32_e32 v17, v17, v35
	v_cvt_pk_bf16_f32 v17, v17, s0
	v_cvt_pk_bf16_f32 v34, v34, s0
	global_store_short v[30:31], v34, off
	global_store_short v[32:33], v17, off
	ds_write_b16 v50, v17 offset:13824
	v_add_f32_e32 v17, v245, v252
	v_mul_f32_e32 v17, 0x3fb8aa3b, v17
	v_exp_f32_e32 v31, v17
	v_exp_f32_e64 v17, -v17
	v_lshlrev_b32_e32 v30, 16, v161
	v_mul_f32_e32 v30, 0x3e000000, v30
	v_mul_f32_e32 v30, v30, v31
	v_lshlrev_b32_e32 v31, 16, v160
	v_mul_f32_e32 v17, v17, v31
	v_cvt_pk_bf16_f32 v17, v17, s0
	v_cvt_pk_bf16_f32 v30, v30, s0
	global_store_short v[26:27], v30, off
	global_store_short v[28:29], v17, off
	ds_write_b16 v50, v17 offset:14400
	v_add_f32_e32 v17, v246, v252
	v_mul_f32_e32 v17, 0x3fb8aa3b, v17
	v_exp_f32_e32 v27, v17
	v_exp_f32_e64 v17, -v17
	v_lshlrev_b32_e32 v26, 16, v159
	v_mul_f32_e32 v26, 0x3e000000, v26
	v_mul_f32_e32 v26, v26, v27
	v_lshlrev_b32_e32 v27, 16, v158
	v_mul_f32_e32 v17, v17, v27
	v_cvt_pk_bf16_f32 v17, v17, s0
	v_cvt_pk_bf16_f32 v26, v26, s0
	global_store_short v[22:23], v26, off
	global_store_short v[24:25], v17, off
	ds_write_b16 v50, v17 offset:14976
	v_add_f32_e32 v17, v247, v252
	v_mul_f32_e32 v17, 0x3fb8aa3b, v17
	v_exp_f32_e32 v23, v17
	v_exp_f32_e64 v17, -v17
	v_lshlrev_b32_e32 v22, 16, v157
	v_mul_f32_e32 v22, 0x3e000000, v22
	v_mul_f32_e32 v22, v22, v23
	v_lshlrev_b32_e32 v23, 16, v156
	v_mul_f32_e32 v17, v17, v23
	v_cvt_pk_bf16_f32 v17, v17, s0
	v_cvt_pk_bf16_f32 v22, v22, s0
	global_store_short v[18:19], v22, off
	global_store_short v[20:21], v17, off
	ds_write_b16 v50, v17 offset:15552
	v_add_f32_e32 v17, v248, v252
	v_mul_f32_e32 v17, 0x3fb8aa3b, v17
	v_exp_f32_e32 v19, v17
	v_exp_f32_e64 v17, -v17
	v_lshlrev_b32_e32 v18, 16, v155
	v_mul_f32_e32 v18, 0x3e000000, v18
	v_mul_f32_e32 v18, v18, v19
	v_lshlrev_b32_e32 v19, 16, v154
	v_mul_f32_e32 v17, v17, v19
	v_cvt_pk_bf16_f32 v18, v18, s0
	v_cvt_pk_bf16_f32 v17, v17, s0
	global_store_short v[12:13], v18, off
	global_store_short v[14:15], v17, off
	v_add_f32_e32 v12, v249, v252
	v_mul_f32_e32 v12, 0x3fb8aa3b, v12
	v_exp_f32_e32 v14, v12
	v_exp_f32_e64 v12, -v12
	v_lshlrev_b32_e32 v13, 16, v153
	v_mul_f32_e32 v13, 0x3e000000, v13
	v_mul_f32_e32 v13, v13, v14
	v_lshlrev_b32_e32 v14, 16, v152
	v_mul_f32_e32 v12, v12, v14
	v_cvt_pk_bf16_f32 v13, v13, s0
	ds_write_b16 v50, v17 offset:16128
	v_cvt_pk_bf16_f32 v12, v12, s0
	global_store_short v[8:9], v13, off
	global_store_short v[10:11], v12, off
	v_add_f32_e32 v8, v250, v252
	v_mul_f32_e32 v8, 0x3fb8aa3b, v8
	v_exp_f32_e32 v10, v8
	v_exp_f32_e64 v8, -v8
	v_lshlrev_b32_e32 v9, 16, v151
	v_mul_f32_e32 v9, 0x3e000000, v9
	v_mul_f32_e32 v9, v9, v10
	v_lshlrev_b32_e32 v10, 16, v150
	v_mul_f32_e32 v8, v8, v10
	v_cvt_pk_bf16_f32 v9, v9, s0
	ds_write_b16 v50, v12 offset:16704
	v_cvt_pk_bf16_f32 v8, v8, s0
	global_store_short v[4:5], v9, off
	global_store_short v[6:7], v8, off
	v_add_f32_e32 v4, v251, v252
	v_mul_f32_e32 v5, 0x3fb8aa3b, v4
	v_lshlrev_b32_e32 v4, 16, v149
	v_mul_f32_e32 v6, 0x3e000000, v4
	v_exp_f32_e32 v4, v5
	v_exp_f32_e64 v5, -v5
	v_lshlrev_b32_e32 v7, 16, v148
	ds_write_b16 v50, v8 offset:17280
	v_mul_f32_e32 v6, v6, v4
	v_mul_f32_e32 v5, v5, v7
	v_cvt_pk_bf16_f32 v6, v6, s0
	v_cvt_pk_bf16_f32 v5, v5, s0
	global_store_short v[0:1], v6, off
	global_store_short v[2:3], v5, off
	v_or_b32_e32 v0, 31, v69
	v_mad_u64_u32 v[0:1], s[0:1], v0, s88, v[16:17]
	ds_write_b16 v0, v5
	s_and_saveexec_b64 s[20:21], vcc
	s_cbranch_execz .LBB0_347
	v_add_u32_e32 v0, 0, v66
	v_add_u32_e32 v0, 0x1d000, v0
	ds_write_b32 v0, v4
	global_store_dword v66, v4, s[64:65]
	s_branch .LBB0_347

; #define FX_LOAD(T) do { const bf16_t* rp = proj + (rowbase + 128 * (T) + krow) * NPROJ + h * 64 + chunk * 8; \
;         kreg[0] = *(const u32x4*)(rp + C_FK); kreg[1] = *(const u32x4*)(rp + C_FK + 32); vreg[0] = *(const u32x4*)(rp + C_FV); vreg[1] = *(const u32x4*)(rp + C_FV + 32); \
;         if (tid < 128) ckreg = FX_C2(128 * (T) + tid); } while (0)
; DI void fox_unit(int bh, int qb, const Params& p, LAS unsigned char* lds, float thr2) {
;     ...
;     for (int T = T_hi; T >= T_lo; --T) {
;         const int buf = (T_hi - T) & 1;
;         if (T > T_lo) FX_LOAD(T - 1);
.LBB0_522:
	s_cmp_gt_i32 s18, s36
	s_cselect_b64 s[84:85], -1, 0
	s_cmp_le_i32 s18, s36
	s_cselect_b64 s[78:79], -1, 0
	s_and_b64 vcc, exec, s[78:79]
	s_cbranch_vccnz .LBB0_526
	s_ashr_i32 s23, s22, 31
	v_lshl_add_u64 v[34:35], v[170:171], 0, s[22:23]
	v_mad_u64_u32 v[36:37], s[8:9], v34, s5, v[172:173]
	v_mad_i32_i24 v37, v35, s5, v37
	global_load_dwordx4 v[98:101], v[36:37], off offset:1024
	global_load_dwordx4 v[102:105], v[36:37], off offset:1088
	global_load_dwordx4 v[106:109], v[36:37], off offset:2048
	global_load_dwordx4 v[110:113], v[36:37], off offset:2112
	s_and_saveexec_b64 s[42:43], s[38:39]
	s_cbranch_execz .LBB0_525
	v_add_u32_e32 v34, s22, v212
	v_ashrrev_i32_e32 v35, 31, v34
	v_lshl_add_u64 v[36:37], v[34:35], 2, s[28:29]
	global_load_dword v236, v[36:37], off
	v_ashrrev_i32_e32 v34, 6, v34
	v_lshl_add_u32 v34, v34, 2, 0
	v_add_u32_e32 v34, 0x12400, v34
	ds_read_b32 v237, v34

; DI unsigned pk2(float lo, float hi) { f32x2 v = {lo, hi}; bf16x2_t b = __builtin_convertvector(v, bf16x2_t); return __builtin_bit_cast(unsigned, b); }
; #define FX_STORE(buf) do { _Pragma("unroll") for (int i_ = 0; i_ < 2; ++i_) { *(LAS u32x4*)(Kb + (buf) * 9216 + krow * FX_KP + (chunk + 4 * i_) * 8) = kreg[i_]; \
;             *(LAS u32x4*)(Vb + (buf) * 9216 + krow * FX_KP + (chunk + 4 * i_) * 8) = vreg[i_]; } \
;         if (tid < 128) ckb[(buf) * 128 + tid] = ckreg; } while (0)
; template <bool PEND> DI void fx_softmax(f32x16& p0, f32x16& p1, f32x16& q0, f32x16& q1, bf16x8 (&pw)[4], f32x16 (&o)[2], float& m, float& l, float& cqm, float cq, LAS float* al,
;                                         int k0, int qw0, int qrow, int r32, int hi) {
;     ...
;     for (int i = 0; i < 16; ++i) { p0[i] = __builtin_amdgcn_exp2f(p0[i]); p1[i] = __builtin_amdgcn_exp2f(p1[i]); }
;     { const f32x16 t = p0 + p1; const f32x4 u4 = (f32x4){t[0], t[1], t[2], t[3]} + (f32x4){t[4], t[5], t[6], t[7]} + (f32x4){t[8], t[9], t[10], t[11]} + (f32x4){t[12], t[13], t[14], t[15]};
;       l += (u4.x + u4.y) + (u4.z + u4.w); }
; #pragma unroll
;     for (int s2 = 0; s2 < 2; ++s2) { u32x4 w0, w1;
; #pragma unroll
;         for (int e = 0; e < 4; ++e) { w0[e] = pk2(p0[8 * s2 + 2 * e], p0[8 * s2 + 2 * e + 1]); w1[e] = pk2(p1[8 * s2 + 2 * e], p1[8 * s2 + 2 * e + 1]); }
;         pw[s2] = __builtin_bit_cast(bf16x8, w0); pw[2 + s2] = __builtin_bit_cast(bf16x8, w1); }
; }
; DI void fx_pv(f32x16 (&o)[2], const bf16x8 (&pw)[4], const bf16x8 (&vfr)[4][2]) {
; #pragma unroll
;     for (int st = 0; st < 4; ++st)
; #pragma unroll
;         for (int db = 0; db < 2; ++db) o[db] = __builtin_amdgcn_mfma_f32_32x32x16_bf16(pw[st], vfr[st][db], o[db], 0, 0, 0);
; DI void fox_unit(int bh, int qb, const Params& p, LAS unsigned char* lds, float thr2) {
;     ...
;         if (T > T_lo) FX_STORE(buf ^ 1);
.LBB0_557:
	v_exp_f32_e32 v132, v34
	v_exp_f32_e32 v50, v50
	v_exp_f32_e32 v133, v35
	v_exp_f32_e32 v51, v51
	v_exp_f32_e32 v134, v36
	v_exp_f32_e32 v52, v52
	v_exp_f32_e32 v135, v37
	v_exp_f32_e32 v53, v53
	v_exp_f32_e32 v38, v38
	v_exp_f32_e32 v54, v54
	v_exp_f32_e32 v39, v39
	v_exp_f32_e32 v55, v55
	v_exp_f32_e32 v136, v40
	v_exp_f32_e32 v56, v56
	v_exp_f32_e32 v137, v41
	v_exp_f32_e32 v57, v57
	v_exp_f32_e32 v138, v42
	v_exp_f32_e32 v58, v58
	v_exp_f32_e32 v139, v43
	v_exp_f32_e32 v140, v44
	v_exp_f32_e32 v60, v60
	v_exp_f32_e32 v141, v45
	v_exp_f32_e32 v61, v61
	v_exp_f32_e32 v59, v59
	v_exp_f32_e32 v46, v46
	v_exp_f32_e32 v62, v62
	v_exp_f32_e32 v47, v47
	v_exp_f32_e32 v63, v63
	v_exp_f32_e32 v142, v48
	v_exp_f32_e32 v64, v64
	v_exp_f32_e32 v143, v49
	v_exp_f32_e32 v65, v65
	v_pk_add_f32 v[44:45], v[54:55], v[38:39]
	v_pk_add_f32 v[48:49], v[50:51], v[132:133]
	v_pk_add_f32 v[144:145], v[56:57], v[136:137]
	v_pk_add_f32 v[146:147], v[52:53], v[134:135]
	v_pk_add_f32 v[40:41], v[60:61], v[140:141]
	v_pk_add_f32 v[42:43], v[58:59], v[138:139]
	v_pk_add_f32 v[144:145], v[146:147], v[144:145]
	v_pk_add_f32 v[44:45], v[48:49], v[44:45]
	v_pk_add_f32 v[34:35], v[62:63], v[46:47]
	v_pk_add_f32 v[36:37], v[64:65], v[142:143]
	v_pk_add_f32 v[42:43], v[42:43], v[44:45]
	v_pk_add_f32 v[40:41], v[40:41], v[144:145]
	v_pk_add_f32 v[34:35], v[34:35], v[42:43]
	v_pk_add_f32 v[36:37], v[36:37], v[40:41]
	v_cvt_pk_bf16_f32 v38, v38, v39
	v_pk_mov_b32 v[40:41], v[34:35], v[36:37] op_sel:[1,0]
	v_mov_b32_e32 v35, v37
	v_pk_add_f32 v[34:35], v[40:41], v[34:35]
	v_cvt_pk_bf16_f32 v36, v132, v133
	v_add_f32_e32 v34, v34, v35
	v_add_f32_e32 v34, v131, v34
	v_cvt_pk_bf16_f32 v40, v50, v51
	v_cvt_pk_bf16_f32 v37, v134, v135
	v_cvt_pk_bf16_f32 v41, v52, v53
	v_cvt_pk_bf16_f32 v42, v54, v55
	v_cvt_pk_bf16_f32 v39, v136, v137
	v_cvt_pk_bf16_f32 v43, v56, v57
	v_cvt_pk_bf16_f32 v44, v138, v139
	v_cvt_pk_bf16_f32 v48, v58, v59
	v_cvt_pk_bf16_f32 v45, v140, v141
	v_cvt_pk_bf16_f32 v49, v60, v61
	v_cvt_pk_bf16_f32 v46, v46, v47
	v_cvt_pk_bf16_f32 v50, v62, v63
	v_cvt_pk_bf16_f32 v47, v142, v143
	v_cvt_pk_bf16_f32 v51, v64, v65
	v_mfma_f32_32x32x16_bf16 v[18:33], v[36:39], v[70:73], v[18:33]
	v_mfma_f32_32x32x16_bf16 v[2:17], v[36:39], v[78:81], v[2:17]
	v_mfma_f32_32x32x16_bf16 v[18:33], v[44:47], v[74:77], v[18:33]
	v_mfma_f32_32x32x16_bf16 v[2:17], v[44:47], v[82:85], v[2:17]
	v_mfma_f32_32x32x16_bf16 v[18:33], v[40:43], v[86:89], v[18:33]
	v_mfma_f32_32x32x16_bf16 v[2:17], v[40:43], v[90:93], v[2:17]
	v_mfma_f32_32x32x16_bf16 v[2:17], v[48:51], v[94:97], v[2:17]
	v_mfma_f32_32x32x16_bf16 v[18:33], v[48:51], v[66:69], v[18:33]
	s_and_b64 vcc, exec, s[78:79]
	s_cbranch_vccz .Lfox_fast_tail
	s_nop 10
	v_mov_b64_e32 v[96:97], v[16:17]
	v_mov_b64_e32 v[94:95], v[14:15]
	v_mov_b64_e32 v[92:93], v[12:13]
	v_mov_b64_e32 v[90:91], v[10:11]
	v_mov_b64_e32 v[88:89], v[8:9]
	v_mov_b64_e32 v[86:87], v[6:7]
	v_mov_b64_e32 v[84:85], v[4:5]
	v_mov_b64_e32 v[80:81], v[32:33]
	v_mov_b64_e32 v[82:83], v[2:3]
	v_mov_b64_e32 v[78:79], v[30:31]
	v_mov_b64_e32 v[76:77], v[28:29]
	v_mov_b64_e32 v[74:75], v[26:27]
	v_mov_b64_e32 v[72:73], v[24:25]
	v_mov_b64_e32 v[70:71], v[22:23]
	v_mov_b64_e32 v[68:69], v[20:21]
	v_mov_b64_e32 v[66:67], v[18:19]
	s_andn2_b64 vcc, exec, s[84:85]
	s_cbranch_vccnz .LBB0_561
.LBB0_558:
	s_mul_i32 s8, s23, 0x4800
	v_add_u32_e32 v2, s8, v218
	s_waitcnt vmcnt(3)
	ds_write_b128 v2, v[98:101]
	s_waitcnt vmcnt(1)
	ds_write_b128 v2, v[106:109] offset:36864
	ds_write_b128 v2, v[102:105] offset:64
	s_waitcnt vmcnt(0)
	ds_write_b128 v2, v[110:113] offset:36928
	s_and_saveexec_b64 s[42:43], s[38:39]
	v_lshl_add_u32 v2, s23, 9, v219
	s_waitcnt lgkmcnt(4)
	v_add_f32_e32 v215, v237, v236
	ds_write_b32 v2, v215
	s_or_b64 exec, exec, s[42:43]

; #define FX_STORE(buf) do { _Pragma("unroll") for (int i_ = 0; i_ < 2; ++i_) { *(LAS u32x4*)(Kb + (buf) * 9216 + krow * FX_KP + (chunk + 4 * i_) * 8) = kreg[i_]; \
;             *(LAS u32x4*)(Vb + (buf) * 9216 + krow * FX_KP + (chunk + 4 * i_) * 8) = vreg[i_]; } \
;         if (tid < 128) ckb[(buf) * 128 + tid] = ckreg; } while (0)
; DI void fox_unit(int bh, int qb, const Params& p, LAS unsigned char* lds, float thr2) {
;     ...
;         if (T > T_lo) FX_STORE(buf ^ 1);
;         __syncthreads();
.Lfox_fast_tail:
	s_mul_i32 s8, s23, 0x4800
	v_add_u32_e32 v238, s8, v218
	s_waitcnt vmcnt(3)
	ds_write_b128 v238, v[98:101]
	s_waitcnt vmcnt(1)
	ds_write_b128 v238, v[106:109] offset:36864
	ds_write_b128 v238, v[102:105] offset:64
	s_waitcnt vmcnt(0)
	ds_write_b128 v238, v[110:113] offset:36928
	s_and_saveexec_b64 s[42:43], s[38:39]
	v_lshl_add_u32 v238, s23, 9, v219
	s_waitcnt lgkmcnt(4)
	v_add_f32_e32 v215, v237, v236
	ds_write_b32 v238, v215
	s_or_b64 exec, exec, s[42:43]
	s_add_i32 s18, s18, -1
	s_add_i32 s37, s37, -2
	s_addk_i32 s22, 0xff80
	s_waitcnt lgkmcnt(0)
	s_barrier
	v_mov_b32_e32 v227, v34
	v_mov_b32_e32 v226, v174
	v_mov_b32_e32 v228, v175
	s_branch .LBB0_522

; DI unsigned xb_ld(unsigned* p)              { return __hip_atomic_load(p, __ATOMIC_RELAXED, __HIP_MEMORY_SCOPE_AGENT); }
; DI unsigned xb_add(unsigned* p, unsigned v) { return __hip_atomic_fetch_add(p, v, __ATOMIC_RELAXED, __HIP_MEMORY_SCOPE_AGENT); }
; #define XB_SPIN(cond, bar) do { unsigned _sp = 0; while (cond) { __builtin_amdgcn_s_sleep(1); \
;     if ((++_sp & 255u) == 0u) { if (xb_ld(&(bar)[XB_TMO])) break; if (_sp > XB_SPIN_CAP) { atomicAdd(&(bar)[XB_TMO], 1u); break; } } } } while (0)
; DI void xcd_barrier(const XcdBarrier& b) {
;     asm volatile("s_waitcnt vmcnt(0)" ::: "memory");
;     __syncthreads();
;     if (threadIdx.x == 0) {
;         unsigned* bar = b.bar;
;         __builtin_amdgcn_s_waitcnt(0);
;         unsigned nloc = b.st[0], nx = b.st[1];
;         if (nloc == 0u) { xcd_barrier_complete(bar, b.x, nloc, nx); b.st[0] = nloc; b.st[1] = nx; }
;         const unsigned old = xb_add(&bar[XB_XSUB(b.x)], 1u);
;         const unsigned gen = old / nloc;
;         if (old + 1u == (gen + 1u) * nloc) {
;             __builtin_amdgcn_fence(__ATOMIC_RELEASE, "agent");
;             asm volatile("s_waitcnt vmcnt(0)" ::: "memory");
;             const unsigned og = xb_add(&bar[XB_TOP], 1u);
;             const unsigned tg = og / nx;
;             if (og + 1u == (tg + 1u) * nx) xb_add(&bar[XB_TOPGEN], 1u);
;             else XB_SPIN(xb_ld(&bar[XB_TOPGEN]) == tg, bar);
;             __builtin_amdgcn_fence(__ATOMIC_ACQUIRE, "agent");
;             xb_add(&bar[XB_XGEN(b.x)], 1u);
;             asm volatile("s_waitcnt vmcnt(0)" ::: "memory");
;         } else {
;             XB_SPIN(xb_ld(&bar[XB_XGEN(b.x)]) == gen, bar);
;             __builtin_amdgcn_fence(__ATOMIC_ACQUIRE, "agent");
;             asm volatile("s_waitcnt vmcnt(0)" ::: "memory");
;         }
;     }
;     __syncthreads();
.LBB0_818:
	s_waitcnt vmcnt(0)
	s_barrier
	s_mov_b64 s[0:1], exec
	v_readlane_b32 s4, v254, 16
	v_readlane_b32 s5, v254, 17
	s_and_b64 s[4:5], s[0:1], s[4:5]
	s_xor_b64 s[16:17], s[4:5], s[0:1]
	s_mov_b64 exec, s[4:5]
	s_branch .LBB0_867

; #define PG8_STAGE(bufoff, gbase, voff) do { _Pragma("unroll") for (int _i = 0; _i < 2; ++_i) \
;         __builtin_amdgcn_global_load_lds((const unsigned*)((const char*)(gbase) + (voff)[_i]), (LAS unsigned*)(lds + (bufoff) + ldsw + _i * 8192), 16, 0, 0); } while (0)
; #define PG8_LDA(dst, b, h) do { _Pragma("unroll") for (int m = 0; m < 4; ++m) _Pragma("unroll") for (int k = 0; k < 2; ++k) dst[m][k] = *(const LAS bf16x8*)(lds + PG8_SA(b, h) + aoff + m * 2048 + k * 1024); } while (0)
; #define PG8_LDB(dst, b, h) do { _Pragma("unroll") for (int n = 0; n < 2; ++n) _Pragma("unroll") for (int k = 0; k < 2; ++k) dst[n][k] = *(const LAS bf16x8*)(lds + PG8_SB(b, h) + boff + n * 2048 + k * 1024); } while (0)
; #define PG8_MMA(ai, bj, At, Bt) do { __builtin_amdgcn_s_setprio(1); _Pragma("unroll") for (int m = 0; m < 4; ++m) _Pragma("unroll") for (int n = 0; n < 2; ++n) _Pragma("unroll") for (int k = 0; k < 2; ++k) \
;         acc[ai][bj][m][n] = __builtin_amdgcn_mfma_f32_16x16x32_bf16(Bt[n][k], At[m][k], acc[ai][bj][m][n], 0, 0, 0); __builtin_amdgcn_s_setprio(0); } while (0)
; #define PG8_WAIT_V(n) asm volatile("s_waitcnt vmcnt(" #n ")" ::: "memory")
; #define PG8_WAIT_L(n) asm volatile("s_waitcnt lgkmcnt(" #n ")" ::: "memory")
; #define PG8_BAR __builtin_amdgcn_s_barrier()
; #define PG8_SCHED __builtin_amdgcn_sched_barrier(0)
; template <class GEO, class Epi>
; __device__ __forceinline__ void gemm_phase(LAS unsigned char* lds, const Gemm g, const StaticOrder& S, const Epi& E) {
;     ...
;             PG8_LDB(B0, 0, 0); PG8_LDB(B1, 0, 1); PG8_SCHED; PG8_LDA(At, 0, 0); PG8_STAGE(PG8_SA(1, 1), a1 + hstepA, voffA);
;             PG8_WAIT_V(8); PG8_WAIT_L(0); PG8_BAR; PG8_MMA(0, 0, At, B0); PG8_MMA(0, 1, At, B1); PG8_BAR; PG8_SCHED;
;             PG8_LDA(At, 0, 1); PG8_STAGE(PG8_SB(0, 0), b2, voffB); PG8_STAGE(PG8_SB(0, 1), b2 + hstepB, voffB); PG8_STAGE(PG8_SA(0, 0), a2, voffA);
;             PG8_WAIT_V(8); PG8_WAIT_L(0); PG8_BAR; PG8_MMA(1, 0, At, B0); PG8_MMA(1, 1, At, B1); PG8_BAR; PG8_SCHED;
.LBB0_1148:
	ds_read_b128 v[144:147], v151
	ds_read_b128 v[154:157], v151 offset:1024
	ds_read_b128 v[158:161], v151 offset:2048
	ds_read_b128 v[162:165], v151 offset:3072
	ds_read_b128 v[166:169], v152
	ds_read_b128 v[170:173], v152 offset:1024
	ds_read_b128 v[174:177], v152 offset:2048
	ds_read_b128 v[178:181], v152 offset:3072
	s_add_u32 s24, s22, 0xfff00080
	s_addc_u32 s25, s23, -1
	s_cmp_eq_u32 s46, 60
	s_cselect_b32 s29, s15, s25
	s_cselect_b32 s28, s42, s24
	s_cselect_b32 s25, s4, s45
	s_cselect_b32 s24, s43, s44
	v_lshl_add_u64 v[214:215], s[22:23], 0, v[136:137]
	s_add_i32 m0, s21, 0xc000
	ds_read_b128 v[182:185], v153
	ds_read_b128 v[186:189], v153 offset:1024
	ds_read_b128 v[190:193], v153 offset:2048
	ds_read_b128 v[194:197], v153 offset:3072
	ds_read_b128 v[198:201], v153 offset:4096
	ds_read_b128 v[202:205], v153 offset:5120
	ds_read_b128 v[206:209], v153 offset:6144
	ds_read_b128 v[210:213], v153 offset:7168
	global_load_lds_dwordx4 v[214:215], off
	v_lshl_add_u64 v[214:215], s[22:23], 0, v[138:139]
	s_add_i32 m0, s21, 0xe000
	s_nop 0
	global_load_lds_dwordx4 v[214:215], off
	s_waitcnt vmcnt(8)
	s_waitcnt lgkmcnt(0)
	s_barrier
	s_setprio 1
	s_waitcnt lgkmcnt(0)
	v_mfma_f32_16x16x32_bf16 v[124:127], v[144:147], v[182:185], v[124:127]
	v_mfma_f32_16x16x32_bf16 v[120:123], v[158:161], v[182:185], v[120:123]
	v_mfma_f32_16x16x32_bf16 v[108:111], v[144:147], v[190:193], v[108:111]
	v_mfma_f32_16x16x32_bf16 v[104:107], v[158:161], v[190:193], v[104:107]
	v_mfma_f32_16x16x32_bf16 v[92:95], v[144:147], v[198:201], v[92:95]
	v_mfma_f32_16x16x32_bf16 v[88:91], v[158:161], v[198:201], v[88:91]
	v_mfma_f32_16x16x32_bf16 v[76:79], v[144:147], v[206:209], v[76:79]
	v_mfma_f32_16x16x32_bf16 v[72:75], v[158:161], v[206:209], v[72:75]
	v_mfma_f32_16x16x32_bf16 v[124:127], v[154:157], v[186:189], v[124:127]
	v_mfma_f32_16x16x32_bf16 v[120:123], v[162:165], v[186:189], v[120:123]
	v_mfma_f32_16x16x32_bf16 v[108:111], v[154:157], v[194:197], v[108:111]
	v_mfma_f32_16x16x32_bf16 v[104:107], v[162:165], v[194:197], v[104:107]
	v_mfma_f32_16x16x32_bf16 v[92:95], v[154:157], v[202:205], v[92:95]
	v_mfma_f32_16x16x32_bf16 v[88:91], v[162:165], v[202:205], v[88:91]
	v_mfma_f32_16x16x32_bf16 v[76:79], v[154:157], v[210:213], v[76:79]
	v_mfma_f32_16x16x32_bf16 v[72:75], v[162:165], v[210:213], v[72:75]
	s_setprio 0
	s_setprio 1
	v_mfma_f32_16x16x32_bf16 v[116:119], v[166:169], v[182:185], v[116:119]
	v_mfma_f32_16x16x32_bf16 v[112:115], v[174:177], v[182:185], v[112:115]
	v_mfma_f32_16x16x32_bf16 v[100:103], v[166:169], v[190:193], v[100:103]
	v_mfma_f32_16x16x32_bf16 v[96:99], v[174:177], v[190:193], v[96:99]
	v_mfma_f32_16x16x32_bf16 v[84:87], v[166:169], v[198:201], v[84:87]
	v_mfma_f32_16x16x32_bf16 v[80:83], v[174:177], v[198:201], v[80:83]
	v_mfma_f32_16x16x32_bf16 v[68:71], v[166:169], v[206:209], v[68:71]
	v_mfma_f32_16x16x32_bf16 v[64:67], v[174:177], v[206:209], v[64:67]
	v_mfma_f32_16x16x32_bf16 v[116:119], v[170:173], v[186:189], v[116:119]
	v_mfma_f32_16x16x32_bf16 v[112:115], v[178:181], v[186:189], v[112:115]
	v_mfma_f32_16x16x32_bf16 v[100:103], v[170:173], v[194:197], v[100:103]
	v_mfma_f32_16x16x32_bf16 v[96:99], v[178:181], v[194:197], v[96:99]
	v_mfma_f32_16x16x32_bf16 v[84:87], v[170:173], v[202:205], v[84:87]
	v_mfma_f32_16x16x32_bf16 v[80:83], v[178:181], v[202:205], v[80:83]
	v_mfma_f32_16x16x32_bf16 v[68:71], v[170:173], v[210:213], v[68:71]
	v_mfma_f32_16x16x32_bf16 v[64:67], v[178:181], v[210:213], v[64:67]
	s_setprio 0
	s_barrier
	s_add_i32 s47, s37, s30
	v_lshl_add_u64 v[214:215], s[24:25], 0, v[130:131]
	s_mov_b32 m0, s47
	ds_read_b128 v[182:185], v153 offset:16384
	ds_read_b128 v[186:189], v153 offset:17408
	ds_read_b128 v[190:193], v153 offset:18432
	ds_read_b128 v[194:197], v153 offset:19456
	ds_read_b128 v[198:201], v153 offset:20480
	ds_read_b128 v[202:205], v153 offset:21504
	ds_read_b128 v[206:209], v153 offset:22528
	ds_read_b128 v[210:213], v153 offset:23552
	global_load_lds_dwordx4 v[214:215], off
	s_add_i32 m0, s47, 0x2000
	s_add_u32 s48, s24, 0x100000
	v_lshl_add_u64 v[216:217], s[24:25], 0, v[134:135]
	s_addc_u32 s49, s25, 0
	s_add_i32 s47, s38, s30
	global_load_lds_dwordx4 v[216:217], off
	v_lshl_add_u64 v[218:219], s[48:49], 0, v[130:131]
	s_mov_b32 m0, s47
	v_lshl_add_u64 v[220:221], s[28:29], 0, v[132:133]
	global_load_lds_dwordx4 v[218:219], off
	v_lshl_add_u64 v[218:219], s[48:49], 0, v[134:135]
	s_add_i32 m0, s47, 0x2000
	s_nop 0
	global_load_lds_dwordx4 v[218:219], off
	v_lshl_add_u64 v[218:219], s[28:29], 0, v[128:129]
	s_mov_b32 m0, s21
	s_nop 0
	global_load_lds_dwordx4 v[218:219], off
	s_mov_b32 m0, s31
	s_nop 0
	global_load_lds_dwordx4 v[220:221], off
	s_waitcnt vmcnt(8)
	s_waitcnt lgkmcnt(0)
	s_barrier
; #define PG8_STAGE(bufoff, gbase, voff) do { _Pragma("unroll") for (int _i = 0; _i < 2; ++_i) \
;         __builtin_amdgcn_global_load_lds((const unsigned*)((const char*)(gbase) + (voff)[_i]), (LAS unsigned*)(lds + (bufoff) + ldsw + _i * 8192), 16, 0, 0); } while (0)
; #define PG8_LDA(dst, b, h) do { _Pragma("unroll") for (int m = 0; m < 4; ++m) _Pragma("unroll") for (int k = 0; k < 2; ++k) dst[m][k] = *(const LAS bf16x8*)(lds + PG8_SA(b, h) + aoff + m * 2048 + k * 1024); } while (0)
; #define PG8_LDB(dst, b, h) do { _Pragma("unroll") for (int n = 0; n < 2; ++n) _Pragma("unroll") for (int k = 0; k < 2; ++k) dst[n][k] = *(const LAS bf16x8*)(lds + PG8_SB(b, h) + boff + n * 2048 + k * 1024); } while (0)
; #define PG8_MMA(ai, bj, At, Bt) do { __builtin_amdgcn_s_setprio(1); _Pragma("unroll") for (int m = 0; m < 4; ++m) _Pragma("unroll") for (int n = 0; n < 2; ++n) _Pragma("unroll") for (int k = 0; k < 2; ++k) \
;         acc[ai][bj][m][n] = __builtin_amdgcn_mfma_f32_16x16x32_bf16(Bt[n][k], At[m][k], acc[ai][bj][m][n], 0, 0, 0); __builtin_amdgcn_s_setprio(0); } while (0)
; #define PG8_WAIT_V(n) asm volatile("s_waitcnt vmcnt(" #n ")" ::: "memory")
; #define PG8_WAIT_L(n) asm volatile("s_waitcnt lgkmcnt(" #n ")" ::: "memory")
; #define PG8_BAR __builtin_amdgcn_s_barrier()
; #define PG8_SCHED __builtin_amdgcn_sched_barrier(0)
; template <class GEO, class Epi>
; __device__ __forceinline__ void gemm_phase(LAS unsigned char* lds, const Gemm g, const StaticOrder& S, const Epi& E) {
;     ...
;             PG8_WAIT_V(8); PG8_WAIT_L(0); PG8_BAR; PG8_MMA(1, 0, At, B0); PG8_MMA(1, 1, At, B1); PG8_BAR; PG8_SCHED;
;             PG8_LDB(B0, 1, 0); PG8_LDB(B1, 1, 1); PG8_SCHED; PG8_LDA(At, 1, 0); PG8_STAGE(PG8_SA(0, 1), a2 + hstepA, voffA);
;             PG8_WAIT_V(8); PG8_WAIT_L(0); PG8_BAR; PG8_MMA(0, 0, At, B0); PG8_MMA(0, 1, At, B1); PG8_BAR; PG8_SCHED;
	s_setprio 1
	s_waitcnt lgkmcnt(0)
	v_mfma_f32_16x16x32_bf16 v[60:63], v[144:147], v[182:185], v[60:63]
	v_mfma_f32_16x16x32_bf16 v[56:59], v[158:161], v[182:185], v[56:59]
	v_mfma_f32_16x16x32_bf16 v[44:47], v[144:147], v[190:193], v[44:47]
	v_mfma_f32_16x16x32_bf16 v[40:43], v[158:161], v[190:193], v[40:43]
	v_mfma_f32_16x16x32_bf16 v[28:31], v[144:147], v[198:201], v[28:31]
	v_mfma_f32_16x16x32_bf16 v[24:27], v[158:161], v[198:201], v[24:27]
	v_mfma_f32_16x16x32_bf16 v[12:15], v[144:147], v[206:209], v[12:15]
	v_mfma_f32_16x16x32_bf16 v[8:11], v[158:161], v[206:209], v[8:11]
	v_mfma_f32_16x16x32_bf16 v[60:63], v[154:157], v[186:189], v[60:63]
	v_mfma_f32_16x16x32_bf16 v[56:59], v[162:165], v[186:189], v[56:59]
	v_mfma_f32_16x16x32_bf16 v[44:47], v[154:157], v[194:197], v[44:47]
	v_mfma_f32_16x16x32_bf16 v[40:43], v[162:165], v[194:197], v[40:43]
	v_mfma_f32_16x16x32_bf16 v[28:31], v[154:157], v[202:205], v[28:31]
	v_mfma_f32_16x16x32_bf16 v[24:27], v[162:165], v[202:205], v[24:27]
	v_mfma_f32_16x16x32_bf16 v[12:15], v[154:157], v[210:213], v[12:15]
	v_mfma_f32_16x16x32_bf16 v[8:11], v[162:165], v[210:213], v[8:11]
	s_setprio 0
	s_setprio 1
	v_mfma_f32_16x16x32_bf16 v[52:55], v[166:169], v[182:185], v[52:55]
	v_mfma_f32_16x16x32_bf16 v[48:51], v[174:177], v[182:185], v[48:51]
	v_mfma_f32_16x16x32_bf16 v[36:39], v[166:169], v[190:193], v[36:39]
	v_mfma_f32_16x16x32_bf16 v[32:35], v[174:177], v[190:193], v[32:35]
	v_mfma_f32_16x16x32_bf16 v[20:23], v[166:169], v[198:201], v[20:23]
	v_mfma_f32_16x16x32_bf16 v[16:19], v[174:177], v[198:201], v[16:19]
	v_mfma_f32_16x16x32_bf16 v[4:7], v[166:169], v[206:209], v[4:7]
	v_mfma_f32_16x16x32_bf16 v[0:3], v[174:177], v[206:209], v[0:3]
	v_mfma_f32_16x16x32_bf16 v[52:55], v[170:173], v[186:189], v[52:55]
	v_mfma_f32_16x16x32_bf16 v[48:51], v[178:181], v[186:189], v[48:51]
	v_mfma_f32_16x16x32_bf16 v[36:39], v[170:173], v[194:197], v[36:39]
	v_mfma_f32_16x16x32_bf16 v[32:35], v[178:181], v[194:197], v[32:35]
	v_mfma_f32_16x16x32_bf16 v[20:23], v[170:173], v[202:205], v[20:23]
	v_mfma_f32_16x16x32_bf16 v[16:19], v[178:181], v[202:205], v[16:19]
	v_mfma_f32_16x16x32_bf16 v[4:7], v[170:173], v[210:213], v[4:7]
	v_mfma_f32_16x16x32_bf16 v[0:3], v[178:181], v[210:213], v[0:3]
	s_setprio 0
	s_barrier
	s_add_i32 s47, 0, 0x18000
	s_add_i32 s48, 0, 0x1c000
	v_add_u32_e32 v162, s47, v149
	v_add_u32_e32 v178, s48, v149
	ds_read_b128 v[144:147], v162
	ds_read_b128 v[154:157], v162 offset:1024
	ds_read_b128 v[158:161], v162 offset:2048
	ds_read_b128 v[162:165], v162 offset:3072
	ds_read_b128 v[166:169], v178
	ds_read_b128 v[170:173], v178 offset:1024
	ds_read_b128 v[174:177], v178 offset:2048
	ds_read_b128 v[178:181], v178 offset:3072
	s_add_u32 s28, s28, 0x100000
	s_addc_u32 s29, s29, 0
	s_mov_b32 m0, s33
	v_lshl_add_u64 v[222:223], s[28:29], 0, v[128:129]
	ds_read_b128 v[182:185], v153 offset:32768
	ds_read_b128 v[186:189], v153 offset:33792
	ds_read_b128 v[190:193], v153 offset:34816
	ds_read_b128 v[194:197], v153 offset:35840
	ds_read_b128 v[198:201], v153 offset:36864
	ds_read_b128 v[202:205], v153 offset:37888
	ds_read_b128 v[206:209], v153 offset:38912
	ds_read_b128 v[210:213], v153 offset:39936
	global_load_lds_dwordx4 v[222:223], off
	v_lshl_add_u64 v[222:223], s[28:29], 0, v[132:133]
	s_mov_b32 m0, s34
	s_nop 0
	global_load_lds_dwordx4 v[222:223], off
	s_waitcnt vmcnt(8)
	s_waitcnt lgkmcnt(0)
	s_barrier
	s_setprio 1
	s_waitcnt lgkmcnt(0)
	v_mfma_f32_16x16x32_bf16 v[124:127], v[144:147], v[182:185], v[124:127]
	v_mfma_f32_16x16x32_bf16 v[120:123], v[158:161], v[182:185], v[120:123]
	v_mfma_f32_16x16x32_bf16 v[108:111], v[144:147], v[190:193], v[108:111]
	v_mfma_f32_16x16x32_bf16 v[104:107], v[158:161], v[190:193], v[104:107]
	v_mfma_f32_16x16x32_bf16 v[92:95], v[144:147], v[198:201], v[92:95]
	v_mfma_f32_16x16x32_bf16 v[88:91], v[158:161], v[198:201], v[88:91]
	v_mfma_f32_16x16x32_bf16 v[76:79], v[144:147], v[206:209], v[76:79]
	v_mfma_f32_16x16x32_bf16 v[72:75], v[158:161], v[206:209], v[72:75]
	v_mfma_f32_16x16x32_bf16 v[124:127], v[154:157], v[186:189], v[124:127]
	v_mfma_f32_16x16x32_bf16 v[120:123], v[162:165], v[186:189], v[120:123]
	v_mfma_f32_16x16x32_bf16 v[108:111], v[154:157], v[194:197], v[108:111]
	v_mfma_f32_16x16x32_bf16 v[104:107], v[162:165], v[194:197], v[104:107]
	v_mfma_f32_16x16x32_bf16 v[92:95], v[154:157], v[202:205], v[92:95]
	v_mfma_f32_16x16x32_bf16 v[88:91], v[162:165], v[202:205], v[88:91]
	v_mfma_f32_16x16x32_bf16 v[76:79], v[154:157], v[210:213], v[76:79]
	v_mfma_f32_16x16x32_bf16 v[72:75], v[162:165], v[210:213], v[72:75]
	s_setprio 0
	s_setprio 1
	v_mfma_f32_16x16x32_bf16 v[116:119], v[166:169], v[182:185], v[116:119]
	v_mfma_f32_16x16x32_bf16 v[112:115], v[174:177], v[182:185], v[112:115]
	v_mfma_f32_16x16x32_bf16 v[100:103], v[166:169], v[190:193], v[100:103]
	v_mfma_f32_16x16x32_bf16 v[96:99], v[174:177], v[190:193], v[96:99]
	v_mfma_f32_16x16x32_bf16 v[84:87], v[166:169], v[198:201], v[84:87]
	v_mfma_f32_16x16x32_bf16 v[80:83], v[174:177], v[198:201], v[80:83]
	v_mfma_f32_16x16x32_bf16 v[68:71], v[166:169], v[206:209], v[68:71]
	v_mfma_f32_16x16x32_bf16 v[64:67], v[174:177], v[206:209], v[64:67]
	v_mfma_f32_16x16x32_bf16 v[116:119], v[170:173], v[186:189], v[116:119]
	v_mfma_f32_16x16x32_bf16 v[112:115], v[178:181], v[186:189], v[112:115]
	v_mfma_f32_16x16x32_bf16 v[100:103], v[170:173], v[194:197], v[100:103]
	v_mfma_f32_16x16x32_bf16 v[96:99], v[178:181], v[194:197], v[96:99]
	v_mfma_f32_16x16x32_bf16 v[84:87], v[170:173], v[202:205], v[84:87]
	v_mfma_f32_16x16x32_bf16 v[80:83], v[178:181], v[202:205], v[80:83]
	v_mfma_f32_16x16x32_bf16 v[68:71], v[170:173], v[210:213], v[68:71]
	v_mfma_f32_16x16x32_bf16 v[64:67], v[178:181], v[210:213], v[64:67]
	s_setprio 0
	s_barrier
; DI float bflo(unsigned w) { return __uint_as_float(w << 16); }
; DI float bfhi(unsigned w) { return __uint_as_float(w & 0xffff0000u); }
; #define PG8_STAGE(bufoff, gbase, voff) do { _Pragma("unroll") for (int _i = 0; _i < 2; ++_i) \
;         __builtin_amdgcn_global_load_lds((const unsigned*)((const char*)(gbase) + (voff)[_i]), (LAS unsigned*)(lds + (bufoff) + ldsw + _i * 8192), 16, 0, 0); } while (0)
; #define PG8_LDA(dst, b, h) do { _Pragma("unroll") for (int m = 0; m < 4; ++m) _Pragma("unroll") for (int k = 0; k < 2; ++k) dst[m][k] = *(const LAS bf16x8*)(lds + PG8_SA(b, h) + aoff + m * 2048 + k * 1024); } while (0)
; #define PG8_MMA(ai, bj, At, Bt) do { __builtin_amdgcn_s_setprio(1); _Pragma("unroll") for (int m = 0; m < 4; ++m) _Pragma("unroll") for (int n = 0; n < 2; ++n) _Pragma("unroll") for (int k = 0; k < 2; ++k) \
;         acc[ai][bj][m][n] = __builtin_amdgcn_mfma_f32_16x16x32_bf16(Bt[n][k], At[m][k], acc[ai][bj][m][n], 0, 0, 0); __builtin_amdgcn_s_setprio(0); } while (0)
; #define PG8_WAIT_V(n) asm volatile("s_waitcnt vmcnt(" #n ")" ::: "memory")
; #define PG8_WAIT_L(n) asm volatile("s_waitcnt lgkmcnt(" #n ")" ::: "memory")
; #define PG8_BAR __builtin_amdgcn_s_barrier()
; #define PG8_SCHED __builtin_amdgcn_sched_barrier(0)
;     DI void operator()(Acc& acc, const Unit& u, int wr, int wc, int fr, int fq, LAS unsigned char* lds) const {
;     ...
;             for (int m = 0; m < 4; ++m) { const int row = u.pm * BM + ai * HALF + wr * 64 + m * 16 + fr; const size_t off = (size_t)row * DM + col0; float ss = 0.f;
; #pragma unroll
;                 for (int bj = 0; bj < 2; ++bj) { const size_t o = off + bj * HALF;
;                     f32x4 b0, b1;
;                     if (BASE_BF16) { const u32x4 w = *(const u32x4*)((const bf16_t*)base + o); b0 = (f32x4){bflo(w.x), bfhi(w.x), bflo(w.y), bfhi(w.y)}; b1 = (f32x4){bflo(w.z), bfhi(w.z), bflo(w.w), bfhi(w.w)}; }
; template <class GEO, class Epi>
; __device__ __forceinline__ void gemm_phase(LAS unsigned char* lds, const Gemm g, const StaticOrder& S, const Epi& E) {
;     ...
;             PG8_LDA(At, 1, 1); PG8_STAGE(PG8_SB(1, 0), b3, voffB); PG8_STAGE(PG8_SB(1, 1), b3 + hstepB, voffB); PG8_STAGE(PG8_SA(1, 0), a3, voffA);
;             PG8_WAIT_V(8); PG8_WAIT_L(0); PG8_BAR; PG8_MMA(1, 0, At, B0); PG8_MMA(1, 1, At, B1); PG8_BAR; PG8_SCHED;
;         }
;         if (wr == 0) PG8_BAR;
	s_add_i32 s28, s47, s30
	v_lshl_add_u64 v[214:215], v[214:215], 0, s[8:9]
	s_mov_b32 m0, s28
	ds_read_b128 v[182:185], v153 offset:49152
	ds_read_b128 v[186:189], v153 offset:50176
	ds_read_b128 v[190:193], v153 offset:51200
	ds_read_b128 v[194:197], v153 offset:52224
	ds_read_b128 v[198:201], v153 offset:53248
	ds_read_b128 v[202:205], v153 offset:54272
	ds_read_b128 v[206:209], v153 offset:55296
	ds_read_b128 v[210:213], v153 offset:56320
	global_load_lds_dwordx4 v[214:215], off
	s_add_i32 m0, s28, 0x2000
	s_add_u32 s24, s24, 0x100080
	v_lshl_add_u64 v[214:215], v[216:217], 0, s[8:9]
	s_addc_u32 s25, s25, 0
	s_add_i32 s28, s48, s30
	global_load_lds_dwordx4 v[214:215], off
	v_lshl_add_u64 v[214:215], s[24:25], 0, v[130:131]
	s_mov_b32 m0, s28
	s_nop 0
	global_load_lds_dwordx4 v[214:215], off
	v_lshl_add_u64 v[214:215], s[24:25], 0, v[134:135]
	s_add_i32 m0, s28, 0x2000
	s_nop 0
	global_load_lds_dwordx4 v[214:215], off
	v_lshl_add_u64 v[214:215], v[218:219], 0, s[8:9]
	s_mov_b32 m0, s35
	s_nop 0
	global_load_lds_dwordx4 v[214:215], off
	v_lshl_add_u64 v[214:215], v[220:221], 0, s[8:9]
	s_mov_b32 m0, s36
	s_nop 0
	global_load_lds_dwordx4 v[214:215], off
	s_waitcnt vmcnt(8)
	s_waitcnt lgkmcnt(0)
	s_barrier
	s_setprio 1
	s_waitcnt lgkmcnt(0)
	v_mfma_f32_16x16x32_bf16 v[60:63], v[144:147], v[182:185], v[60:63]
	v_mfma_f32_16x16x32_bf16 v[56:59], v[158:161], v[182:185], v[56:59]
	v_mfma_f32_16x16x32_bf16 v[44:47], v[144:147], v[190:193], v[44:47]
	v_mfma_f32_16x16x32_bf16 v[40:43], v[158:161], v[190:193], v[40:43]
	v_mfma_f32_16x16x32_bf16 v[28:31], v[144:147], v[198:201], v[28:31]
	v_mfma_f32_16x16x32_bf16 v[24:27], v[158:161], v[198:201], v[24:27]
	v_mfma_f32_16x16x32_bf16 v[12:15], v[144:147], v[206:209], v[12:15]
	v_mfma_f32_16x16x32_bf16 v[8:11], v[158:161], v[206:209], v[8:11]
	v_mfma_f32_16x16x32_bf16 v[60:63], v[154:157], v[186:189], v[60:63]
	v_mfma_f32_16x16x32_bf16 v[56:59], v[162:165], v[186:189], v[56:59]
	v_mfma_f32_16x16x32_bf16 v[44:47], v[154:157], v[194:197], v[44:47]
	v_mfma_f32_16x16x32_bf16 v[40:43], v[162:165], v[194:197], v[40:43]
	v_mfma_f32_16x16x32_bf16 v[28:31], v[154:157], v[202:205], v[28:31]
	v_mfma_f32_16x16x32_bf16 v[24:27], v[162:165], v[202:205], v[24:27]
	v_mfma_f32_16x16x32_bf16 v[12:15], v[154:157], v[210:213], v[12:15]
	v_mfma_f32_16x16x32_bf16 v[8:11], v[162:165], v[210:213], v[8:11]
	s_setprio 0
	s_setprio 1
	v_mfma_f32_16x16x32_bf16 v[52:55], v[166:169], v[182:185], v[52:55]
	v_mfma_f32_16x16x32_bf16 v[48:51], v[174:177], v[182:185], v[48:51]
	v_mfma_f32_16x16x32_bf16 v[36:39], v[166:169], v[190:193], v[36:39]
	v_mfma_f32_16x16x32_bf16 v[32:35], v[174:177], v[190:193], v[32:35]
	v_mfma_f32_16x16x32_bf16 v[20:23], v[166:169], v[198:201], v[20:23]
	v_mfma_f32_16x16x32_bf16 v[16:19], v[174:177], v[198:201], v[16:19]
	v_mfma_f32_16x16x32_bf16 v[4:7], v[166:169], v[206:209], v[4:7]
	v_mfma_f32_16x16x32_bf16 v[0:3], v[174:177], v[206:209], v[0:3]
	v_mfma_f32_16x16x32_bf16 v[52:55], v[170:173], v[186:189], v[52:55]
	v_mfma_f32_16x16x32_bf16 v[48:51], v[178:181], v[186:189], v[48:51]
	v_mfma_f32_16x16x32_bf16 v[36:39], v[170:173], v[194:197], v[36:39]
	v_mfma_f32_16x16x32_bf16 v[32:35], v[178:181], v[194:197], v[32:35]
	v_mfma_f32_16x16x32_bf16 v[20:23], v[170:173], v[202:205], v[20:23]
	v_mfma_f32_16x16x32_bf16 v[16:19], v[178:181], v[202:205], v[16:19]
	v_mfma_f32_16x16x32_bf16 v[4:7], v[170:173], v[210:213], v[4:7]
	v_mfma_f32_16x16x32_bf16 v[0:3], v[178:181], v[210:213], v[0:3]
	s_setprio 0
	s_barrier
	s_add_i32 s46, s46, 2
	s_add_u32 s22, s22, 0x100
	s_addc_u32 s23, s23, 0
	s_add_u32 s44, s44, 0x100
	s_addc_u32 s45, s45, 0
	s_cmp_gt_u32 s46, 61
	s_cbranch_scc0 .LBB0_1148
	v_lshl_add_u32 v146, s20, 8, v148
	v_lshl_or_b32 v144, s41, 8, v150
	v_ashrrev_i32_e32 v147, 31, v146
	v_ashrrev_i32_e32 v145, 31, v144
	v_lshlrev_b64 v[154:155], 10, v[146:147]
	v_lshl_add_u64 v[158:159], v[154:155], 0, v[144:145]
	v_lshlrev_b64 v[154:155], 1, v[158:159]
	v_lshl_add_u64 v[154:155], s[26:27], 0, v[154:155]
	v_lshl_add_u64 v[158:159], v[158:159], 2, s[74:75]
	s_mov_b32 s42, 0x8000
	s_mov_b32 s43, 0
	s_mov_b32 s44, 0x40000
	s_mov_b32 s45, 0
	s_mov_b32 s46, 0x10000
	s_mov_b32 s47, 0
	s_mov_b32 s48, 0x80000
	s_mov_b32 s49, 0
	v_lshl_add_u64 v[224:225], v[154:155], 0, s[44:45]
	global_load_dwordx4 v[160:163], v[154:155], off
	global_load_dwordx4 v[164:167], v[154:155], off offset:256
	v_lshl_add_u64 v[156:157], v[154:155], 0, s[42:43]
	global_load_dwordx4 v[168:171], v[156:157], off
	global_load_dwordx4 v[172:175], v[156:157], off offset:256
	v_lshl_add_u64 v[154:155], v[156:157], 0, s[42:43]
	global_load_dwordx4 v[176:179], v[154:155], off
	global_load_dwordx4 v[180:183], v[154:155], off offset:256
	v_lshl_add_u64 v[156:157], v[154:155], 0, s[42:43]
	global_load_dwordx4 v[184:187], v[156:157], off
	global_load_dwordx4 v[188:191], v[156:157], off offset:256
	global_load_dwordx4 v[192:195], v[224:225], off
	global_load_dwordx4 v[196:199], v[224:225], off offset:256
	v_lshl_add_u64 v[156:157], v[224:225], 0, s[42:43]
	global_load_dwordx4 v[200:203], v[156:157], off
	global_load_dwordx4 v[204:207], v[156:157], off offset:256
	v_lshl_add_u64 v[154:155], v[156:157], 0, s[42:43]
	global_load_dwordx4 v[208:211], v[154:155], off
	global_load_dwordx4 v[212:215], v[154:155], off offset:256
	v_lshl_add_u64 v[156:157], v[154:155], 0, s[42:43]
	global_load_dwordx4 v[216:219], v[156:157], off
	global_load_dwordx4 v[220:223], v[156:157], off offset:256
	s_and_b64 vcc, exec, s[12:13]
	s_cbranch_vccz .LBB0_1151
	s_barrier
; DI float bflo(unsigned w) { return __uint_as_float(w << 16); }
; DI float bfhi(unsigned w) { return __uint_as_float(w & 0xffff0000u); }
;     DI void operator()(Acc& acc, const Unit& u, int wr, int wc, int fr, int fq, LAS unsigned char* lds) const {
;     ...
;             for (int m = 0; m < 4; ++m) { const int row = u.pm * BM + ai * HALF + wr * 64 + m * 16 + fr; const size_t off = (size_t)row * DM + col0; float ss = 0.f;
; #pragma unroll
;                 for (int bj = 0; bj < 2; ++bj) { const size_t o = off + bj * HALF;
;                     f32x4 b0, b1;
;                     if (BASE_BF16) { const u32x4 w = *(const u32x4*)((const bf16_t*)base + o); b0 = (f32x4){bflo(w.x), bfhi(w.x), bflo(w.y), bfhi(w.y)}; b1 = (f32x4){bflo(w.z), bfhi(w.z), bflo(w.w), bfhi(w.w)}; }
;                     else { b0 = *(const f32x4*)((const float*)base + o); b1 = *(const f32x4*)((const float*)base + o + 4); }
;                     const f32x4 v0 = b0 + acc[ai][bj][m][0], v1 = b1 + acc[ai][bj][m][1];
;                     if (OUT_F32) { __builtin_nontemporal_store(v0, (f32x4*)(out + o)); __builtin_nontemporal_store(v1, (f32x4*)(out + o + 4)); }
.LBB0_1151:
	v_lshl_add_u64 v[228:229], v[158:159], 0, s[48:49]
	s_waitcnt vmcnt(15)
	v_lshlrev_b32_e32 v230, 16, v160
	v_and_b32_e32 v231, 0xffff0000, v160
	v_lshlrev_b32_e32 v232, 16, v161
	v_and_b32_e32 v233, 0xffff0000, v161
	v_lshlrev_b32_e32 v234, 16, v162
	v_and_b32_e32 v235, 0xffff0000, v162
	v_lshlrev_b32_e32 v236, 16, v163
	v_and_b32_e32 v237, 0xffff0000, v163
	v_pk_add_f32 v[124:125], v[124:125], v[230:231]
	v_pk_add_f32 v[126:127], v[126:127], v[232:233]
	v_pk_add_f32 v[120:121], v[120:121], v[234:235]
	v_pk_add_f32 v[122:123], v[122:123], v[236:237]
	global_store_dwordx4 v[158:159], v[124:127], off nt
	global_store_dwordx4 v[158:159], v[120:123], off offset:16 nt
	s_waitcnt vmcnt(16)
	v_lshlrev_b32_e32 v238, 16, v164
	v_and_b32_e32 v239, 0xffff0000, v164
	v_lshlrev_b32_e32 v240, 16, v165
	v_and_b32_e32 v241, 0xffff0000, v165
	v_lshlrev_b32_e32 v242, 16, v166
	v_and_b32_e32 v243, 0xffff0000, v166
	v_lshlrev_b32_e32 v244, 16, v167
	v_and_b32_e32 v245, 0xffff0000, v167
	v_pk_add_f32 v[116:117], v[116:117], v[238:239]
	v_pk_add_f32 v[118:119], v[118:119], v[240:241]
	v_pk_add_f32 v[112:113], v[112:113], v[242:243]
	v_pk_add_f32 v[114:115], v[114:115], v[244:245]
	global_store_dwordx4 v[158:159], v[116:119], off offset:512 nt
	global_store_dwordx4 v[158:159], v[112:115], off offset:528 nt
	v_lshl_add_u64 v[226:227], v[158:159], 0, s[46:47]
	s_waitcnt vmcnt(17)
	v_lshlrev_b32_e32 v230, 16, v168
	v_and_b32_e32 v231, 0xffff0000, v168
	v_lshlrev_b32_e32 v232, 16, v169
	v_and_b32_e32 v233, 0xffff0000, v169
	v_lshlrev_b32_e32 v234, 16, v170
	v_and_b32_e32 v235, 0xffff0000, v170
	v_lshlrev_b32_e32 v236, 16, v171
	v_and_b32_e32 v237, 0xffff0000, v171
	v_pk_add_f32 v[108:109], v[108:109], v[230:231]
	v_pk_add_f32 v[110:111], v[110:111], v[232:233]
	v_pk_add_f32 v[104:105], v[104:105], v[234:235]
	v_pk_add_f32 v[106:107], v[106:107], v[236:237]
	global_store_dwordx4 v[226:227], v[108:111], off nt
	global_store_dwordx4 v[226:227], v[104:107], off offset:16 nt
	s_waitcnt vmcnt(18)
	v_lshlrev_b32_e32 v238, 16, v172
	v_and_b32_e32 v239, 0xffff0000, v172
	v_lshlrev_b32_e32 v240, 16, v173
	v_and_b32_e32 v241, 0xffff0000, v173
	v_lshlrev_b32_e32 v242, 16, v174
	v_and_b32_e32 v243, 0xffff0000, v174
	v_lshlrev_b32_e32 v244, 16, v175
	v_and_b32_e32 v245, 0xffff0000, v175
	v_pk_add_f32 v[100:101], v[100:101], v[238:239]
	v_pk_add_f32 v[102:103], v[102:103], v[240:241]
	v_pk_add_f32 v[96:97], v[96:97], v[242:243]
	v_pk_add_f32 v[98:99], v[98:99], v[244:245]
	global_store_dwordx4 v[226:227], v[100:103], off offset:512 nt
	global_store_dwordx4 v[226:227], v[96:99], off offset:528 nt
	v_lshl_add_u64 v[246:247], v[226:227], 0, s[46:47]
	s_waitcnt vmcnt(19)
	v_lshlrev_b32_e32 v230, 16, v176
	v_and_b32_e32 v231, 0xffff0000, v176
	v_lshlrev_b32_e32 v232, 16, v177
	v_and_b32_e32 v233, 0xffff0000, v177
	v_lshlrev_b32_e32 v234, 16, v178
	v_and_b32_e32 v235, 0xffff0000, v178
	v_lshlrev_b32_e32 v236, 16, v179
	v_and_b32_e32 v237, 0xffff0000, v179
	v_pk_add_f32 v[92:93], v[92:93], v[230:231]
	v_pk_add_f32 v[94:95], v[94:95], v[232:233]
	v_pk_add_f32 v[88:89], v[88:89], v[234:235]
	v_pk_add_f32 v[90:91], v[90:91], v[236:237]
	global_store_dwordx4 v[246:247], v[92:95], off nt
	global_store_dwordx4 v[246:247], v[88:91], off offset:16 nt
	s_waitcnt vmcnt(20)
	v_lshlrev_b32_e32 v238, 16, v180
	v_and_b32_e32 v239, 0xffff0000, v180
	v_lshlrev_b32_e32 v240, 16, v181
	v_and_b32_e32 v241, 0xffff0000, v181
	v_lshlrev_b32_e32 v242, 16, v182
	v_and_b32_e32 v243, 0xffff0000, v182
	v_lshlrev_b32_e32 v244, 16, v183
	v_and_b32_e32 v245, 0xffff0000, v183
	v_pk_add_f32 v[84:85], v[84:85], v[238:239]
	v_pk_add_f32 v[86:87], v[86:87], v[240:241]
	v_pk_add_f32 v[80:81], v[80:81], v[242:243]
	v_pk_add_f32 v[82:83], v[82:83], v[244:245]
	global_store_dwordx4 v[246:247], v[84:87], off offset:512 nt
	global_store_dwordx4 v[246:247], v[80:83], off offset:528 nt
	v_lshl_add_u64 v[226:227], v[246:247], 0, s[46:47]
	s_waitcnt vmcnt(21)
	v_lshlrev_b32_e32 v230, 16, v184
	v_and_b32_e32 v231, 0xffff0000, v184
	v_lshlrev_b32_e32 v232, 16, v185
	v_and_b32_e32 v233, 0xffff0000, v185
	v_lshlrev_b32_e32 v234, 16, v186
	v_and_b32_e32 v235, 0xffff0000, v186
	v_lshlrev_b32_e32 v236, 16, v187
	v_and_b32_e32 v237, 0xffff0000, v187
	v_pk_add_f32 v[76:77], v[76:77], v[230:231]
	v_pk_add_f32 v[78:79], v[78:79], v[232:233]
	v_pk_add_f32 v[72:73], v[72:73], v[234:235]
	v_pk_add_f32 v[74:75], v[74:75], v[236:237]
	global_store_dwordx4 v[226:227], v[76:79], off nt
	global_store_dwordx4 v[226:227], v[72:75], off offset:16 nt
	s_waitcnt vmcnt(22)
	v_lshlrev_b32_e32 v238, 16, v188
	v_and_b32_e32 v239, 0xffff0000, v188
	v_lshlrev_b32_e32 v240, 16, v189
	v_and_b32_e32 v241, 0xffff0000, v189
	v_lshlrev_b32_e32 v242, 16, v190
	v_and_b32_e32 v243, 0xffff0000, v190
	v_lshlrev_b32_e32 v244, 16, v191
	v_and_b32_e32 v245, 0xffff0000, v191
	v_pk_add_f32 v[68:69], v[68:69], v[238:239]
	v_pk_add_f32 v[70:71], v[70:71], v[240:241]
	v_pk_add_f32 v[64:65], v[64:65], v[242:243]
	v_pk_add_f32 v[66:67], v[66:67], v[244:245]
	global_store_dwordx4 v[226:227], v[68:71], off offset:512 nt
	global_store_dwordx4 v[226:227], v[64:67], off offset:528 nt
	s_waitcnt vmcnt(23)
; DI float bflo(unsigned w) { return __uint_as_float(w << 16); }
; DI float bfhi(unsigned w) { return __uint_as_float(w & 0xffff0000u); }
;     DI void operator()(Acc& acc, const Unit& u, int wr, int wc, int fr, int fq, LAS unsigned char* lds) const {
;     ...
;             for (int m = 0; m < 4; ++m) { const int row = u.pm * BM + ai * HALF + wr * 64 + m * 16 + fr; const size_t off = (size_t)row * DM + col0; float ss = 0.f;
; #pragma unroll
;                 for (int bj = 0; bj < 2; ++bj) { const size_t o = off + bj * HALF;
;                     f32x4 b0, b1;
;                     if (BASE_BF16) { const u32x4 w = *(const u32x4*)((const bf16_t*)base + o); b0 = (f32x4){bflo(w.x), bfhi(w.x), bflo(w.y), bfhi(w.y)}; b1 = (f32x4){bflo(w.z), bfhi(w.z), bflo(w.w), bfhi(w.w)}; }
;                     else { b0 = *(const f32x4*)((const float*)base + o); b1 = *(const f32x4*)((const float*)base + o + 4); }
;                     const f32x4 v0 = b0 + acc[ai][bj][m][0], v1 = b1 + acc[ai][bj][m][1];
;                     if (OUT_F32) { __builtin_nontemporal_store(v0, (f32x4*)(out + o)); __builtin_nontemporal_store(v1, (f32x4*)(out + o + 4)); }
	v_lshlrev_b32_e32 v230, 16, v192
	v_and_b32_e32 v231, 0xffff0000, v192
	v_lshlrev_b32_e32 v232, 16, v193
	v_and_b32_e32 v233, 0xffff0000, v193
	v_lshlrev_b32_e32 v234, 16, v194
	v_and_b32_e32 v235, 0xffff0000, v194
	v_lshlrev_b32_e32 v236, 16, v195
	v_and_b32_e32 v237, 0xffff0000, v195
	v_pk_add_f32 v[60:61], v[60:61], v[230:231]
	v_pk_add_f32 v[62:63], v[62:63], v[232:233]
	v_pk_add_f32 v[56:57], v[56:57], v[234:235]
	v_pk_add_f32 v[58:59], v[58:59], v[236:237]
	global_store_dwordx4 v[228:229], v[60:63], off nt
	global_store_dwordx4 v[228:229], v[56:59], off offset:16 nt
	s_waitcnt vmcnt(24)
	v_lshlrev_b32_e32 v238, 16, v196
	v_and_b32_e32 v239, 0xffff0000, v196
	v_lshlrev_b32_e32 v240, 16, v197
	v_and_b32_e32 v241, 0xffff0000, v197
	v_lshlrev_b32_e32 v242, 16, v198
	v_and_b32_e32 v243, 0xffff0000, v198
	v_lshlrev_b32_e32 v244, 16, v199
	v_and_b32_e32 v245, 0xffff0000, v199
	v_pk_add_f32 v[52:53], v[52:53], v[238:239]
	v_pk_add_f32 v[54:55], v[54:55], v[240:241]
	v_pk_add_f32 v[48:49], v[48:49], v[242:243]
	v_pk_add_f32 v[50:51], v[50:51], v[244:245]
	global_store_dwordx4 v[228:229], v[52:55], off offset:512 nt
	global_store_dwordx4 v[228:229], v[48:51], off offset:528 nt
	v_lshl_add_u64 v[226:227], v[228:229], 0, s[46:47]
	s_waitcnt vmcnt(25)
	v_lshlrev_b32_e32 v230, 16, v200
	v_and_b32_e32 v231, 0xffff0000, v200
	v_lshlrev_b32_e32 v232, 16, v201
	v_and_b32_e32 v233, 0xffff0000, v201
	v_lshlrev_b32_e32 v234, 16, v202
	v_and_b32_e32 v235, 0xffff0000, v202
	v_lshlrev_b32_e32 v236, 16, v203
	v_and_b32_e32 v237, 0xffff0000, v203
	v_pk_add_f32 v[44:45], v[44:45], v[230:231]
	v_pk_add_f32 v[46:47], v[46:47], v[232:233]
	v_pk_add_f32 v[40:41], v[40:41], v[234:235]
	v_pk_add_f32 v[42:43], v[42:43], v[236:237]
	global_store_dwordx4 v[226:227], v[44:47], off nt
	global_store_dwordx4 v[226:227], v[40:43], off offset:16 nt
	s_waitcnt vmcnt(26)
	v_lshlrev_b32_e32 v238, 16, v204
	v_and_b32_e32 v239, 0xffff0000, v204
	v_lshlrev_b32_e32 v240, 16, v205
	v_and_b32_e32 v241, 0xffff0000, v205
	v_lshlrev_b32_e32 v242, 16, v206
	v_and_b32_e32 v243, 0xffff0000, v206
	v_lshlrev_b32_e32 v244, 16, v207
	v_and_b32_e32 v245, 0xffff0000, v207
	v_pk_add_f32 v[36:37], v[36:37], v[238:239]
	v_pk_add_f32 v[38:39], v[38:39], v[240:241]
	v_pk_add_f32 v[32:33], v[32:33], v[242:243]
	v_pk_add_f32 v[34:35], v[34:35], v[244:245]
	global_store_dwordx4 v[226:227], v[36:39], off offset:512 nt
	global_store_dwordx4 v[226:227], v[32:35], off offset:528 nt
	v_lshl_add_u64 v[246:247], v[226:227], 0, s[46:47]
	s_waitcnt vmcnt(27)
	v_lshlrev_b32_e32 v230, 16, v208
	v_and_b32_e32 v231, 0xffff0000, v208
	v_lshlrev_b32_e32 v232, 16, v209
	v_and_b32_e32 v233, 0xffff0000, v209
	v_lshlrev_b32_e32 v234, 16, v210
	v_and_b32_e32 v235, 0xffff0000, v210
	v_lshlrev_b32_e32 v236, 16, v211
	v_and_b32_e32 v237, 0xffff0000, v211
	v_pk_add_f32 v[28:29], v[28:29], v[230:231]
	v_pk_add_f32 v[30:31], v[30:31], v[232:233]
	v_pk_add_f32 v[24:25], v[24:25], v[234:235]
	v_pk_add_f32 v[26:27], v[26:27], v[236:237]
	global_store_dwordx4 v[246:247], v[28:31], off nt
	global_store_dwordx4 v[246:247], v[24:27], off offset:16 nt
	s_waitcnt vmcnt(28)
	v_lshlrev_b32_e32 v238, 16, v212
	v_and_b32_e32 v239, 0xffff0000, v212
	v_lshlrev_b32_e32 v240, 16, v213
	v_and_b32_e32 v241, 0xffff0000, v213
	v_lshlrev_b32_e32 v242, 16, v214
	v_and_b32_e32 v243, 0xffff0000, v214
	v_lshlrev_b32_e32 v244, 16, v215
	v_and_b32_e32 v245, 0xffff0000, v215
	v_pk_add_f32 v[20:21], v[20:21], v[238:239]
	v_pk_add_f32 v[22:23], v[22:23], v[240:241]
	v_pk_add_f32 v[16:17], v[16:17], v[242:243]
	v_pk_add_f32 v[18:19], v[18:19], v[244:245]
	global_store_dwordx4 v[246:247], v[20:23], off offset:512 nt
	global_store_dwordx4 v[246:247], v[16:19], off offset:528 nt
	v_lshl_add_u64 v[226:227], v[246:247], 0, s[46:47]
	s_waitcnt vmcnt(29)
	v_lshlrev_b32_e32 v230, 16, v216
	v_and_b32_e32 v231, 0xffff0000, v216
	v_lshlrev_b32_e32 v232, 16, v217
	v_and_b32_e32 v233, 0xffff0000, v217
	v_lshlrev_b32_e32 v234, 16, v218
	v_and_b32_e32 v235, 0xffff0000, v218
	v_lshlrev_b32_e32 v236, 16, v219
	v_and_b32_e32 v237, 0xffff0000, v219
	v_pk_add_f32 v[12:13], v[12:13], v[230:231]
	v_pk_add_f32 v[14:15], v[14:15], v[232:233]
	v_pk_add_f32 v[8:9], v[8:9], v[234:235]
	v_pk_add_f32 v[10:11], v[10:11], v[236:237]
	global_store_dwordx4 v[226:227], v[12:15], off nt
	global_store_dwordx4 v[226:227], v[8:11], off offset:16 nt
	s_waitcnt vmcnt(30)
	v_lshlrev_b32_e32 v238, 16, v220
	v_and_b32_e32 v239, 0xffff0000, v220
	v_lshlrev_b32_e32 v240, 16, v221
	v_and_b32_e32 v241, 0xffff0000, v221
	v_lshlrev_b32_e32 v242, 16, v222
	v_and_b32_e32 v243, 0xffff0000, v222
	v_lshlrev_b32_e32 v244, 16, v223
	v_and_b32_e32 v245, 0xffff0000, v223
	v_pk_add_f32 v[4:5], v[4:5], v[238:239]
	v_pk_add_f32 v[6:7], v[6:7], v[240:241]
	v_pk_add_f32 v[0:1], v[0:1], v[242:243]
	v_pk_add_f32 v[2:3], v[2:3], v[244:245]
	global_store_dwordx4 v[226:227], v[4:7], off offset:512 nt
	global_store_dwordx4 v[226:227], v[0:3], off offset:528 nt
	s_andn2_b64 vcc, exec, s[0:1]
	s_mov_b64 s[0:1], -1
	s_cbranch_vccnz .LBB0_1140
	s_andn2_b64 vcc, exec, s[6:7]
	s_cbranch_vccnz .LBB0_1139
	s_barrier
	s_branch .LBB0_1139

; __global__ void __launch_bounds__(512, 2) fwd_megakernel(Params p) {
	.amdhsa_kernel _Z14fwd_megakernel6Params
		.amdhsa_group_segment_fixed_size 0
		.amdhsa_private_segment_fixed_size 0
		.amdhsa_kernarg_size 448
		.amdhsa_user_sgpr_count 2
		.amdhsa_user_sgpr_dispatch_ptr 0
		.amdhsa_user_sgpr_queue_ptr 0
		.amdhsa_user_sgpr_kernarg_segment_ptr 1
		.amdhsa_user_sgpr_dispatch_id 0
		.amdhsa_user_sgpr_kernarg_preload_length 0
		.amdhsa_user_sgpr_kernarg_preload_offset 0
		.amdhsa_user_sgpr_private_segment_size 0
		.amdhsa_uses_dynamic_stack 0
		.amdhsa_enable_private_segment 0
		.amdhsa_system_sgpr_workgroup_id_x 1
		.amdhsa_system_sgpr_workgroup_id_y 0
		.amdhsa_system_sgpr_workgroup_id_z 0
		.amdhsa_system_sgpr_workgroup_info 0
		.amdhsa_system_vgpr_workitem_id 2
		.amdhsa_next_free_vgpr 255
		.amdhsa_next_free_sgpr 102
		.amdhsa_accum_offset 256
		.amdhsa_reserve_vcc 1
		.amdhsa_float_round_mode_32 0
		.amdhsa_float_round_mode_16_64 0
		.amdhsa_float_denorm_mode_32 3
		.amdhsa_float_denorm_mode_16_64 3
		.amdhsa_dx10_clamp 1
		.amdhsa_ieee_mode 1
		.amdhsa_fp16_overflow 0
		.amdhsa_tg_split 0
		.amdhsa_exception_fp_ieee_invalid_op 0
		.amdhsa_exception_fp_denorm_src 0
		.amdhsa_exception_fp_ieee_div_zero 0
		.amdhsa_exception_fp_ieee_overflow 0
		.amdhsa_exception_fp_ieee_underflow 0
		.amdhsa_exception_fp_ieee_inexact 0
		.amdhsa_exception_int_div_zero 0
	.end_amdhsa_kernel

; __global__ void __launch_bounds__(512, 2) fwd_megakernel(Params p) {
amdhsa.kernels:
  - .agpr_count:     0
    .args:
      - .offset:         0
        .size:           192
        .value_kind:     by_value
      - .offset:         192
        .size:           4
        .value_kind:     hidden_block_count_x
      - .offset:         196
        .size:           4
        .value_kind:     hidden_block_count_y
      - .offset:         200
        .size:           4
        .value_kind:     hidden_block_count_z
      - .offset:         204
        .size:           2
        .value_kind:     hidden_group_size_x
      - .offset:         206
        .size:           2
        .value_kind:     hidden_group_size_y
      - .offset:         208
        .size:           2
        .value_kind:     hidden_group_size_z
      - .offset:         210
        .size:           2
        .value_kind:     hidden_remainder_x
      - .offset:         212
        .size:           2
        .value_kind:     hidden_remainder_y
      - .offset:         214
        .size:           2
        .value_kind:     hidden_remainder_z
      - .offset:         232
        .size:           8
        .value_kind:     hidden_global_offset_x
      - .offset:         240
        .size:           8
        .value_kind:     hidden_global_offset_y
      - .offset:         248
        .size:           8
        .value_kind:     hidden_global_offset_z
      - .offset:         256
        .size:           2
        .value_kind:     hidden_grid_dims
      - .offset:         280
        .size:           8
        .value_kind:     hidden_multigrid_sync_arg
      - .offset:         312
        .size:           4
        .value_kind:     hidden_dynamic_lds_size
    .group_segment_fixed_size: 0
    .kernarg_segment_align: 8
    .kernarg_segment_size: 448
    .language:       OpenCL C
    .language_version:
      - 2
      - 0
    .max_flat_workgroup_size: 512
    .name:           _Z14fwd_megakernel6Params
    .private_segment_fixed_size: 0
    .sgpr_count:     108
    .sgpr_spill_count: 132
    .symbol:         _Z14fwd_megakernel6Params.kd
    .uniform_work_group_size: 1
    .uses_dynamic_stack: false
    .vgpr_count:     255
    .vgpr_spill_count: 0
    .wavefront_size: 64
